# previous + s_setprio 1 issued before the pre-MFMA barrier instead of after it
# speedup vs baseline: 1.0006x; 1.0006x over previous
.LBB0_287:
	ds_read_b128 v[160:163], v156
	ds_read_b128 v[164:167], v156 offset:1024
	ds_read_b128 v[168:171], v156 offset:2048
	ds_read_b128 v[172:175], v156 offset:3072
	ds_read_b128 v[176:179], v157
	ds_read_b128 v[180:183], v157 offset:1024
	ds_read_b128 v[184:187], v157 offset:2048
	ds_read_b128 v[188:191], v157 offset:3072
	s_add_u32 s28, s26, 0xfff00080
	s_addc_u32 s29, s27, -1
	s_cmp_eq_u32 s58, 60
	s_cselect_b32 s31, s21, s29
	s_cselect_b32 s30, s54, s28
	s_cselect_b32 s29, s19, s57
	s_cselect_b32 s28, s55, s56
	v_lshl_add_u64 v[192:193], s[26:27], 0, v[138:139]
	s_add_i32 m0, s17, 0xc000
	ds_read_b128 v[196:199], v158
	ds_read_b128 v[200:203], v158 offset:1024
	ds_read_b128 v[204:207], v158 offset:2048
	ds_read_b128 v[208:211], v158 offset:3072
	ds_read_b128 v[212:215], v158 offset:4096
	ds_read_b128 v[216:219], v158 offset:5120
	ds_read_b128 v[220:223], v158 offset:6144
	ds_read_b128 v[224:227], v158 offset:7168
	global_load_lds_dwordx4 v[192:193], off
	v_lshl_add_u64 v[192:193], s[26:27], 0, v[140:141]
	s_add_i32 m0, s17, 0xe000
	s_nop 0
	global_load_lds_dwordx4 v[192:193], off
	s_nop 0
	s_waitcnt vmcnt(8)
	s_waitcnt lgkmcnt(0)
	s_setprio 1
	s_barrier
	v_mfma_f32_16x16x32_bf16 v[126:129], v[160:163], v[196:199], v[126:129]
	v_mfma_f32_16x16x32_bf16 v[122:125], v[168:171], v[196:199], v[122:125]
	v_mfma_f32_16x16x32_bf16 v[118:121], v[160:163], v[204:207], v[118:121]
	v_mfma_f32_16x16x32_bf16 v[114:117], v[168:171], v[204:207], v[114:117]
	v_mfma_f32_16x16x32_bf16 v[102:105], v[160:163], v[212:215], v[102:105]
	v_mfma_f32_16x16x32_bf16 v[98:101], v[168:171], v[212:215], v[98:101]
	v_mfma_f32_16x16x32_bf16 v[86:89], v[160:163], v[220:223], v[86:89]
	v_mfma_f32_16x16x32_bf16 v[82:85], v[168:171], v[220:223], v[82:85]
	v_mfma_f32_16x16x32_bf16 v[126:129], v[164:167], v[200:203], v[126:129]
	v_mfma_f32_16x16x32_bf16 v[122:125], v[172:175], v[200:203], v[122:125]
	v_mfma_f32_16x16x32_bf16 v[118:121], v[164:167], v[208:211], v[118:121]
	v_mfma_f32_16x16x32_bf16 v[114:117], v[172:175], v[208:211], v[114:117]
	v_mfma_f32_16x16x32_bf16 v[102:105], v[164:167], v[216:219], v[102:105]
	v_mfma_f32_16x16x32_bf16 v[98:101], v[172:175], v[216:219], v[98:101]
	v_mfma_f32_16x16x32_bf16 v[86:89], v[164:167], v[224:227], v[86:89]
	v_mfma_f32_16x16x32_bf16 v[82:85], v[172:175], v[224:227], v[82:85]
	v_mfma_f32_16x16x32_bf16 v[110:113], v[176:179], v[196:199], v[110:113]
	v_mfma_f32_16x16x32_bf16 v[106:109], v[184:187], v[196:199], v[106:109]
	v_mfma_f32_16x16x32_bf16 v[94:97], v[176:179], v[204:207], v[94:97]
	v_mfma_f32_16x16x32_bf16 v[90:93], v[184:187], v[204:207], v[90:93]
	v_mfma_f32_16x16x32_bf16 v[78:81], v[176:179], v[212:215], v[78:81]
	v_mfma_f32_16x16x32_bf16 v[74:77], v[184:187], v[212:215], v[74:77]
	v_mfma_f32_16x16x32_bf16 v[70:73], v[176:179], v[220:223], v[70:73]
	v_mfma_f32_16x16x32_bf16 v[66:69], v[184:187], v[220:223], v[66:69]
	v_mfma_f32_16x16x32_bf16 v[110:113], v[180:183], v[200:203], v[110:113]
	v_mfma_f32_16x16x32_bf16 v[106:109], v[188:191], v[200:203], v[106:109]
	v_mfma_f32_16x16x32_bf16 v[94:97], v[180:183], v[208:211], v[94:97]
	v_mfma_f32_16x16x32_bf16 v[90:93], v[188:191], v[208:211], v[90:93]
	v_mfma_f32_16x16x32_bf16 v[78:81], v[180:183], v[216:219], v[78:81]
	v_mfma_f32_16x16x32_bf16 v[74:77], v[188:191], v[216:219], v[74:77]
	v_mfma_f32_16x16x32_bf16 v[70:73], v[180:183], v[224:227], v[70:73]
	v_mfma_f32_16x16x32_bf16 v[66:69], v[188:191], v[224:227], v[66:69]
	s_setprio 0
	s_barrier
	s_add_i32 s59, s50, s41
	v_lshl_add_u64 v[192:193], s[28:29], 0, v[134:135]
	s_mov_b32 m0, s59
	ds_read_b128 v[196:199], v158 offset:16384
	ds_read_b128 v[200:203], v158 offset:17408
	ds_read_b128 v[204:207], v158 offset:18432
	ds_read_b128 v[208:211], v158 offset:19456
	ds_read_b128 v[212:215], v158 offset:20480
	ds_read_b128 v[216:219], v158 offset:21504
	ds_read_b128 v[220:223], v158 offset:22528
	ds_read_b128 v[224:227], v158 offset:23552
	global_load_lds_dwordx4 v[192:193], off
	s_add_i32 m0, s59, 0x2000
	s_add_u32 s60, s28, 0x100000
	v_lshl_add_u64 v[228:229], s[28:29], 0, v[136:137]
	s_addc_u32 s61, s29, 0
	s_add_i32 s59, s51, s41
	global_load_lds_dwordx4 v[228:229], off
	v_lshl_add_u64 v[230:231], s[60:61], 0, v[134:135]
	s_mov_b32 m0, s59
	v_lshl_add_u64 v[232:233], s[30:31], 0, v[132:133]
	global_load_lds_dwordx4 v[230:231], off
	v_lshl_add_u64 v[230:231], s[60:61], 0, v[136:137]
	s_add_i32 m0, s59, 0x2000
	s_nop 0
	global_load_lds_dwordx4 v[230:231], off
	v_lshl_add_u64 v[230:231], s[30:31], 0, v[130:131]
	s_mov_b32 m0, s17
	s_nop 0
	global_load_lds_dwordx4 v[230:231], off
	s_mov_b32 m0, s42
	s_nop 0
	global_load_lds_dwordx4 v[232:233], off
	s_waitcnt vmcnt(8)
	s_waitcnt lgkmcnt(0)
	s_setprio 1
	s_barrier
	v_mfma_f32_16x16x32_bf16 v[62:65], v[160:163], v[196:199], v[62:65]
	v_mfma_f32_16x16x32_bf16 v[58:61], v[168:171], v[196:199], v[58:61]
	v_mfma_f32_16x16x32_bf16 v[54:57], v[160:163], v[204:207], v[54:57]
	v_mfma_f32_16x16x32_bf16 v[50:53], v[168:171], v[204:207], v[50:53]
	v_mfma_f32_16x16x32_bf16 v[38:41], v[160:163], v[212:215], v[38:41]
	v_mfma_f32_16x16x32_bf16 v[34:37], v[168:171], v[212:215], v[34:37]
	v_mfma_f32_16x16x32_bf16 v[22:25], v[160:163], v[220:223], v[22:25]
	v_mfma_f32_16x16x32_bf16 v[18:21], v[168:171], v[220:223], v[18:21]
	v_mfma_f32_16x16x32_bf16 v[62:65], v[164:167], v[200:203], v[62:65]
	v_mfma_f32_16x16x32_bf16 v[58:61], v[172:175], v[200:203], v[58:61]
	v_mfma_f32_16x16x32_bf16 v[54:57], v[164:167], v[208:211], v[54:57]
	v_mfma_f32_16x16x32_bf16 v[50:53], v[172:175], v[208:211], v[50:53]
	v_mfma_f32_16x16x32_bf16 v[38:41], v[164:167], v[216:219], v[38:41]
	v_mfma_f32_16x16x32_bf16 v[34:37], v[172:175], v[216:219], v[34:37]
	v_mfma_f32_16x16x32_bf16 v[22:25], v[164:167], v[224:227], v[22:25]
	v_mfma_f32_16x16x32_bf16 v[18:21], v[172:175], v[224:227], v[18:21]
	v_mfma_f32_16x16x32_bf16 v[46:49], v[176:179], v[196:199], v[46:49]
	v_mfma_f32_16x16x32_bf16 v[42:45], v[184:187], v[196:199], v[42:45]
	v_mfma_f32_16x16x32_bf16 v[30:33], v[176:179], v[204:207], v[30:33]
	v_mfma_f32_16x16x32_bf16 v[26:29], v[184:187], v[204:207], v[26:29]
	v_mfma_f32_16x16x32_bf16 v[14:17], v[176:179], v[212:215], v[14:17]
	v_mfma_f32_16x16x32_bf16 v[10:13], v[184:187], v[212:215], v[10:13]
	v_mfma_f32_16x16x32_bf16 v[6:9], v[176:179], v[220:223], v[6:9]
	v_mfma_f32_16x16x32_bf16 v[2:5], v[184:187], v[220:223], v[2:5]
	v_mfma_f32_16x16x32_bf16 v[46:49], v[180:183], v[200:203], v[46:49]
	v_mfma_f32_16x16x32_bf16 v[42:45], v[188:191], v[200:203], v[42:45]
	v_mfma_f32_16x16x32_bf16 v[30:33], v[180:183], v[208:211], v[30:33]
	v_mfma_f32_16x16x32_bf16 v[26:29], v[188:191], v[208:211], v[26:29]
	v_mfma_f32_16x16x32_bf16 v[14:17], v[180:183], v[216:219], v[14:17]
	v_mfma_f32_16x16x32_bf16 v[10:13], v[188:191], v[216:219], v[10:13]
	v_mfma_f32_16x16x32_bf16 v[6:9], v[180:183], v[224:227], v[6:9]
	v_mfma_f32_16x16x32_bf16 v[2:5], v[188:191], v[224:227], v[2:5]
	s_setprio 0
	s_barrier
	s_add_i32 s59, 0, 0x18000
	v_add_u32_e32 v159, s59, v154
	s_add_i32 s60, 0, 0x1c000
	ds_read_b128 v[160:163], v159
	ds_read_b128 v[164:167], v159 offset:1024
	ds_read_b128 v[168:171], v159 offset:2048
	ds_read_b128 v[172:175], v159 offset:3072
	v_add_u32_e32 v159, s60, v154
	ds_read_b128 v[176:179], v159
	ds_read_b128 v[180:183], v159 offset:1024
	ds_read_b128 v[184:187], v159 offset:2048
	ds_read_b128 v[188:191], v159 offset:3072
	s_add_u32 s30, s30, 0x100000
	s_addc_u32 s31, s31, 0
	s_mov_b32 m0, s43
	v_lshl_add_u64 v[234:235], s[30:31], 0, v[130:131]
	ds_read_b128 v[196:199], v158 offset:32768
	ds_read_b128 v[200:203], v158 offset:33792
	ds_read_b128 v[204:207], v158 offset:34816
	ds_read_b128 v[208:211], v158 offset:35840
	ds_read_b128 v[212:215], v158 offset:36864
	ds_read_b128 v[216:219], v158 offset:37888
	ds_read_b128 v[220:223], v158 offset:38912
	ds_read_b128 v[224:227], v158 offset:39936
	global_load_lds_dwordx4 v[234:235], off
	v_lshl_add_u64 v[234:235], s[30:31], 0, v[132:133]
	s_mov_b32 m0, s45
	s_nop 0
	global_load_lds_dwordx4 v[234:235], off
	s_waitcnt vmcnt(8)
	s_waitcnt lgkmcnt(0)
	s_setprio 1
	s_barrier
	v_mfma_f32_16x16x32_bf16 v[126:129], v[160:163], v[196:199], v[126:129]
	v_mfma_f32_16x16x32_bf16 v[122:125], v[168:171], v[196:199], v[122:125]
	v_mfma_f32_16x16x32_bf16 v[118:121], v[160:163], v[204:207], v[118:121]
	v_mfma_f32_16x16x32_bf16 v[114:117], v[168:171], v[204:207], v[114:117]
	v_mfma_f32_16x16x32_bf16 v[102:105], v[160:163], v[212:215], v[102:105]
	v_mfma_f32_16x16x32_bf16 v[98:101], v[168:171], v[212:215], v[98:101]
	v_mfma_f32_16x16x32_bf16 v[86:89], v[160:163], v[220:223], v[86:89]
	v_mfma_f32_16x16x32_bf16 v[82:85], v[168:171], v[220:223], v[82:85]
	v_mfma_f32_16x16x32_bf16 v[126:129], v[164:167], v[200:203], v[126:129]
	v_mfma_f32_16x16x32_bf16 v[122:125], v[172:175], v[200:203], v[122:125]
	v_mfma_f32_16x16x32_bf16 v[118:121], v[164:167], v[208:211], v[118:121]
	v_mfma_f32_16x16x32_bf16 v[114:117], v[172:175], v[208:211], v[114:117]
	v_mfma_f32_16x16x32_bf16 v[102:105], v[164:167], v[216:219], v[102:105]
	v_mfma_f32_16x16x32_bf16 v[98:101], v[172:175], v[216:219], v[98:101]
	v_mfma_f32_16x16x32_bf16 v[86:89], v[164:167], v[224:227], v[86:89]
	v_mfma_f32_16x16x32_bf16 v[82:85], v[172:175], v[224:227], v[82:85]
	v_mfma_f32_16x16x32_bf16 v[110:113], v[176:179], v[196:199], v[110:113]
	v_mfma_f32_16x16x32_bf16 v[106:109], v[184:187], v[196:199], v[106:109]
	v_mfma_f32_16x16x32_bf16 v[94:97], v[176:179], v[204:207], v[94:97]
	v_mfma_f32_16x16x32_bf16 v[90:93], v[184:187], v[204:207], v[90:93]
	v_mfma_f32_16x16x32_bf16 v[78:81], v[176:179], v[212:215], v[78:81]
	v_mfma_f32_16x16x32_bf16 v[74:77], v[184:187], v[212:215], v[74:77]
	v_mfma_f32_16x16x32_bf16 v[70:73], v[176:179], v[220:223], v[70:73]
	v_mfma_f32_16x16x32_bf16 v[66:69], v[184:187], v[220:223], v[66:69]
	v_mfma_f32_16x16x32_bf16 v[110:113], v[180:183], v[200:203], v[110:113]
	v_mfma_f32_16x16x32_bf16 v[106:109], v[188:191], v[200:203], v[106:109]
	v_mfma_f32_16x16x32_bf16 v[94:97], v[180:183], v[208:211], v[94:97]
	v_mfma_f32_16x16x32_bf16 v[90:93], v[188:191], v[208:211], v[90:93]
	v_mfma_f32_16x16x32_bf16 v[78:81], v[180:183], v[216:219], v[78:81]
	v_mfma_f32_16x16x32_bf16 v[74:77], v[188:191], v[216:219], v[74:77]
	v_mfma_f32_16x16x32_bf16 v[70:73], v[180:183], v[224:227], v[70:73]
	v_mfma_f32_16x16x32_bf16 v[66:69], v[188:191], v[224:227], v[66:69]
	s_setprio 0
	s_barrier
	s_add_i32 s30, s59, s41
	v_lshl_add_u64 v[192:193], v[192:193], 0, s[12:13]
	s_mov_b32 m0, s30
	ds_read_b128 v[196:199], v158 offset:49152
	ds_read_b128 v[200:203], v158 offset:50176
	ds_read_b128 v[204:207], v158 offset:51200
	ds_read_b128 v[208:211], v158 offset:52224
	ds_read_b128 v[212:215], v158 offset:53248
	ds_read_b128 v[216:219], v158 offset:54272
	ds_read_b128 v[220:223], v158 offset:55296
	ds_read_b128 v[224:227], v158 offset:56320
	global_load_lds_dwordx4 v[192:193], off
	s_add_i32 m0, s30, 0x2000
	s_add_u32 s28, s28, 0x100080
	v_lshl_add_u64 v[192:193], v[228:229], 0, s[12:13]
	s_addc_u32 s29, s29, 0
	s_add_i32 s30, s60, s41
	global_load_lds_dwordx4 v[192:193], off
	v_lshl_add_u64 v[192:193], s[28:29], 0, v[134:135]
	s_mov_b32 m0, s30
	s_nop 0
	global_load_lds_dwordx4 v[192:193], off
	v_lshl_add_u64 v[192:193], s[28:29], 0, v[136:137]
	s_add_i32 m0, s30, 0x2000
	s_nop 0
	global_load_lds_dwordx4 v[192:193], off
	v_lshl_add_u64 v[192:193], v[230:231], 0, s[12:13]
	s_mov_b32 m0, s47
	s_nop 0
	global_load_lds_dwordx4 v[192:193], off
	v_lshl_add_u64 v[192:193], v[232:233], 0, s[12:13]
	s_mov_b32 m0, s48
	s_nop 0
	global_load_lds_dwordx4 v[192:193], off
	s_nop 0
	s_waitcnt vmcnt(8)
	s_waitcnt lgkmcnt(0)
	s_setprio 1
	s_barrier
	v_mfma_f32_16x16x32_bf16 v[62:65], v[160:163], v[196:199], v[62:65]
	v_mfma_f32_16x16x32_bf16 v[58:61], v[168:171], v[196:199], v[58:61]
	v_mfma_f32_16x16x32_bf16 v[54:57], v[160:163], v[204:207], v[54:57]
	v_mfma_f32_16x16x32_bf16 v[50:53], v[168:171], v[204:207], v[50:53]
	v_mfma_f32_16x16x32_bf16 v[38:41], v[160:163], v[212:215], v[38:41]
	v_mfma_f32_16x16x32_bf16 v[34:37], v[168:171], v[212:215], v[34:37]
	v_mfma_f32_16x16x32_bf16 v[22:25], v[160:163], v[220:223], v[22:25]
	v_mfma_f32_16x16x32_bf16 v[18:21], v[168:171], v[220:223], v[18:21]
	v_mfma_f32_16x16x32_bf16 v[62:65], v[164:167], v[200:203], v[62:65]
	v_mfma_f32_16x16x32_bf16 v[58:61], v[172:175], v[200:203], v[58:61]
	v_mfma_f32_16x16x32_bf16 v[54:57], v[164:167], v[208:211], v[54:57]
	v_mfma_f32_16x16x32_bf16 v[50:53], v[172:175], v[208:211], v[50:53]
	v_mfma_f32_16x16x32_bf16 v[38:41], v[164:167], v[216:219], v[38:41]
	v_mfma_f32_16x16x32_bf16 v[34:37], v[172:175], v[216:219], v[34:37]
	v_mfma_f32_16x16x32_bf16 v[22:25], v[164:167], v[224:227], v[22:25]
	v_mfma_f32_16x16x32_bf16 v[18:21], v[172:175], v[224:227], v[18:21]
	v_mfma_f32_16x16x32_bf16 v[46:49], v[176:179], v[196:199], v[46:49]
	v_mfma_f32_16x16x32_bf16 v[42:45], v[184:187], v[196:199], v[42:45]
	v_mfma_f32_16x16x32_bf16 v[30:33], v[176:179], v[204:207], v[30:33]
	v_mfma_f32_16x16x32_bf16 v[26:29], v[184:187], v[204:207], v[26:29]
	v_mfma_f32_16x16x32_bf16 v[14:17], v[176:179], v[212:215], v[14:17]
	v_mfma_f32_16x16x32_bf16 v[10:13], v[184:187], v[212:215], v[10:13]
	v_mfma_f32_16x16x32_bf16 v[6:9], v[176:179], v[220:223], v[6:9]
	v_mfma_f32_16x16x32_bf16 v[2:5], v[184:187], v[220:223], v[2:5]
	v_mfma_f32_16x16x32_bf16 v[46:49], v[180:183], v[200:203], v[46:49]
	v_mfma_f32_16x16x32_bf16 v[42:45], v[188:191], v[200:203], v[42:45]
	v_mfma_f32_16x16x32_bf16 v[30:33], v[180:183], v[208:211], v[30:33]
	v_mfma_f32_16x16x32_bf16 v[26:29], v[188:191], v[208:211], v[26:29]
	v_mfma_f32_16x16x32_bf16 v[14:17], v[180:183], v[216:219], v[14:17]
	v_mfma_f32_16x16x32_bf16 v[10:13], v[188:191], v[216:219], v[10:13]
	v_mfma_f32_16x16x32_bf16 v[6:9], v[180:183], v[224:227], v[6:9]
	v_mfma_f32_16x16x32_bf16 v[2:5], v[188:191], v[224:227], v[2:5]
	s_setprio 0
	s_barrier
	s_add_i32 s58, s58, 2
	s_add_u32 s26, s26, 0x100
	s_addc_u32 s27, s27, 0
	s_add_u32 s56, s56, 0x100
	s_addc_u32 s57, s57, 0
	s_cmp_gt_u32 s58, 61
	s_cbranch_scc0 .LBB0_287
	s_and_b64 vcc, exec, s[14:15]
	s_cbranch_vccz .LBB0_290
	s_barrier

.LBB0_311:
	ds_read_b128 v[152:155], v144
	ds_read_b128 v[156:159], v144 offset:1024
	ds_read_b128 v[160:163], v144 offset:2048
	ds_read_b128 v[164:167], v144 offset:3072
	ds_read_b128 v[168:171], v145
	ds_read_b128 v[172:175], v145 offset:1024
	ds_read_b128 v[176:179], v145 offset:2048
	ds_read_b128 v[180:183], v145 offset:3072
	s_add_u32 s42, s40, 0xfff00080
	s_addc_u32 s43, s41, -1
	s_cmp_eq_u32 s70, 60
	s_cselect_b32 s47, s27, s43
	s_cselect_b32 s46, s66, s42
	s_cselect_b32 s43, s25, s69
	s_cselect_b32 s42, s67, s68
	v_lshl_add_u64 v[192:193], s[40:41], 0, v[134:135]
	s_add_i32 m0, s29, 0xc000
	ds_read_b128 v[184:187], v151
	ds_read_b128 v[188:191], v151 offset:1024
	ds_read_b128 v[196:199], v151 offset:2048
	ds_read_b128 v[200:203], v151 offset:3072
	ds_read_b128 v[204:207], v151 offset:4096
	ds_read_b128 v[208:211], v151 offset:5120
	ds_read_b128 v[212:215], v151 offset:6144
	ds_read_b128 v[216:219], v151 offset:7168
	global_load_lds_dwordx4 v[192:193], off
	v_lshl_add_u64 v[192:193], s[40:41], 0, v[136:137]
	s_add_i32 m0, s29, 0xe000
	s_nop 0
	global_load_lds_dwordx4 v[192:193], off
	s_waitcnt vmcnt(8)
	s_waitcnt lgkmcnt(0)
	s_setprio 1
	s_barrier
	v_mfma_f32_16x16x32_bf16 v[126:129], v[152:155], v[184:187], v[126:129]
	v_mfma_f32_16x16x32_bf16 v[122:125], v[160:163], v[184:187], v[122:125]
	v_mfma_f32_16x16x32_bf16 v[118:121], v[152:155], v[196:199], v[118:121]
	v_mfma_f32_16x16x32_bf16 v[110:113], v[160:163], v[196:199], v[110:113]
	v_mfma_f32_16x16x32_bf16 v[102:105], v[152:155], v[204:207], v[102:105]
	v_mfma_f32_16x16x32_bf16 v[94:97], v[160:163], v[204:207], v[94:97]
	v_mfma_f32_16x16x32_bf16 v[86:89], v[152:155], v[212:215], v[86:89]
	v_mfma_f32_16x16x32_bf16 v[78:81], v[160:163], v[212:215], v[78:81]
	v_mfma_f32_16x16x32_bf16 v[126:129], v[156:159], v[188:191], v[126:129]
	v_mfma_f32_16x16x32_bf16 v[122:125], v[164:167], v[188:191], v[122:125]
	v_mfma_f32_16x16x32_bf16 v[118:121], v[156:159], v[200:203], v[118:121]
	v_mfma_f32_16x16x32_bf16 v[110:113], v[164:167], v[200:203], v[110:113]
	v_mfma_f32_16x16x32_bf16 v[102:105], v[156:159], v[208:211], v[102:105]
	v_mfma_f32_16x16x32_bf16 v[94:97], v[164:167], v[208:211], v[94:97]
	v_mfma_f32_16x16x32_bf16 v[86:89], v[156:159], v[216:219], v[86:89]
	v_mfma_f32_16x16x32_bf16 v[78:81], v[164:167], v[216:219], v[78:81]
	v_mfma_f32_16x16x32_bf16 v[114:117], v[168:171], v[184:187], v[114:117]
	v_mfma_f32_16x16x32_bf16 v[106:109], v[176:179], v[184:187], v[106:109]
	v_mfma_f32_16x16x32_bf16 v[98:101], v[168:171], v[196:199], v[98:101]
	v_mfma_f32_16x16x32_bf16 v[90:93], v[176:179], v[196:199], v[90:93]
	v_mfma_f32_16x16x32_bf16 v[82:85], v[168:171], v[204:207], v[82:85]
	v_mfma_f32_16x16x32_bf16 v[74:77], v[176:179], v[204:207], v[74:77]
	v_mfma_f32_16x16x32_bf16 v[70:73], v[168:171], v[212:215], v[70:73]
	v_mfma_f32_16x16x32_bf16 v[66:69], v[176:179], v[212:215], v[66:69]
	v_mfma_f32_16x16x32_bf16 v[114:117], v[172:175], v[188:191], v[114:117]
	v_mfma_f32_16x16x32_bf16 v[106:109], v[180:183], v[188:191], v[106:109]
	v_mfma_f32_16x16x32_bf16 v[98:101], v[172:175], v[200:203], v[98:101]
	v_mfma_f32_16x16x32_bf16 v[90:93], v[180:183], v[200:203], v[90:93]
	v_mfma_f32_16x16x32_bf16 v[82:85], v[172:175], v[208:211], v[82:85]
	v_mfma_f32_16x16x32_bf16 v[74:77], v[180:183], v[208:211], v[74:77]
	v_mfma_f32_16x16x32_bf16 v[70:73], v[172:175], v[216:219], v[70:73]
	v_mfma_f32_16x16x32_bf16 v[66:69], v[180:183], v[216:219], v[66:69]
	s_setprio 0
	s_barrier
	s_add_i32 s71, s62, s54
	v_lshl_add_u64 v[192:193], s[42:43], 0, v[130:131]
	s_mov_b32 m0, s71
	ds_read_b128 v[184:187], v151 offset:16384
	ds_read_b128 v[188:191], v151 offset:17408
	ds_read_b128 v[196:199], v151 offset:18432
	ds_read_b128 v[200:203], v151 offset:19456
	ds_read_b128 v[204:207], v151 offset:20480
	ds_read_b128 v[208:211], v151 offset:21504
	ds_read_b128 v[212:215], v151 offset:22528
	ds_read_b128 v[216:219], v151 offset:23552
	global_load_lds_dwordx4 v[192:193], off
	s_add_i32 m0, s71, 0x2000
	s_add_u32 s72, s42, 0x100000
	v_lshl_add_u64 v[220:221], s[42:43], 0, v[132:133]
	s_addc_u32 s73, s43, 0
	s_add_i32 s71, s63, s54
	global_load_lds_dwordx4 v[220:221], off
	v_lshl_add_u64 v[222:223], s[72:73], 0, v[130:131]
	s_mov_b32 m0, s71
	v_lshl_add_u64 v[224:225], s[46:47], 0, v[132:133]
	global_load_lds_dwordx4 v[222:223], off
	v_lshl_add_u64 v[222:223], s[72:73], 0, v[132:133]
	s_add_i32 m0, s71, 0x2000
	s_nop 0
	global_load_lds_dwordx4 v[222:223], off
	v_lshl_add_u64 v[222:223], s[46:47], 0, v[130:131]
	s_mov_b32 m0, s29
	s_nop 0
	global_load_lds_dwordx4 v[222:223], off
	s_mov_b32 m0, s55
	s_nop 0
	global_load_lds_dwordx4 v[224:225], off
	s_waitcnt vmcnt(8)
	s_waitcnt lgkmcnt(0)
	s_setprio 1
	s_barrier
	v_mfma_f32_16x16x32_bf16 v[62:65], v[152:155], v[184:187], v[62:65]
	v_mfma_f32_16x16x32_bf16 v[58:61], v[160:163], v[184:187], v[58:61]
	v_mfma_f32_16x16x32_bf16 v[54:57], v[152:155], v[196:199], v[54:57]
	v_mfma_f32_16x16x32_bf16 v[46:49], v[160:163], v[196:199], v[46:49]
	v_mfma_f32_16x16x32_bf16 v[38:41], v[152:155], v[204:207], v[38:41]
	v_mfma_f32_16x16x32_bf16 v[30:33], v[160:163], v[204:207], v[30:33]
	v_mfma_f32_16x16x32_bf16 v[22:25], v[152:155], v[212:215], v[22:25]
	v_mfma_f32_16x16x32_bf16 v[14:17], v[160:163], v[212:215], v[14:17]
	v_mfma_f32_16x16x32_bf16 v[62:65], v[156:159], v[188:191], v[62:65]
	v_mfma_f32_16x16x32_bf16 v[58:61], v[164:167], v[188:191], v[58:61]
	v_mfma_f32_16x16x32_bf16 v[54:57], v[156:159], v[200:203], v[54:57]
	v_mfma_f32_16x16x32_bf16 v[46:49], v[164:167], v[200:203], v[46:49]
	v_mfma_f32_16x16x32_bf16 v[38:41], v[156:159], v[208:211], v[38:41]
	v_mfma_f32_16x16x32_bf16 v[30:33], v[164:167], v[208:211], v[30:33]
	v_mfma_f32_16x16x32_bf16 v[22:25], v[156:159], v[216:219], v[22:25]
	v_mfma_f32_16x16x32_bf16 v[14:17], v[164:167], v[216:219], v[14:17]
	v_mfma_f32_16x16x32_bf16 v[50:53], v[168:171], v[184:187], v[50:53]
	v_mfma_f32_16x16x32_bf16 v[42:45], v[176:179], v[184:187], v[42:45]
	v_mfma_f32_16x16x32_bf16 v[34:37], v[168:171], v[196:199], v[34:37]
	v_mfma_f32_16x16x32_bf16 v[26:29], v[176:179], v[196:199], v[26:29]
	v_mfma_f32_16x16x32_bf16 v[18:21], v[168:171], v[204:207], v[18:21]
	v_mfma_f32_16x16x32_bf16 v[10:13], v[176:179], v[204:207], v[10:13]
	v_mfma_f32_16x16x32_bf16 v[6:9], v[168:171], v[212:215], v[6:9]
	v_mfma_f32_16x16x32_bf16 v[2:5], v[176:179], v[212:215], v[2:5]
	v_mfma_f32_16x16x32_bf16 v[50:53], v[172:175], v[188:191], v[50:53]
	v_mfma_f32_16x16x32_bf16 v[42:45], v[180:183], v[188:191], v[42:45]
	v_mfma_f32_16x16x32_bf16 v[34:37], v[172:175], v[200:203], v[34:37]
	v_mfma_f32_16x16x32_bf16 v[26:29], v[180:183], v[200:203], v[26:29]
	v_mfma_f32_16x16x32_bf16 v[18:21], v[172:175], v[208:211], v[18:21]
	v_mfma_f32_16x16x32_bf16 v[10:13], v[180:183], v[208:211], v[10:13]
	v_mfma_f32_16x16x32_bf16 v[6:9], v[172:175], v[216:219], v[6:9]
	v_mfma_f32_16x16x32_bf16 v[2:5], v[180:183], v[216:219], v[2:5]
	s_setprio 0
	s_barrier
	s_add_i32 s71, 0, 0x18000
	s_add_i32 s72, 0, 0x1c000
	v_add_u32_e32 v164, s71, v142
	v_add_u32_e32 v180, s72, v142
	ds_read_b128 v[152:155], v164
	ds_read_b128 v[156:159], v164 offset:1024
	ds_read_b128 v[160:163], v164 offset:2048
	ds_read_b128 v[164:167], v164 offset:3072
	ds_read_b128 v[168:171], v180
	ds_read_b128 v[172:175], v180 offset:1024
	ds_read_b128 v[176:179], v180 offset:2048
	ds_read_b128 v[180:183], v180 offset:3072
	s_add_u32 s46, s46, 0x100000
	s_addc_u32 s47, s47, 0
	s_mov_b32 m0, s56
	v_lshl_add_u64 v[226:227], s[46:47], 0, v[130:131]
	ds_read_b128 v[184:187], v151 offset:32768
	ds_read_b128 v[188:191], v151 offset:33792
	ds_read_b128 v[196:199], v151 offset:34816
	ds_read_b128 v[200:203], v151 offset:35840
	ds_read_b128 v[204:207], v151 offset:36864
	ds_read_b128 v[208:211], v151 offset:37888
	ds_read_b128 v[212:215], v151 offset:38912
	ds_read_b128 v[216:219], v151 offset:39936
	global_load_lds_dwordx4 v[226:227], off
	v_lshl_add_u64 v[226:227], s[46:47], 0, v[132:133]
	s_mov_b32 m0, s57
	s_nop 0
	global_load_lds_dwordx4 v[226:227], off
	s_waitcnt vmcnt(8)
	s_waitcnt lgkmcnt(0)
	s_setprio 1
	s_barrier
	v_mfma_f32_16x16x32_bf16 v[126:129], v[152:155], v[184:187], v[126:129]
	v_mfma_f32_16x16x32_bf16 v[122:125], v[160:163], v[184:187], v[122:125]
	v_mfma_f32_16x16x32_bf16 v[118:121], v[152:155], v[196:199], v[118:121]
	v_mfma_f32_16x16x32_bf16 v[110:113], v[160:163], v[196:199], v[110:113]
	v_mfma_f32_16x16x32_bf16 v[102:105], v[152:155], v[204:207], v[102:105]
	v_mfma_f32_16x16x32_bf16 v[94:97], v[160:163], v[204:207], v[94:97]
	v_mfma_f32_16x16x32_bf16 v[86:89], v[152:155], v[212:215], v[86:89]
	v_mfma_f32_16x16x32_bf16 v[78:81], v[160:163], v[212:215], v[78:81]
	v_mfma_f32_16x16x32_bf16 v[126:129], v[156:159], v[188:191], v[126:129]
	v_mfma_f32_16x16x32_bf16 v[122:125], v[164:167], v[188:191], v[122:125]
	v_mfma_f32_16x16x32_bf16 v[118:121], v[156:159], v[200:203], v[118:121]
	v_mfma_f32_16x16x32_bf16 v[110:113], v[164:167], v[200:203], v[110:113]
	v_mfma_f32_16x16x32_bf16 v[102:105], v[156:159], v[208:211], v[102:105]
	v_mfma_f32_16x16x32_bf16 v[94:97], v[164:167], v[208:211], v[94:97]
	v_mfma_f32_16x16x32_bf16 v[86:89], v[156:159], v[216:219], v[86:89]
	v_mfma_f32_16x16x32_bf16 v[78:81], v[164:167], v[216:219], v[78:81]
	v_mfma_f32_16x16x32_bf16 v[114:117], v[168:171], v[184:187], v[114:117]
	v_mfma_f32_16x16x32_bf16 v[106:109], v[176:179], v[184:187], v[106:109]
	v_mfma_f32_16x16x32_bf16 v[98:101], v[168:171], v[196:199], v[98:101]
	v_mfma_f32_16x16x32_bf16 v[90:93], v[176:179], v[196:199], v[90:93]
	v_mfma_f32_16x16x32_bf16 v[82:85], v[168:171], v[204:207], v[82:85]
	v_mfma_f32_16x16x32_bf16 v[74:77], v[176:179], v[204:207], v[74:77]
	v_mfma_f32_16x16x32_bf16 v[70:73], v[168:171], v[212:215], v[70:73]
	v_mfma_f32_16x16x32_bf16 v[66:69], v[176:179], v[212:215], v[66:69]
	v_mfma_f32_16x16x32_bf16 v[114:117], v[172:175], v[188:191], v[114:117]
	v_mfma_f32_16x16x32_bf16 v[106:109], v[180:183], v[188:191], v[106:109]
	v_mfma_f32_16x16x32_bf16 v[98:101], v[172:175], v[200:203], v[98:101]
	v_mfma_f32_16x16x32_bf16 v[90:93], v[180:183], v[200:203], v[90:93]
	v_mfma_f32_16x16x32_bf16 v[82:85], v[172:175], v[208:211], v[82:85]
	v_mfma_f32_16x16x32_bf16 v[74:77], v[180:183], v[208:211], v[74:77]
	v_mfma_f32_16x16x32_bf16 v[70:73], v[172:175], v[216:219], v[70:73]
	v_mfma_f32_16x16x32_bf16 v[66:69], v[180:183], v[216:219], v[66:69]
	s_setprio 0
	s_barrier
	s_add_i32 s46, s71, s54
	v_lshl_add_u64 v[192:193], v[192:193], 0, s[10:11]
	s_mov_b32 m0, s46
	ds_read_b128 v[184:187], v151 offset:49152
	ds_read_b128 v[188:191], v151 offset:50176
	ds_read_b128 v[196:199], v151 offset:51200
	ds_read_b128 v[200:203], v151 offset:52224
	ds_read_b128 v[204:207], v151 offset:53248
	ds_read_b128 v[208:211], v151 offset:54272
	ds_read_b128 v[212:215], v151 offset:55296
	ds_read_b128 v[216:219], v151 offset:56320
	global_load_lds_dwordx4 v[192:193], off
	s_add_i32 m0, s46, 0x2000
	s_add_u32 s42, s42, 0x100080
	v_lshl_add_u64 v[192:193], v[220:221], 0, s[10:11]
	s_addc_u32 s43, s43, 0
	s_add_i32 s46, s72, s54
	global_load_lds_dwordx4 v[192:193], off
	v_lshl_add_u64 v[192:193], s[42:43], 0, v[130:131]
	s_mov_b32 m0, s46
	s_nop 0
	global_load_lds_dwordx4 v[192:193], off
	v_lshl_add_u64 v[192:193], s[42:43], 0, v[132:133]
	s_add_i32 m0, s46, 0x2000
	s_nop 0
	global_load_lds_dwordx4 v[192:193], off
	v_lshl_add_u64 v[192:193], v[222:223], 0, s[10:11]
	s_mov_b32 m0, s59
	s_nop 0
	global_load_lds_dwordx4 v[192:193], off
	v_lshl_add_u64 v[192:193], v[224:225], 0, s[10:11]
	s_mov_b32 m0, s60
	s_nop 0
	global_load_lds_dwordx4 v[192:193], off
	s_nop 0
	s_waitcnt vmcnt(8)
	s_waitcnt lgkmcnt(0)
	s_setprio 1
	s_barrier
	v_mfma_f32_16x16x32_bf16 v[62:65], v[152:155], v[184:187], v[62:65]
	v_mfma_f32_16x16x32_bf16 v[58:61], v[160:163], v[184:187], v[58:61]
	v_mfma_f32_16x16x32_bf16 v[54:57], v[152:155], v[196:199], v[54:57]
	v_mfma_f32_16x16x32_bf16 v[46:49], v[160:163], v[196:199], v[46:49]
	v_mfma_f32_16x16x32_bf16 v[38:41], v[152:155], v[204:207], v[38:41]
	v_mfma_f32_16x16x32_bf16 v[30:33], v[160:163], v[204:207], v[30:33]
	v_mfma_f32_16x16x32_bf16 v[22:25], v[152:155], v[212:215], v[22:25]
	v_mfma_f32_16x16x32_bf16 v[14:17], v[160:163], v[212:215], v[14:17]
	v_mfma_f32_16x16x32_bf16 v[62:65], v[156:159], v[188:191], v[62:65]
	v_mfma_f32_16x16x32_bf16 v[58:61], v[164:167], v[188:191], v[58:61]
	v_mfma_f32_16x16x32_bf16 v[54:57], v[156:159], v[200:203], v[54:57]
	v_mfma_f32_16x16x32_bf16 v[46:49], v[164:167], v[200:203], v[46:49]
	v_mfma_f32_16x16x32_bf16 v[38:41], v[156:159], v[208:211], v[38:41]
	v_mfma_f32_16x16x32_bf16 v[30:33], v[164:167], v[208:211], v[30:33]
	v_mfma_f32_16x16x32_bf16 v[22:25], v[156:159], v[216:219], v[22:25]
	v_mfma_f32_16x16x32_bf16 v[14:17], v[164:167], v[216:219], v[14:17]
	v_mfma_f32_16x16x32_bf16 v[50:53], v[168:171], v[184:187], v[50:53]
	v_mfma_f32_16x16x32_bf16 v[42:45], v[176:179], v[184:187], v[42:45]
	v_mfma_f32_16x16x32_bf16 v[34:37], v[168:171], v[196:199], v[34:37]
	v_mfma_f32_16x16x32_bf16 v[26:29], v[176:179], v[196:199], v[26:29]
	v_mfma_f32_16x16x32_bf16 v[18:21], v[168:171], v[204:207], v[18:21]
	v_mfma_f32_16x16x32_bf16 v[10:13], v[176:179], v[204:207], v[10:13]
	v_mfma_f32_16x16x32_bf16 v[6:9], v[168:171], v[212:215], v[6:9]
	v_mfma_f32_16x16x32_bf16 v[2:5], v[176:179], v[212:215], v[2:5]
	v_mfma_f32_16x16x32_bf16 v[50:53], v[172:175], v[188:191], v[50:53]
	v_mfma_f32_16x16x32_bf16 v[42:45], v[180:183], v[188:191], v[42:45]
	v_mfma_f32_16x16x32_bf16 v[34:37], v[172:175], v[200:203], v[34:37]
	v_mfma_f32_16x16x32_bf16 v[26:29], v[180:183], v[200:203], v[26:29]
	v_mfma_f32_16x16x32_bf16 v[18:21], v[172:175], v[208:211], v[18:21]
	v_mfma_f32_16x16x32_bf16 v[10:13], v[180:183], v[208:211], v[10:13]
	v_mfma_f32_16x16x32_bf16 v[6:9], v[172:175], v[216:219], v[6:9]
	v_mfma_f32_16x16x32_bf16 v[2:5], v[180:183], v[216:219], v[2:5]
	s_setprio 0
	s_barrier
	s_add_i32 s70, s70, 2
	s_add_u32 s40, s40, 0x100
	s_addc_u32 s41, s41, 0
	s_add_u32 s68, s68, 0x100
	s_addc_u32 s69, s69, 0
	s_cmp_gt_u32 s70, 61
	s_cbranch_scc0 .LBB0_311
	s_and_b64 vcc, exec, s[12:13]
	s_cbranch_vccz .LBB0_314
	s_barrier

.LBB0_335:
	ds_read_b128 v[144:147], v140
	ds_read_b128 v[148:151], v140 offset:1024
	ds_read_b128 v[152:155], v140 offset:2048
	ds_read_b128 v[156:159], v140 offset:3072
	ds_read_b128 v[160:163], v142
	ds_read_b128 v[164:167], v142 offset:1024
	ds_read_b128 v[168:171], v142 offset:2048
	ds_read_b128 v[172:175], v142 offset:3072
	s_add_u32 s42, s40, 0xfff00080
	s_addc_u32 s43, s41, -1
	s_cmp_eq_u32 s67, 60
	s_cselect_b32 s47, s27, s43
	s_cselect_b32 s46, s63, s42
	s_cselect_b32 s43, s25, s66
	s_cselect_b32 s42, s64, s65
	v_lshl_add_u64 v[192:193], s[40:41], 0, v[134:135]
	s_add_i32 m0, s29, 0xc000
	ds_read_b128 v[176:179], v143
	ds_read_b128 v[180:183], v143 offset:1024
	ds_read_b128 v[184:187], v143 offset:2048
	ds_read_b128 v[188:191], v143 offset:3072
	ds_read_b128 v[196:199], v143 offset:4096
	ds_read_b128 v[200:203], v143 offset:5120
	ds_read_b128 v[204:207], v143 offset:6144
	ds_read_b128 v[208:211], v143 offset:7168
	global_load_lds_dwordx4 v[192:193], off
	v_lshl_add_u64 v[192:193], s[40:41], 0, v[136:137]
	s_add_i32 m0, s29, 0xe000
	s_nop 0
	global_load_lds_dwordx4 v[192:193], off
	s_waitcnt vmcnt(8)
	s_waitcnt lgkmcnt(0)
	s_setprio 1
	s_barrier
	v_mfma_f32_16x16x32_bf16 v[126:129], v[144:147], v[176:179], v[126:129]
	v_mfma_f32_16x16x32_bf16 v[122:125], v[152:155], v[176:179], v[122:125]
	v_mfma_f32_16x16x32_bf16 v[118:121], v[144:147], v[184:187], v[118:121]
	v_mfma_f32_16x16x32_bf16 v[110:113], v[152:155], v[184:187], v[110:113]
	v_mfma_f32_16x16x32_bf16 v[102:105], v[144:147], v[196:199], v[102:105]
	v_mfma_f32_16x16x32_bf16 v[94:97], v[152:155], v[196:199], v[94:97]
	v_mfma_f32_16x16x32_bf16 v[86:89], v[144:147], v[204:207], v[86:89]
	v_mfma_f32_16x16x32_bf16 v[78:81], v[152:155], v[204:207], v[78:81]
	v_mfma_f32_16x16x32_bf16 v[126:129], v[148:151], v[180:183], v[126:129]
	v_mfma_f32_16x16x32_bf16 v[122:125], v[156:159], v[180:183], v[122:125]
	v_mfma_f32_16x16x32_bf16 v[118:121], v[148:151], v[188:191], v[118:121]
	v_mfma_f32_16x16x32_bf16 v[110:113], v[156:159], v[188:191], v[110:113]
	v_mfma_f32_16x16x32_bf16 v[102:105], v[148:151], v[200:203], v[102:105]
	v_mfma_f32_16x16x32_bf16 v[94:97], v[156:159], v[200:203], v[94:97]
	v_mfma_f32_16x16x32_bf16 v[86:89], v[148:151], v[208:211], v[86:89]
	v_mfma_f32_16x16x32_bf16 v[78:81], v[156:159], v[208:211], v[78:81]
	v_mfma_f32_16x16x32_bf16 v[114:117], v[160:163], v[176:179], v[114:117]
	v_mfma_f32_16x16x32_bf16 v[106:109], v[168:171], v[176:179], v[106:109]
	v_mfma_f32_16x16x32_bf16 v[98:101], v[160:163], v[184:187], v[98:101]
	v_mfma_f32_16x16x32_bf16 v[90:93], v[168:171], v[184:187], v[90:93]
	v_mfma_f32_16x16x32_bf16 v[82:85], v[160:163], v[196:199], v[82:85]
	v_mfma_f32_16x16x32_bf16 v[74:77], v[168:171], v[196:199], v[74:77]
	v_mfma_f32_16x16x32_bf16 v[70:73], v[160:163], v[204:207], v[70:73]
	v_mfma_f32_16x16x32_bf16 v[66:69], v[168:171], v[204:207], v[66:69]
	v_mfma_f32_16x16x32_bf16 v[114:117], v[164:167], v[180:183], v[114:117]
	v_mfma_f32_16x16x32_bf16 v[106:109], v[172:175], v[180:183], v[106:109]
	v_mfma_f32_16x16x32_bf16 v[98:101], v[164:167], v[188:191], v[98:101]
	v_mfma_f32_16x16x32_bf16 v[90:93], v[172:175], v[188:191], v[90:93]
	v_mfma_f32_16x16x32_bf16 v[82:85], v[164:167], v[200:203], v[82:85]
	v_mfma_f32_16x16x32_bf16 v[74:77], v[172:175], v[200:203], v[74:77]
	v_mfma_f32_16x16x32_bf16 v[70:73], v[164:167], v[208:211], v[70:73]
	v_mfma_f32_16x16x32_bf16 v[66:69], v[172:175], v[208:211], v[66:69]
	s_setprio 0
	s_barrier
	s_add_i32 s68, s59, s51
	v_lshl_add_u64 v[192:193], s[42:43], 0, v[130:131]
	s_mov_b32 m0, s68
	ds_read_b128 v[176:179], v143 offset:16384
	ds_read_b128 v[180:183], v143 offset:17408
	ds_read_b128 v[184:187], v143 offset:18432
	ds_read_b128 v[188:191], v143 offset:19456
	ds_read_b128 v[196:199], v143 offset:20480
	ds_read_b128 v[200:203], v143 offset:21504
	ds_read_b128 v[204:207], v143 offset:22528
	ds_read_b128 v[208:211], v143 offset:23552
	global_load_lds_dwordx4 v[192:193], off
	s_add_i32 m0, s68, 0x2000
	s_add_u32 s68, s42, 0x100000
	v_lshl_add_u64 v[212:213], s[42:43], 0, v[132:133]
	s_addc_u32 s69, s43, 0
	s_add_i32 s70, s60, s51
	global_load_lds_dwordx4 v[212:213], off
	v_lshl_add_u64 v[214:215], s[68:69], 0, v[130:131]
	s_mov_b32 m0, s70
	v_lshl_add_u64 v[216:217], s[46:47], 0, v[132:133]
	global_load_lds_dwordx4 v[214:215], off
	v_lshl_add_u64 v[214:215], s[68:69], 0, v[132:133]
	s_add_i32 m0, s70, 0x2000
	s_nop 0
	global_load_lds_dwordx4 v[214:215], off
	v_lshl_add_u64 v[214:215], s[46:47], 0, v[130:131]
	s_mov_b32 m0, s29
	s_nop 0
	global_load_lds_dwordx4 v[214:215], off
	s_mov_b32 m0, s52
	s_nop 0
	global_load_lds_dwordx4 v[216:217], off
	s_waitcnt vmcnt(8)
	s_waitcnt lgkmcnt(0)
	s_setprio 1
	s_barrier
	v_mfma_f32_16x16x32_bf16 v[62:65], v[144:147], v[176:179], v[62:65]
	v_mfma_f32_16x16x32_bf16 v[58:61], v[152:155], v[176:179], v[58:61]
	v_mfma_f32_16x16x32_bf16 v[54:57], v[144:147], v[184:187], v[54:57]
	v_mfma_f32_16x16x32_bf16 v[46:49], v[152:155], v[184:187], v[46:49]
	v_mfma_f32_16x16x32_bf16 v[38:41], v[144:147], v[196:199], v[38:41]
	v_mfma_f32_16x16x32_bf16 v[30:33], v[152:155], v[196:199], v[30:33]
	v_mfma_f32_16x16x32_bf16 v[22:25], v[144:147], v[204:207], v[22:25]
	v_mfma_f32_16x16x32_bf16 v[14:17], v[152:155], v[204:207], v[14:17]
	v_mfma_f32_16x16x32_bf16 v[62:65], v[148:151], v[180:183], v[62:65]
	v_mfma_f32_16x16x32_bf16 v[58:61], v[156:159], v[180:183], v[58:61]
	v_mfma_f32_16x16x32_bf16 v[54:57], v[148:151], v[188:191], v[54:57]
	v_mfma_f32_16x16x32_bf16 v[46:49], v[156:159], v[188:191], v[46:49]
	v_mfma_f32_16x16x32_bf16 v[38:41], v[148:151], v[200:203], v[38:41]
	v_mfma_f32_16x16x32_bf16 v[30:33], v[156:159], v[200:203], v[30:33]
	v_mfma_f32_16x16x32_bf16 v[22:25], v[148:151], v[208:211], v[22:25]
	v_mfma_f32_16x16x32_bf16 v[14:17], v[156:159], v[208:211], v[14:17]
	v_mfma_f32_16x16x32_bf16 v[50:53], v[160:163], v[176:179], v[50:53]
	v_mfma_f32_16x16x32_bf16 v[42:45], v[168:171], v[176:179], v[42:45]
	v_mfma_f32_16x16x32_bf16 v[34:37], v[160:163], v[184:187], v[34:37]
	v_mfma_f32_16x16x32_bf16 v[26:29], v[168:171], v[184:187], v[26:29]
	v_mfma_f32_16x16x32_bf16 v[18:21], v[160:163], v[196:199], v[18:21]
	v_mfma_f32_16x16x32_bf16 v[10:13], v[168:171], v[196:199], v[10:13]
	v_mfma_f32_16x16x32_bf16 v[6:9], v[160:163], v[204:207], v[6:9]
	v_mfma_f32_16x16x32_bf16 v[2:5], v[168:171], v[204:207], v[2:5]
	v_mfma_f32_16x16x32_bf16 v[50:53], v[164:167], v[180:183], v[50:53]
	v_mfma_f32_16x16x32_bf16 v[42:45], v[172:175], v[180:183], v[42:45]
	v_mfma_f32_16x16x32_bf16 v[34:37], v[164:167], v[188:191], v[34:37]
	v_mfma_f32_16x16x32_bf16 v[26:29], v[172:175], v[188:191], v[26:29]
	v_mfma_f32_16x16x32_bf16 v[18:21], v[164:167], v[200:203], v[18:21]
	v_mfma_f32_16x16x32_bf16 v[10:13], v[172:175], v[200:203], v[10:13]
	v_mfma_f32_16x16x32_bf16 v[6:9], v[164:167], v[208:211], v[6:9]
	v_mfma_f32_16x16x32_bf16 v[2:5], v[172:175], v[208:211], v[2:5]
	s_setprio 0
	s_barrier
	s_add_i32 s68, 0, 0x18000
	s_add_i32 s69, 0, 0x1c000
	v_add_u32_e32 v156, s68, v139
	v_add_u32_e32 v172, s69, v139
	ds_read_b128 v[144:147], v156
	ds_read_b128 v[148:151], v156 offset:1024
	ds_read_b128 v[152:155], v156 offset:2048
	ds_read_b128 v[156:159], v156 offset:3072
	ds_read_b128 v[160:163], v172
	ds_read_b128 v[164:167], v172 offset:1024
	ds_read_b128 v[168:171], v172 offset:2048
	ds_read_b128 v[172:175], v172 offset:3072
	s_add_u32 s46, s46, 0x100000
	s_addc_u32 s47, s47, 0
	s_mov_b32 m0, s53
	v_lshl_add_u64 v[218:219], s[46:47], 0, v[130:131]
	ds_read_b128 v[176:179], v143 offset:32768
	ds_read_b128 v[180:183], v143 offset:33792
	ds_read_b128 v[184:187], v143 offset:34816
	ds_read_b128 v[188:191], v143 offset:35840
	ds_read_b128 v[196:199], v143 offset:36864
	ds_read_b128 v[200:203], v143 offset:37888
	ds_read_b128 v[204:207], v143 offset:38912
	ds_read_b128 v[208:211], v143 offset:39936
	global_load_lds_dwordx4 v[218:219], off
	v_lshl_add_u64 v[218:219], s[46:47], 0, v[132:133]
	s_mov_b32 m0, s54
	s_nop 0
	global_load_lds_dwordx4 v[218:219], off
	s_waitcnt vmcnt(8)
	s_waitcnt lgkmcnt(0)
	s_setprio 1
	s_barrier
	v_mfma_f32_16x16x32_bf16 v[126:129], v[144:147], v[176:179], v[126:129]
	v_mfma_f32_16x16x32_bf16 v[122:125], v[152:155], v[176:179], v[122:125]
	v_mfma_f32_16x16x32_bf16 v[118:121], v[144:147], v[184:187], v[118:121]
	v_mfma_f32_16x16x32_bf16 v[110:113], v[152:155], v[184:187], v[110:113]
	v_mfma_f32_16x16x32_bf16 v[102:105], v[144:147], v[196:199], v[102:105]
	v_mfma_f32_16x16x32_bf16 v[94:97], v[152:155], v[196:199], v[94:97]
	v_mfma_f32_16x16x32_bf16 v[86:89], v[144:147], v[204:207], v[86:89]
	v_mfma_f32_16x16x32_bf16 v[78:81], v[152:155], v[204:207], v[78:81]
	v_mfma_f32_16x16x32_bf16 v[126:129], v[148:151], v[180:183], v[126:129]
	v_mfma_f32_16x16x32_bf16 v[122:125], v[156:159], v[180:183], v[122:125]
	v_mfma_f32_16x16x32_bf16 v[118:121], v[148:151], v[188:191], v[118:121]
	v_mfma_f32_16x16x32_bf16 v[110:113], v[156:159], v[188:191], v[110:113]
	v_mfma_f32_16x16x32_bf16 v[102:105], v[148:151], v[200:203], v[102:105]
	v_mfma_f32_16x16x32_bf16 v[94:97], v[156:159], v[200:203], v[94:97]
	v_mfma_f32_16x16x32_bf16 v[86:89], v[148:151], v[208:211], v[86:89]
	v_mfma_f32_16x16x32_bf16 v[78:81], v[156:159], v[208:211], v[78:81]
	v_mfma_f32_16x16x32_bf16 v[114:117], v[160:163], v[176:179], v[114:117]
	v_mfma_f32_16x16x32_bf16 v[106:109], v[168:171], v[176:179], v[106:109]
	v_mfma_f32_16x16x32_bf16 v[98:101], v[160:163], v[184:187], v[98:101]
	v_mfma_f32_16x16x32_bf16 v[90:93], v[168:171], v[184:187], v[90:93]
	v_mfma_f32_16x16x32_bf16 v[82:85], v[160:163], v[196:199], v[82:85]
	v_mfma_f32_16x16x32_bf16 v[74:77], v[168:171], v[196:199], v[74:77]
	v_mfma_f32_16x16x32_bf16 v[70:73], v[160:163], v[204:207], v[70:73]
	v_mfma_f32_16x16x32_bf16 v[66:69], v[168:171], v[204:207], v[66:69]
	v_mfma_f32_16x16x32_bf16 v[114:117], v[164:167], v[180:183], v[114:117]
	v_mfma_f32_16x16x32_bf16 v[106:109], v[172:175], v[180:183], v[106:109]
	v_mfma_f32_16x16x32_bf16 v[98:101], v[164:167], v[188:191], v[98:101]
	v_mfma_f32_16x16x32_bf16 v[90:93], v[172:175], v[188:191], v[90:93]
	v_mfma_f32_16x16x32_bf16 v[82:85], v[164:167], v[200:203], v[82:85]
	v_mfma_f32_16x16x32_bf16 v[74:77], v[172:175], v[200:203], v[74:77]
	v_mfma_f32_16x16x32_bf16 v[70:73], v[164:167], v[208:211], v[70:73]
	v_mfma_f32_16x16x32_bf16 v[66:69], v[172:175], v[208:211], v[66:69]
	s_setprio 0
	s_barrier
	s_add_i32 s46, s68, s51
	v_lshl_add_u64 v[192:193], v[192:193], 0, s[10:11]
	s_mov_b32 m0, s46
	ds_read_b128 v[176:179], v143 offset:49152
	ds_read_b128 v[180:183], v143 offset:50176
	ds_read_b128 v[184:187], v143 offset:51200
	ds_read_b128 v[188:191], v143 offset:52224
	ds_read_b128 v[196:199], v143 offset:53248
	ds_read_b128 v[200:203], v143 offset:54272
	ds_read_b128 v[204:207], v143 offset:55296
	ds_read_b128 v[208:211], v143 offset:56320
	global_load_lds_dwordx4 v[192:193], off
	s_add_i32 m0, s46, 0x2000
	s_add_u32 s42, s42, 0x100080
	v_lshl_add_u64 v[192:193], v[212:213], 0, s[10:11]
	s_addc_u32 s43, s43, 0
	s_add_i32 s46, s69, s51
	global_load_lds_dwordx4 v[192:193], off
	v_lshl_add_u64 v[192:193], s[42:43], 0, v[130:131]
	s_mov_b32 m0, s46
	s_nop 0
	global_load_lds_dwordx4 v[192:193], off
	v_lshl_add_u64 v[192:193], s[42:43], 0, v[132:133]
	s_add_i32 m0, s46, 0x2000
	s_nop 0
	global_load_lds_dwordx4 v[192:193], off
	v_lshl_add_u64 v[192:193], v[214:215], 0, s[10:11]
	s_mov_b32 m0, s56
	s_nop 0
	global_load_lds_dwordx4 v[192:193], off
	v_lshl_add_u64 v[192:193], v[216:217], 0, s[10:11]
	s_mov_b32 m0, s57
	s_nop 0
	global_load_lds_dwordx4 v[192:193], off
	s_nop 0
	s_waitcnt vmcnt(8)
	s_waitcnt lgkmcnt(0)
	s_setprio 1
	s_barrier
	v_mfma_f32_16x16x32_bf16 v[62:65], v[144:147], v[176:179], v[62:65]
	v_mfma_f32_16x16x32_bf16 v[58:61], v[152:155], v[176:179], v[58:61]
	v_mfma_f32_16x16x32_bf16 v[54:57], v[144:147], v[184:187], v[54:57]
	v_mfma_f32_16x16x32_bf16 v[46:49], v[152:155], v[184:187], v[46:49]
	v_mfma_f32_16x16x32_bf16 v[38:41], v[144:147], v[196:199], v[38:41]
	v_mfma_f32_16x16x32_bf16 v[30:33], v[152:155], v[196:199], v[30:33]
	v_mfma_f32_16x16x32_bf16 v[22:25], v[144:147], v[204:207], v[22:25]
	v_mfma_f32_16x16x32_bf16 v[14:17], v[152:155], v[204:207], v[14:17]
	v_mfma_f32_16x16x32_bf16 v[62:65], v[148:151], v[180:183], v[62:65]
	v_mfma_f32_16x16x32_bf16 v[58:61], v[156:159], v[180:183], v[58:61]
	v_mfma_f32_16x16x32_bf16 v[54:57], v[148:151], v[188:191], v[54:57]
	v_mfma_f32_16x16x32_bf16 v[46:49], v[156:159], v[188:191], v[46:49]
	v_mfma_f32_16x16x32_bf16 v[38:41], v[148:151], v[200:203], v[38:41]
	v_mfma_f32_16x16x32_bf16 v[30:33], v[156:159], v[200:203], v[30:33]
	v_mfma_f32_16x16x32_bf16 v[22:25], v[148:151], v[208:211], v[22:25]
	v_mfma_f32_16x16x32_bf16 v[14:17], v[156:159], v[208:211], v[14:17]
	v_mfma_f32_16x16x32_bf16 v[50:53], v[160:163], v[176:179], v[50:53]
	v_mfma_f32_16x16x32_bf16 v[42:45], v[168:171], v[176:179], v[42:45]
	v_mfma_f32_16x16x32_bf16 v[34:37], v[160:163], v[184:187], v[34:37]
	v_mfma_f32_16x16x32_bf16 v[26:29], v[168:171], v[184:187], v[26:29]
	v_mfma_f32_16x16x32_bf16 v[18:21], v[160:163], v[196:199], v[18:21]
	v_mfma_f32_16x16x32_bf16 v[10:13], v[168:171], v[196:199], v[10:13]
	v_mfma_f32_16x16x32_bf16 v[6:9], v[160:163], v[204:207], v[6:9]
	v_mfma_f32_16x16x32_bf16 v[2:5], v[168:171], v[204:207], v[2:5]
	v_mfma_f32_16x16x32_bf16 v[50:53], v[164:167], v[180:183], v[50:53]
	v_mfma_f32_16x16x32_bf16 v[42:45], v[172:175], v[180:183], v[42:45]
	v_mfma_f32_16x16x32_bf16 v[34:37], v[164:167], v[188:191], v[34:37]
	v_mfma_f32_16x16x32_bf16 v[26:29], v[172:175], v[188:191], v[26:29]
	v_mfma_f32_16x16x32_bf16 v[18:21], v[164:167], v[200:203], v[18:21]
	v_mfma_f32_16x16x32_bf16 v[10:13], v[172:175], v[200:203], v[10:13]
	v_mfma_f32_16x16x32_bf16 v[6:9], v[164:167], v[208:211], v[6:9]
	v_mfma_f32_16x16x32_bf16 v[2:5], v[172:175], v[208:211], v[2:5]
	s_setprio 0
	s_barrier
	s_add_i32 s67, s67, 2
	s_add_u32 s40, s40, 0x100
	s_addc_u32 s41, s41, 0
	s_add_u32 s65, s65, 0x100
	s_addc_u32 s66, s66, 0
	s_cmp_gt_u32 s67, 61
	s_cbranch_scc0 .LBB0_335
	s_and_b64 vcc, exec, s[12:13]
	s_cbranch_vccz .LBB0_338
	s_barrier

.LBB0_657:
	ds_read_b128 v[158:161], v155
	ds_read_b128 v[162:165], v155 offset:1024
	ds_read_b128 v[166:169], v155 offset:2048
	ds_read_b128 v[170:173], v155 offset:3072
	ds_read_b128 v[174:177], v156
	ds_read_b128 v[178:181], v156 offset:1024
	ds_read_b128 v[182:185], v156 offset:2048
	ds_read_b128 v[186:189], v156 offset:3072
	s_add_u32 s28, s26, 0xfff00080
	s_addc_u32 s29, s27, -1
	s_cmp_eq_u32 s58, 60
	s_cselect_b32 s31, s21, s29
	s_cselect_b32 s30, s54, s28
	s_cselect_b32 s29, s19, s57
	s_cselect_b32 s28, s55, s56
	v_lshl_add_u64 v[224:225], s[26:27], 0, v[138:139]
	s_add_i32 m0, s17, 0xc000
	ds_read_b128 v[190:193], v157
	ds_read_b128 v[196:199], v157 offset:1024
	ds_read_b128 v[200:203], v157 offset:2048
	ds_read_b128 v[204:207], v157 offset:3072
	ds_read_b128 v[208:211], v157 offset:4096
	ds_read_b128 v[212:215], v157 offset:5120
	ds_read_b128 v[216:219], v157 offset:6144
	ds_read_b128 v[220:223], v157 offset:7168
	global_load_lds_dwordx4 v[224:225], off
	v_lshl_add_u64 v[224:225], s[26:27], 0, v[140:141]
	s_add_i32 m0, s17, 0xe000
	s_nop 0
	global_load_lds_dwordx4 v[224:225], off
	s_nop 0
	s_waitcnt vmcnt(8)
	s_waitcnt lgkmcnt(0)
	s_setprio 1
	s_barrier
	v_mfma_f32_16x16x32_bf16 v[126:129], v[158:161], v[190:193], v[126:129]
	v_mfma_f32_16x16x32_bf16 v[122:125], v[166:169], v[190:193], v[122:125]
	v_mfma_f32_16x16x32_bf16 v[118:121], v[158:161], v[200:203], v[118:121]
	v_mfma_f32_16x16x32_bf16 v[114:117], v[166:169], v[200:203], v[114:117]
	v_mfma_f32_16x16x32_bf16 v[102:105], v[158:161], v[208:211], v[102:105]
	v_mfma_f32_16x16x32_bf16 v[98:101], v[166:169], v[208:211], v[98:101]
	v_mfma_f32_16x16x32_bf16 v[86:89], v[158:161], v[216:219], v[86:89]
	v_mfma_f32_16x16x32_bf16 v[82:85], v[166:169], v[216:219], v[82:85]
	v_mfma_f32_16x16x32_bf16 v[126:129], v[162:165], v[196:199], v[126:129]
	v_mfma_f32_16x16x32_bf16 v[122:125], v[170:173], v[196:199], v[122:125]
	v_mfma_f32_16x16x32_bf16 v[118:121], v[162:165], v[204:207], v[118:121]
	v_mfma_f32_16x16x32_bf16 v[114:117], v[170:173], v[204:207], v[114:117]
	v_mfma_f32_16x16x32_bf16 v[102:105], v[162:165], v[212:215], v[102:105]
	v_mfma_f32_16x16x32_bf16 v[98:101], v[170:173], v[212:215], v[98:101]
	v_mfma_f32_16x16x32_bf16 v[86:89], v[162:165], v[220:223], v[86:89]
	v_mfma_f32_16x16x32_bf16 v[82:85], v[170:173], v[220:223], v[82:85]
	v_mfma_f32_16x16x32_bf16 v[110:113], v[174:177], v[190:193], v[110:113]
	v_mfma_f32_16x16x32_bf16 v[106:109], v[182:185], v[190:193], v[106:109]
	v_mfma_f32_16x16x32_bf16 v[94:97], v[174:177], v[200:203], v[94:97]
	v_mfma_f32_16x16x32_bf16 v[90:93], v[182:185], v[200:203], v[90:93]
	v_mfma_f32_16x16x32_bf16 v[78:81], v[174:177], v[208:211], v[78:81]
	v_mfma_f32_16x16x32_bf16 v[74:77], v[182:185], v[208:211], v[74:77]
	v_mfma_f32_16x16x32_bf16 v[70:73], v[174:177], v[216:219], v[70:73]
	v_mfma_f32_16x16x32_bf16 v[66:69], v[182:185], v[216:219], v[66:69]
	v_mfma_f32_16x16x32_bf16 v[110:113], v[178:181], v[196:199], v[110:113]
	v_mfma_f32_16x16x32_bf16 v[106:109], v[186:189], v[196:199], v[106:109]
	v_mfma_f32_16x16x32_bf16 v[94:97], v[178:181], v[204:207], v[94:97]
	v_mfma_f32_16x16x32_bf16 v[90:93], v[186:189], v[204:207], v[90:93]
	v_mfma_f32_16x16x32_bf16 v[78:81], v[178:181], v[212:215], v[78:81]
	v_mfma_f32_16x16x32_bf16 v[74:77], v[186:189], v[212:215], v[74:77]
	v_mfma_f32_16x16x32_bf16 v[70:73], v[178:181], v[220:223], v[70:73]
	v_mfma_f32_16x16x32_bf16 v[66:69], v[186:189], v[220:223], v[66:69]
	s_setprio 0
	s_barrier
	s_add_i32 s59, s50, s41
	v_lshl_add_u64 v[224:225], s[28:29], 0, v[134:135]
	s_mov_b32 m0, s59
	ds_read_b128 v[190:193], v157 offset:16384
	ds_read_b128 v[196:199], v157 offset:17408
	ds_read_b128 v[200:203], v157 offset:18432
	ds_read_b128 v[204:207], v157 offset:19456
	ds_read_b128 v[208:211], v157 offset:20480
	ds_read_b128 v[212:215], v157 offset:21504
	ds_read_b128 v[216:219], v157 offset:22528
	ds_read_b128 v[220:223], v157 offset:23552
	global_load_lds_dwordx4 v[224:225], off
	s_add_i32 m0, s59, 0x2000
	s_add_u32 s60, s28, 0x100000
	v_lshl_add_u64 v[226:227], s[28:29], 0, v[136:137]
	s_addc_u32 s61, s29, 0
	s_add_i32 s59, s51, s41
	global_load_lds_dwordx4 v[226:227], off
	v_lshl_add_u64 v[228:229], s[60:61], 0, v[134:135]
	s_mov_b32 m0, s59
	v_lshl_add_u64 v[230:231], s[30:31], 0, v[132:133]
	global_load_lds_dwordx4 v[228:229], off
	v_lshl_add_u64 v[228:229], s[60:61], 0, v[136:137]
	s_add_i32 m0, s59, 0x2000
	s_nop 0
	global_load_lds_dwordx4 v[228:229], off
	v_lshl_add_u64 v[228:229], s[30:31], 0, v[130:131]
	s_mov_b32 m0, s17
	s_nop 0
	global_load_lds_dwordx4 v[228:229], off
	s_mov_b32 m0, s42
	s_nop 0
	global_load_lds_dwordx4 v[230:231], off
	s_waitcnt vmcnt(8)
	s_waitcnt lgkmcnt(0)
	s_setprio 1
	s_barrier
	v_mfma_f32_16x16x32_bf16 v[62:65], v[158:161], v[190:193], v[62:65]
	v_mfma_f32_16x16x32_bf16 v[58:61], v[166:169], v[190:193], v[58:61]
	v_mfma_f32_16x16x32_bf16 v[54:57], v[158:161], v[200:203], v[54:57]
	v_mfma_f32_16x16x32_bf16 v[50:53], v[166:169], v[200:203], v[50:53]
	v_mfma_f32_16x16x32_bf16 v[38:41], v[158:161], v[208:211], v[38:41]
	v_mfma_f32_16x16x32_bf16 v[34:37], v[166:169], v[208:211], v[34:37]
	v_mfma_f32_16x16x32_bf16 v[22:25], v[158:161], v[216:219], v[22:25]
	v_mfma_f32_16x16x32_bf16 v[18:21], v[166:169], v[216:219], v[18:21]
	v_mfma_f32_16x16x32_bf16 v[62:65], v[162:165], v[196:199], v[62:65]
	v_mfma_f32_16x16x32_bf16 v[58:61], v[170:173], v[196:199], v[58:61]
	v_mfma_f32_16x16x32_bf16 v[54:57], v[162:165], v[204:207], v[54:57]
	v_mfma_f32_16x16x32_bf16 v[50:53], v[170:173], v[204:207], v[50:53]
	v_mfma_f32_16x16x32_bf16 v[38:41], v[162:165], v[212:215], v[38:41]
	v_mfma_f32_16x16x32_bf16 v[34:37], v[170:173], v[212:215], v[34:37]
	v_mfma_f32_16x16x32_bf16 v[22:25], v[162:165], v[220:223], v[22:25]
	v_mfma_f32_16x16x32_bf16 v[18:21], v[170:173], v[220:223], v[18:21]
	v_mfma_f32_16x16x32_bf16 v[46:49], v[174:177], v[190:193], v[46:49]
	v_mfma_f32_16x16x32_bf16 v[42:45], v[182:185], v[190:193], v[42:45]
	v_mfma_f32_16x16x32_bf16 v[30:33], v[174:177], v[200:203], v[30:33]
	v_mfma_f32_16x16x32_bf16 v[26:29], v[182:185], v[200:203], v[26:29]
	v_mfma_f32_16x16x32_bf16 v[14:17], v[174:177], v[208:211], v[14:17]
	v_mfma_f32_16x16x32_bf16 v[10:13], v[182:185], v[208:211], v[10:13]
	v_mfma_f32_16x16x32_bf16 v[6:9], v[174:177], v[216:219], v[6:9]
	v_mfma_f32_16x16x32_bf16 v[2:5], v[182:185], v[216:219], v[2:5]
	v_mfma_f32_16x16x32_bf16 v[46:49], v[178:181], v[196:199], v[46:49]
	v_mfma_f32_16x16x32_bf16 v[42:45], v[186:189], v[196:199], v[42:45]
	v_mfma_f32_16x16x32_bf16 v[30:33], v[178:181], v[204:207], v[30:33]
	v_mfma_f32_16x16x32_bf16 v[26:29], v[186:189], v[204:207], v[26:29]
	v_mfma_f32_16x16x32_bf16 v[14:17], v[178:181], v[212:215], v[14:17]
	v_mfma_f32_16x16x32_bf16 v[10:13], v[186:189], v[212:215], v[10:13]
	v_mfma_f32_16x16x32_bf16 v[6:9], v[178:181], v[220:223], v[6:9]
	v_mfma_f32_16x16x32_bf16 v[2:5], v[186:189], v[220:223], v[2:5]
	s_setprio 0
	s_barrier
	s_add_i32 s59, 0, 0x18000
	s_add_i32 s60, 0, 0x1c000
	v_add_u32_e32 v170, s59, v153
	v_add_u32_e32 v186, s60, v153
	ds_read_b128 v[158:161], v170
	ds_read_b128 v[162:165], v170 offset:1024
	ds_read_b128 v[166:169], v170 offset:2048
	ds_read_b128 v[170:173], v170 offset:3072
	ds_read_b128 v[174:177], v186
	ds_read_b128 v[178:181], v186 offset:1024
	ds_read_b128 v[182:185], v186 offset:2048
	ds_read_b128 v[186:189], v186 offset:3072
	s_add_u32 s30, s30, 0x100000
	s_addc_u32 s31, s31, 0
	s_mov_b32 m0, s43
	v_lshl_add_u64 v[232:233], s[30:31], 0, v[130:131]
	ds_read_b128 v[190:193], v157 offset:32768
	ds_read_b128 v[196:199], v157 offset:33792
	ds_read_b128 v[200:203], v157 offset:34816
	ds_read_b128 v[204:207], v157 offset:35840
	ds_read_b128 v[208:211], v157 offset:36864
	ds_read_b128 v[212:215], v157 offset:37888
	ds_read_b128 v[216:219], v157 offset:38912
	ds_read_b128 v[220:223], v157 offset:39936
	global_load_lds_dwordx4 v[232:233], off
	v_lshl_add_u64 v[232:233], s[30:31], 0, v[132:133]
	s_mov_b32 m0, s45
	s_nop 0
	global_load_lds_dwordx4 v[232:233], off
	s_waitcnt vmcnt(8)
	s_waitcnt lgkmcnt(0)
	s_setprio 1
	s_barrier
	v_mfma_f32_16x16x32_bf16 v[126:129], v[158:161], v[190:193], v[126:129]
	v_mfma_f32_16x16x32_bf16 v[122:125], v[166:169], v[190:193], v[122:125]
	v_mfma_f32_16x16x32_bf16 v[118:121], v[158:161], v[200:203], v[118:121]
	v_mfma_f32_16x16x32_bf16 v[114:117], v[166:169], v[200:203], v[114:117]
	v_mfma_f32_16x16x32_bf16 v[102:105], v[158:161], v[208:211], v[102:105]
	v_mfma_f32_16x16x32_bf16 v[98:101], v[166:169], v[208:211], v[98:101]
	v_mfma_f32_16x16x32_bf16 v[86:89], v[158:161], v[216:219], v[86:89]
	v_mfma_f32_16x16x32_bf16 v[82:85], v[166:169], v[216:219], v[82:85]
	v_mfma_f32_16x16x32_bf16 v[126:129], v[162:165], v[196:199], v[126:129]
	v_mfma_f32_16x16x32_bf16 v[122:125], v[170:173], v[196:199], v[122:125]
	v_mfma_f32_16x16x32_bf16 v[118:121], v[162:165], v[204:207], v[118:121]
	v_mfma_f32_16x16x32_bf16 v[114:117], v[170:173], v[204:207], v[114:117]
	v_mfma_f32_16x16x32_bf16 v[102:105], v[162:165], v[212:215], v[102:105]
	v_mfma_f32_16x16x32_bf16 v[98:101], v[170:173], v[212:215], v[98:101]
	v_mfma_f32_16x16x32_bf16 v[86:89], v[162:165], v[220:223], v[86:89]
	v_mfma_f32_16x16x32_bf16 v[82:85], v[170:173], v[220:223], v[82:85]
	v_mfma_f32_16x16x32_bf16 v[110:113], v[174:177], v[190:193], v[110:113]
	v_mfma_f32_16x16x32_bf16 v[106:109], v[182:185], v[190:193], v[106:109]
	v_mfma_f32_16x16x32_bf16 v[94:97], v[174:177], v[200:203], v[94:97]
	v_mfma_f32_16x16x32_bf16 v[90:93], v[182:185], v[200:203], v[90:93]
	v_mfma_f32_16x16x32_bf16 v[78:81], v[174:177], v[208:211], v[78:81]
	v_mfma_f32_16x16x32_bf16 v[74:77], v[182:185], v[208:211], v[74:77]
	v_mfma_f32_16x16x32_bf16 v[70:73], v[174:177], v[216:219], v[70:73]
	v_mfma_f32_16x16x32_bf16 v[66:69], v[182:185], v[216:219], v[66:69]
	v_mfma_f32_16x16x32_bf16 v[110:113], v[178:181], v[196:199], v[110:113]
	v_mfma_f32_16x16x32_bf16 v[106:109], v[186:189], v[196:199], v[106:109]
	v_mfma_f32_16x16x32_bf16 v[94:97], v[178:181], v[204:207], v[94:97]
	v_mfma_f32_16x16x32_bf16 v[90:93], v[186:189], v[204:207], v[90:93]
	v_mfma_f32_16x16x32_bf16 v[78:81], v[178:181], v[212:215], v[78:81]
	v_mfma_f32_16x16x32_bf16 v[74:77], v[186:189], v[212:215], v[74:77]
	v_mfma_f32_16x16x32_bf16 v[70:73], v[178:181], v[220:223], v[70:73]
	v_mfma_f32_16x16x32_bf16 v[66:69], v[186:189], v[220:223], v[66:69]
	s_setprio 0
	s_barrier
	s_add_i32 s30, s59, s41
	v_lshl_add_u64 v[224:225], v[224:225], 0, s[12:13]
	s_mov_b32 m0, s30
	ds_read_b128 v[190:193], v157 offset:49152
	ds_read_b128 v[196:199], v157 offset:50176
	ds_read_b128 v[200:203], v157 offset:51200
	ds_read_b128 v[204:207], v157 offset:52224
	ds_read_b128 v[208:211], v157 offset:53248
	ds_read_b128 v[212:215], v157 offset:54272
	ds_read_b128 v[216:219], v157 offset:55296
	ds_read_b128 v[220:223], v157 offset:56320
	global_load_lds_dwordx4 v[224:225], off
	s_add_i32 m0, s30, 0x2000
	s_add_u32 s28, s28, 0x100080
	v_lshl_add_u64 v[224:225], v[226:227], 0, s[12:13]
	s_addc_u32 s29, s29, 0
	s_add_i32 s30, s60, s41
	global_load_lds_dwordx4 v[224:225], off
	v_lshl_add_u64 v[224:225], s[28:29], 0, v[134:135]
	s_mov_b32 m0, s30
	s_nop 0
	global_load_lds_dwordx4 v[224:225], off
	v_lshl_add_u64 v[224:225], s[28:29], 0, v[136:137]
	s_add_i32 m0, s30, 0x2000
	s_nop 0
	global_load_lds_dwordx4 v[224:225], off
	v_lshl_add_u64 v[224:225], v[228:229], 0, s[12:13]
	s_mov_b32 m0, s47
	s_nop 0
	global_load_lds_dwordx4 v[224:225], off
	v_lshl_add_u64 v[224:225], v[230:231], 0, s[12:13]
	s_mov_b32 m0, s48
	s_nop 0
	global_load_lds_dwordx4 v[224:225], off
	s_nop 0
	s_waitcnt vmcnt(8)
	s_waitcnt lgkmcnt(0)
	s_setprio 1
	s_barrier
	v_mfma_f32_16x16x32_bf16 v[62:65], v[158:161], v[190:193], v[62:65]
	v_mfma_f32_16x16x32_bf16 v[58:61], v[166:169], v[190:193], v[58:61]
	v_mfma_f32_16x16x32_bf16 v[54:57], v[158:161], v[200:203], v[54:57]
	v_mfma_f32_16x16x32_bf16 v[50:53], v[166:169], v[200:203], v[50:53]
	v_mfma_f32_16x16x32_bf16 v[38:41], v[158:161], v[208:211], v[38:41]
	v_mfma_f32_16x16x32_bf16 v[34:37], v[166:169], v[208:211], v[34:37]
	v_mfma_f32_16x16x32_bf16 v[22:25], v[158:161], v[216:219], v[22:25]
	v_mfma_f32_16x16x32_bf16 v[18:21], v[166:169], v[216:219], v[18:21]
	v_mfma_f32_16x16x32_bf16 v[62:65], v[162:165], v[196:199], v[62:65]
	v_mfma_f32_16x16x32_bf16 v[58:61], v[170:173], v[196:199], v[58:61]
	v_mfma_f32_16x16x32_bf16 v[54:57], v[162:165], v[204:207], v[54:57]
	v_mfma_f32_16x16x32_bf16 v[50:53], v[170:173], v[204:207], v[50:53]
	v_mfma_f32_16x16x32_bf16 v[38:41], v[162:165], v[212:215], v[38:41]
	v_mfma_f32_16x16x32_bf16 v[34:37], v[170:173], v[212:215], v[34:37]
	v_mfma_f32_16x16x32_bf16 v[22:25], v[162:165], v[220:223], v[22:25]
	v_mfma_f32_16x16x32_bf16 v[18:21], v[170:173], v[220:223], v[18:21]
	v_mfma_f32_16x16x32_bf16 v[46:49], v[174:177], v[190:193], v[46:49]
	v_mfma_f32_16x16x32_bf16 v[42:45], v[182:185], v[190:193], v[42:45]
	v_mfma_f32_16x16x32_bf16 v[30:33], v[174:177], v[200:203], v[30:33]
	v_mfma_f32_16x16x32_bf16 v[26:29], v[182:185], v[200:203], v[26:29]
	v_mfma_f32_16x16x32_bf16 v[14:17], v[174:177], v[208:211], v[14:17]
	v_mfma_f32_16x16x32_bf16 v[10:13], v[182:185], v[208:211], v[10:13]
	v_mfma_f32_16x16x32_bf16 v[6:9], v[174:177], v[216:219], v[6:9]
	v_mfma_f32_16x16x32_bf16 v[2:5], v[182:185], v[216:219], v[2:5]
	v_mfma_f32_16x16x32_bf16 v[46:49], v[178:181], v[196:199], v[46:49]
	v_mfma_f32_16x16x32_bf16 v[42:45], v[186:189], v[196:199], v[42:45]
	v_mfma_f32_16x16x32_bf16 v[30:33], v[178:181], v[204:207], v[30:33]
	v_mfma_f32_16x16x32_bf16 v[26:29], v[186:189], v[204:207], v[26:29]
	v_mfma_f32_16x16x32_bf16 v[14:17], v[178:181], v[212:215], v[14:17]
	v_mfma_f32_16x16x32_bf16 v[10:13], v[186:189], v[212:215], v[10:13]
	v_mfma_f32_16x16x32_bf16 v[6:9], v[178:181], v[220:223], v[6:9]
	v_mfma_f32_16x16x32_bf16 v[2:5], v[186:189], v[220:223], v[2:5]
	s_setprio 0
	s_barrier
	s_add_i32 s58, s58, 2
	s_add_u32 s26, s26, 0x100
	s_addc_u32 s27, s27, 0
	s_add_u32 s56, s56, 0x100
	s_addc_u32 s57, s57, 0
	s_cmp_gt_u32 s58, 61
	s_cbranch_scc0 .LBB0_657
	s_and_b64 vcc, exec, s[14:15]
	s_cbranch_vccz .LBB0_660
	s_barrier

.LBB0_681:
	ds_read_b128 v[152:155], v144
	ds_read_b128 v[156:159], v144 offset:1024
	ds_read_b128 v[160:163], v144 offset:2048
	ds_read_b128 v[164:167], v144 offset:3072
	ds_read_b128 v[168:171], v145
	ds_read_b128 v[172:175], v145 offset:1024
	ds_read_b128 v[176:179], v145 offset:2048
	ds_read_b128 v[180:183], v145 offset:3072
	s_add_u32 s42, s40, 0xfff00080
	s_addc_u32 s43, s41, -1
	s_cmp_eq_u32 s70, 60
	s_cselect_b32 s47, s27, s43
	s_cselect_b32 s46, s66, s42
	s_cselect_b32 s43, s25, s69
	s_cselect_b32 s42, s67, s68
	v_lshl_add_u64 v[192:193], s[40:41], 0, v[134:135]
	s_add_i32 m0, s29, 0xc000
	ds_read_b128 v[184:187], v150
	ds_read_b128 v[188:191], v150 offset:1024
	ds_read_b128 v[196:199], v150 offset:2048
	ds_read_b128 v[200:203], v150 offset:3072
	ds_read_b128 v[204:207], v150 offset:4096
	ds_read_b128 v[208:211], v150 offset:5120
	ds_read_b128 v[212:215], v150 offset:6144
	ds_read_b128 v[216:219], v150 offset:7168
	global_load_lds_dwordx4 v[192:193], off
	v_lshl_add_u64 v[192:193], s[40:41], 0, v[136:137]
	s_add_i32 m0, s29, 0xe000
	s_nop 0
	global_load_lds_dwordx4 v[192:193], off
	s_nop 0
	s_waitcnt vmcnt(8)
	s_waitcnt lgkmcnt(0)
	s_setprio 1
	s_barrier
	v_mfma_f32_16x16x32_bf16 v[126:129], v[152:155], v[184:187], v[126:129]
	v_mfma_f32_16x16x32_bf16 v[122:125], v[160:163], v[184:187], v[122:125]
	v_mfma_f32_16x16x32_bf16 v[118:121], v[152:155], v[196:199], v[118:121]
	v_mfma_f32_16x16x32_bf16 v[110:113], v[160:163], v[196:199], v[110:113]
	v_mfma_f32_16x16x32_bf16 v[102:105], v[152:155], v[204:207], v[102:105]
	v_mfma_f32_16x16x32_bf16 v[94:97], v[160:163], v[204:207], v[94:97]
	v_mfma_f32_16x16x32_bf16 v[86:89], v[152:155], v[212:215], v[86:89]
	v_mfma_f32_16x16x32_bf16 v[78:81], v[160:163], v[212:215], v[78:81]
	v_mfma_f32_16x16x32_bf16 v[126:129], v[156:159], v[188:191], v[126:129]
	v_mfma_f32_16x16x32_bf16 v[122:125], v[164:167], v[188:191], v[122:125]
	v_mfma_f32_16x16x32_bf16 v[118:121], v[156:159], v[200:203], v[118:121]
	v_mfma_f32_16x16x32_bf16 v[110:113], v[164:167], v[200:203], v[110:113]
	v_mfma_f32_16x16x32_bf16 v[102:105], v[156:159], v[208:211], v[102:105]
	v_mfma_f32_16x16x32_bf16 v[94:97], v[164:167], v[208:211], v[94:97]
	v_mfma_f32_16x16x32_bf16 v[86:89], v[156:159], v[216:219], v[86:89]
	v_mfma_f32_16x16x32_bf16 v[78:81], v[164:167], v[216:219], v[78:81]
	v_mfma_f32_16x16x32_bf16 v[114:117], v[168:171], v[184:187], v[114:117]
	v_mfma_f32_16x16x32_bf16 v[106:109], v[176:179], v[184:187], v[106:109]
	v_mfma_f32_16x16x32_bf16 v[98:101], v[168:171], v[196:199], v[98:101]
	v_mfma_f32_16x16x32_bf16 v[90:93], v[176:179], v[196:199], v[90:93]
	v_mfma_f32_16x16x32_bf16 v[82:85], v[168:171], v[204:207], v[82:85]
	v_mfma_f32_16x16x32_bf16 v[74:77], v[176:179], v[204:207], v[74:77]
	v_mfma_f32_16x16x32_bf16 v[70:73], v[168:171], v[212:215], v[70:73]
	v_mfma_f32_16x16x32_bf16 v[66:69], v[176:179], v[212:215], v[66:69]
	v_mfma_f32_16x16x32_bf16 v[114:117], v[172:175], v[188:191], v[114:117]
	v_mfma_f32_16x16x32_bf16 v[106:109], v[180:183], v[188:191], v[106:109]
	v_mfma_f32_16x16x32_bf16 v[98:101], v[172:175], v[200:203], v[98:101]
	v_mfma_f32_16x16x32_bf16 v[90:93], v[180:183], v[200:203], v[90:93]
	v_mfma_f32_16x16x32_bf16 v[82:85], v[172:175], v[208:211], v[82:85]
	v_mfma_f32_16x16x32_bf16 v[74:77], v[180:183], v[208:211], v[74:77]
	v_mfma_f32_16x16x32_bf16 v[70:73], v[172:175], v[216:219], v[70:73]
	v_mfma_f32_16x16x32_bf16 v[66:69], v[180:183], v[216:219], v[66:69]
	s_setprio 0
	s_barrier
	s_add_i32 s71, s62, s54
	v_lshl_add_u64 v[192:193], s[42:43], 0, v[130:131]
	s_mov_b32 m0, s71
	ds_read_b128 v[184:187], v150 offset:16384
	ds_read_b128 v[188:191], v150 offset:17408
	ds_read_b128 v[196:199], v150 offset:18432
	ds_read_b128 v[200:203], v150 offset:19456
	ds_read_b128 v[204:207], v150 offset:20480
	ds_read_b128 v[208:211], v150 offset:21504
	ds_read_b128 v[212:215], v150 offset:22528
	ds_read_b128 v[216:219], v150 offset:23552
	global_load_lds_dwordx4 v[192:193], off
	s_add_i32 m0, s71, 0x2000
	s_add_u32 s72, s42, 0x100000
	v_lshl_add_u64 v[220:221], s[42:43], 0, v[132:133]
	s_addc_u32 s73, s43, 0
	s_add_i32 s71, s63, s54
	global_load_lds_dwordx4 v[220:221], off
	v_lshl_add_u64 v[222:223], s[72:73], 0, v[130:131]
	s_mov_b32 m0, s71
	v_lshl_add_u64 v[224:225], s[46:47], 0, v[132:133]
	global_load_lds_dwordx4 v[222:223], off
	v_lshl_add_u64 v[222:223], s[72:73], 0, v[132:133]
	s_add_i32 m0, s71, 0x2000
	s_nop 0
	global_load_lds_dwordx4 v[222:223], off
	v_lshl_add_u64 v[222:223], s[46:47], 0, v[130:131]
	s_mov_b32 m0, s29
	s_nop 0
	global_load_lds_dwordx4 v[222:223], off
	s_mov_b32 m0, s55
	s_nop 0
	global_load_lds_dwordx4 v[224:225], off
	s_waitcnt vmcnt(8)
	s_waitcnt lgkmcnt(0)
	s_setprio 1
	s_barrier
	v_mfma_f32_16x16x32_bf16 v[62:65], v[152:155], v[184:187], v[62:65]
	v_mfma_f32_16x16x32_bf16 v[58:61], v[160:163], v[184:187], v[58:61]
	v_mfma_f32_16x16x32_bf16 v[54:57], v[152:155], v[196:199], v[54:57]
	v_mfma_f32_16x16x32_bf16 v[46:49], v[160:163], v[196:199], v[46:49]
	v_mfma_f32_16x16x32_bf16 v[38:41], v[152:155], v[204:207], v[38:41]
	v_mfma_f32_16x16x32_bf16 v[30:33], v[160:163], v[204:207], v[30:33]
	v_mfma_f32_16x16x32_bf16 v[22:25], v[152:155], v[212:215], v[22:25]
	v_mfma_f32_16x16x32_bf16 v[14:17], v[160:163], v[212:215], v[14:17]
	v_mfma_f32_16x16x32_bf16 v[62:65], v[156:159], v[188:191], v[62:65]
	v_mfma_f32_16x16x32_bf16 v[58:61], v[164:167], v[188:191], v[58:61]
	v_mfma_f32_16x16x32_bf16 v[54:57], v[156:159], v[200:203], v[54:57]
	v_mfma_f32_16x16x32_bf16 v[46:49], v[164:167], v[200:203], v[46:49]
	v_mfma_f32_16x16x32_bf16 v[38:41], v[156:159], v[208:211], v[38:41]
	v_mfma_f32_16x16x32_bf16 v[30:33], v[164:167], v[208:211], v[30:33]
	v_mfma_f32_16x16x32_bf16 v[22:25], v[156:159], v[216:219], v[22:25]
	v_mfma_f32_16x16x32_bf16 v[14:17], v[164:167], v[216:219], v[14:17]
	v_mfma_f32_16x16x32_bf16 v[50:53], v[168:171], v[184:187], v[50:53]
	v_mfma_f32_16x16x32_bf16 v[42:45], v[176:179], v[184:187], v[42:45]
	v_mfma_f32_16x16x32_bf16 v[34:37], v[168:171], v[196:199], v[34:37]
	v_mfma_f32_16x16x32_bf16 v[26:29], v[176:179], v[196:199], v[26:29]
	v_mfma_f32_16x16x32_bf16 v[18:21], v[168:171], v[204:207], v[18:21]
	v_mfma_f32_16x16x32_bf16 v[10:13], v[176:179], v[204:207], v[10:13]
	v_mfma_f32_16x16x32_bf16 v[6:9], v[168:171], v[212:215], v[6:9]
	v_mfma_f32_16x16x32_bf16 v[2:5], v[176:179], v[212:215], v[2:5]
	v_mfma_f32_16x16x32_bf16 v[50:53], v[172:175], v[188:191], v[50:53]
	v_mfma_f32_16x16x32_bf16 v[42:45], v[180:183], v[188:191], v[42:45]
	v_mfma_f32_16x16x32_bf16 v[34:37], v[172:175], v[200:203], v[34:37]
	v_mfma_f32_16x16x32_bf16 v[26:29], v[180:183], v[200:203], v[26:29]
	v_mfma_f32_16x16x32_bf16 v[18:21], v[172:175], v[208:211], v[18:21]
	v_mfma_f32_16x16x32_bf16 v[10:13], v[180:183], v[208:211], v[10:13]
	v_mfma_f32_16x16x32_bf16 v[6:9], v[172:175], v[216:219], v[6:9]
	v_mfma_f32_16x16x32_bf16 v[2:5], v[180:183], v[216:219], v[2:5]
	s_setprio 0
	s_barrier
	s_add_i32 s71, 0, 0x18000
	v_add_u32_e32 v151, s71, v142
	s_add_i32 s72, 0, 0x1c000
	ds_read_b128 v[152:155], v151
	ds_read_b128 v[156:159], v151 offset:1024
	ds_read_b128 v[160:163], v151 offset:2048
	ds_read_b128 v[164:167], v151 offset:3072
	v_add_u32_e32 v151, s72, v142
	ds_read_b128 v[168:171], v151
	ds_read_b128 v[172:175], v151 offset:1024
	ds_read_b128 v[176:179], v151 offset:2048
	ds_read_b128 v[180:183], v151 offset:3072
	s_add_u32 s46, s46, 0x100000
	s_addc_u32 s47, s47, 0
	s_mov_b32 m0, s56
	v_lshl_add_u64 v[226:227], s[46:47], 0, v[130:131]
	ds_read_b128 v[184:187], v150 offset:32768
	ds_read_b128 v[188:191], v150 offset:33792
	ds_read_b128 v[196:199], v150 offset:34816
	ds_read_b128 v[200:203], v150 offset:35840
	ds_read_b128 v[204:207], v150 offset:36864
	ds_read_b128 v[208:211], v150 offset:37888
	ds_read_b128 v[212:215], v150 offset:38912
	ds_read_b128 v[216:219], v150 offset:39936
	global_load_lds_dwordx4 v[226:227], off
	v_lshl_add_u64 v[226:227], s[46:47], 0, v[132:133]
	s_mov_b32 m0, s57
	s_nop 0
	global_load_lds_dwordx4 v[226:227], off
	s_waitcnt vmcnt(8)
	s_waitcnt lgkmcnt(0)
	s_setprio 1
	s_barrier
	v_mfma_f32_16x16x32_bf16 v[126:129], v[152:155], v[184:187], v[126:129]
	v_mfma_f32_16x16x32_bf16 v[122:125], v[160:163], v[184:187], v[122:125]
	v_mfma_f32_16x16x32_bf16 v[118:121], v[152:155], v[196:199], v[118:121]
	v_mfma_f32_16x16x32_bf16 v[110:113], v[160:163], v[196:199], v[110:113]
	v_mfma_f32_16x16x32_bf16 v[102:105], v[152:155], v[204:207], v[102:105]
	v_mfma_f32_16x16x32_bf16 v[94:97], v[160:163], v[204:207], v[94:97]
	v_mfma_f32_16x16x32_bf16 v[86:89], v[152:155], v[212:215], v[86:89]
	v_mfma_f32_16x16x32_bf16 v[78:81], v[160:163], v[212:215], v[78:81]
	v_mfma_f32_16x16x32_bf16 v[126:129], v[156:159], v[188:191], v[126:129]
	v_mfma_f32_16x16x32_bf16 v[122:125], v[164:167], v[188:191], v[122:125]
	v_mfma_f32_16x16x32_bf16 v[118:121], v[156:159], v[200:203], v[118:121]
	v_mfma_f32_16x16x32_bf16 v[110:113], v[164:167], v[200:203], v[110:113]
	v_mfma_f32_16x16x32_bf16 v[102:105], v[156:159], v[208:211], v[102:105]
	v_mfma_f32_16x16x32_bf16 v[94:97], v[164:167], v[208:211], v[94:97]
	v_mfma_f32_16x16x32_bf16 v[86:89], v[156:159], v[216:219], v[86:89]
	v_mfma_f32_16x16x32_bf16 v[78:81], v[164:167], v[216:219], v[78:81]
	v_mfma_f32_16x16x32_bf16 v[114:117], v[168:171], v[184:187], v[114:117]
	v_mfma_f32_16x16x32_bf16 v[106:109], v[176:179], v[184:187], v[106:109]
	v_mfma_f32_16x16x32_bf16 v[98:101], v[168:171], v[196:199], v[98:101]
	v_mfma_f32_16x16x32_bf16 v[90:93], v[176:179], v[196:199], v[90:93]
	v_mfma_f32_16x16x32_bf16 v[82:85], v[168:171], v[204:207], v[82:85]
	v_mfma_f32_16x16x32_bf16 v[74:77], v[176:179], v[204:207], v[74:77]
	v_mfma_f32_16x16x32_bf16 v[70:73], v[168:171], v[212:215], v[70:73]
	v_mfma_f32_16x16x32_bf16 v[66:69], v[176:179], v[212:215], v[66:69]
	v_mfma_f32_16x16x32_bf16 v[114:117], v[172:175], v[188:191], v[114:117]
	v_mfma_f32_16x16x32_bf16 v[106:109], v[180:183], v[188:191], v[106:109]
	v_mfma_f32_16x16x32_bf16 v[98:101], v[172:175], v[200:203], v[98:101]
	v_mfma_f32_16x16x32_bf16 v[90:93], v[180:183], v[200:203], v[90:93]
	v_mfma_f32_16x16x32_bf16 v[82:85], v[172:175], v[208:211], v[82:85]
	v_mfma_f32_16x16x32_bf16 v[74:77], v[180:183], v[208:211], v[74:77]
	v_mfma_f32_16x16x32_bf16 v[70:73], v[172:175], v[216:219], v[70:73]
	v_mfma_f32_16x16x32_bf16 v[66:69], v[180:183], v[216:219], v[66:69]
	s_setprio 0
	s_barrier
	s_add_i32 s46, s71, s54
	v_lshl_add_u64 v[192:193], v[192:193], 0, s[10:11]
	s_mov_b32 m0, s46
	ds_read_b128 v[184:187], v150 offset:49152
	ds_read_b128 v[188:191], v150 offset:50176
	ds_read_b128 v[196:199], v150 offset:51200
	ds_read_b128 v[200:203], v150 offset:52224
	ds_read_b128 v[204:207], v150 offset:53248
	ds_read_b128 v[208:211], v150 offset:54272
	ds_read_b128 v[212:215], v150 offset:55296
	ds_read_b128 v[216:219], v150 offset:56320
	global_load_lds_dwordx4 v[192:193], off
	s_add_i32 m0, s46, 0x2000
	s_add_u32 s42, s42, 0x100080
	v_lshl_add_u64 v[192:193], v[220:221], 0, s[10:11]
	s_addc_u32 s43, s43, 0
	s_add_i32 s46, s72, s54
	global_load_lds_dwordx4 v[192:193], off
	v_lshl_add_u64 v[192:193], s[42:43], 0, v[130:131]
	s_mov_b32 m0, s46
	s_nop 0
	global_load_lds_dwordx4 v[192:193], off
	v_lshl_add_u64 v[192:193], s[42:43], 0, v[132:133]
	s_add_i32 m0, s46, 0x2000
	s_nop 0
	global_load_lds_dwordx4 v[192:193], off
	v_lshl_add_u64 v[192:193], v[222:223], 0, s[10:11]
	s_mov_b32 m0, s59
	s_nop 0
	global_load_lds_dwordx4 v[192:193], off
	v_lshl_add_u64 v[192:193], v[224:225], 0, s[10:11]
	s_mov_b32 m0, s60
	s_nop 0
	global_load_lds_dwordx4 v[192:193], off
	s_nop 0
	s_waitcnt vmcnt(8)
	s_waitcnt lgkmcnt(0)
	s_setprio 1
	s_barrier
	v_mfma_f32_16x16x32_bf16 v[62:65], v[152:155], v[184:187], v[62:65]
	v_mfma_f32_16x16x32_bf16 v[58:61], v[160:163], v[184:187], v[58:61]
	v_mfma_f32_16x16x32_bf16 v[54:57], v[152:155], v[196:199], v[54:57]
	v_mfma_f32_16x16x32_bf16 v[46:49], v[160:163], v[196:199], v[46:49]
	v_mfma_f32_16x16x32_bf16 v[38:41], v[152:155], v[204:207], v[38:41]
	v_mfma_f32_16x16x32_bf16 v[30:33], v[160:163], v[204:207], v[30:33]
	v_mfma_f32_16x16x32_bf16 v[22:25], v[152:155], v[212:215], v[22:25]
	v_mfma_f32_16x16x32_bf16 v[14:17], v[160:163], v[212:215], v[14:17]
	v_mfma_f32_16x16x32_bf16 v[62:65], v[156:159], v[188:191], v[62:65]
	v_mfma_f32_16x16x32_bf16 v[58:61], v[164:167], v[188:191], v[58:61]
	v_mfma_f32_16x16x32_bf16 v[54:57], v[156:159], v[200:203], v[54:57]
	v_mfma_f32_16x16x32_bf16 v[46:49], v[164:167], v[200:203], v[46:49]
	v_mfma_f32_16x16x32_bf16 v[38:41], v[156:159], v[208:211], v[38:41]
	v_mfma_f32_16x16x32_bf16 v[30:33], v[164:167], v[208:211], v[30:33]
	v_mfma_f32_16x16x32_bf16 v[22:25], v[156:159], v[216:219], v[22:25]
	v_mfma_f32_16x16x32_bf16 v[14:17], v[164:167], v[216:219], v[14:17]
	v_mfma_f32_16x16x32_bf16 v[50:53], v[168:171], v[184:187], v[50:53]
	v_mfma_f32_16x16x32_bf16 v[42:45], v[176:179], v[184:187], v[42:45]
	v_mfma_f32_16x16x32_bf16 v[34:37], v[168:171], v[196:199], v[34:37]
	v_mfma_f32_16x16x32_bf16 v[26:29], v[176:179], v[196:199], v[26:29]
	v_mfma_f32_16x16x32_bf16 v[18:21], v[168:171], v[204:207], v[18:21]
	v_mfma_f32_16x16x32_bf16 v[10:13], v[176:179], v[204:207], v[10:13]
	v_mfma_f32_16x16x32_bf16 v[6:9], v[168:171], v[212:215], v[6:9]
	v_mfma_f32_16x16x32_bf16 v[2:5], v[176:179], v[212:215], v[2:5]
	v_mfma_f32_16x16x32_bf16 v[50:53], v[172:175], v[188:191], v[50:53]
	v_mfma_f32_16x16x32_bf16 v[42:45], v[180:183], v[188:191], v[42:45]
	v_mfma_f32_16x16x32_bf16 v[34:37], v[172:175], v[200:203], v[34:37]
	v_mfma_f32_16x16x32_bf16 v[26:29], v[180:183], v[200:203], v[26:29]
	v_mfma_f32_16x16x32_bf16 v[18:21], v[172:175], v[208:211], v[18:21]
	v_mfma_f32_16x16x32_bf16 v[10:13], v[180:183], v[208:211], v[10:13]
	v_mfma_f32_16x16x32_bf16 v[6:9], v[172:175], v[216:219], v[6:9]
	v_mfma_f32_16x16x32_bf16 v[2:5], v[180:183], v[216:219], v[2:5]
	s_setprio 0
	s_barrier
	s_add_i32 s70, s70, 2
	s_add_u32 s40, s40, 0x100
	s_addc_u32 s41, s41, 0
	s_add_u32 s68, s68, 0x100
	s_addc_u32 s69, s69, 0
	s_cmp_gt_u32 s70, 61
	s_cbranch_scc0 .LBB0_681
	s_and_b64 vcc, exec, s[12:13]
	s_cbranch_vccz .LBB0_684
	s_barrier

.LBB0_705:
	ds_read_b128 v[144:147], v139
	ds_read_b128 v[148:151], v139 offset:1024
	ds_read_b128 v[152:155], v139 offset:2048
	ds_read_b128 v[156:159], v139 offset:3072
	ds_read_b128 v[160:163], v140
	ds_read_b128 v[164:167], v140 offset:1024
	ds_read_b128 v[168:171], v140 offset:2048
	ds_read_b128 v[172:175], v140 offset:3072
	s_add_u32 s42, s40, 0xfff00080
	s_addc_u32 s43, s41, -1
	s_cmp_eq_u32 s67, 60
	s_cselect_b32 s47, s27, s43
	s_cselect_b32 s46, s63, s42
	s_cselect_b32 s43, s25, s66
	s_cselect_b32 s42, s64, s65
	v_lshl_add_u64 v[192:193], s[40:41], 0, v[134:135]
	s_add_i32 m0, s29, 0xc000
	ds_read_b128 v[176:179], v142
	ds_read_b128 v[180:183], v142 offset:1024
	ds_read_b128 v[184:187], v142 offset:2048
	ds_read_b128 v[188:191], v142 offset:3072
	ds_read_b128 v[196:199], v142 offset:4096
	ds_read_b128 v[200:203], v142 offset:5120
	ds_read_b128 v[204:207], v142 offset:6144
	ds_read_b128 v[208:211], v142 offset:7168
	global_load_lds_dwordx4 v[192:193], off
	v_lshl_add_u64 v[192:193], s[40:41], 0, v[136:137]
	s_add_i32 m0, s29, 0xe000
	s_nop 0
	global_load_lds_dwordx4 v[192:193], off
	s_nop 0
	s_waitcnt vmcnt(8)
	s_waitcnt lgkmcnt(0)
	s_setprio 1
	s_barrier
	v_mfma_f32_16x16x32_bf16 v[126:129], v[144:147], v[176:179], v[126:129]
	v_mfma_f32_16x16x32_bf16 v[122:125], v[152:155], v[176:179], v[122:125]
	v_mfma_f32_16x16x32_bf16 v[118:121], v[144:147], v[184:187], v[118:121]
	v_mfma_f32_16x16x32_bf16 v[110:113], v[152:155], v[184:187], v[110:113]
	v_mfma_f32_16x16x32_bf16 v[102:105], v[144:147], v[196:199], v[102:105]
	v_mfma_f32_16x16x32_bf16 v[94:97], v[152:155], v[196:199], v[94:97]
	v_mfma_f32_16x16x32_bf16 v[86:89], v[144:147], v[204:207], v[86:89]
	v_mfma_f32_16x16x32_bf16 v[78:81], v[152:155], v[204:207], v[78:81]
	v_mfma_f32_16x16x32_bf16 v[126:129], v[148:151], v[180:183], v[126:129]
	v_mfma_f32_16x16x32_bf16 v[122:125], v[156:159], v[180:183], v[122:125]
	v_mfma_f32_16x16x32_bf16 v[118:121], v[148:151], v[188:191], v[118:121]
	v_mfma_f32_16x16x32_bf16 v[110:113], v[156:159], v[188:191], v[110:113]
	v_mfma_f32_16x16x32_bf16 v[102:105], v[148:151], v[200:203], v[102:105]
	v_mfma_f32_16x16x32_bf16 v[94:97], v[156:159], v[200:203], v[94:97]
	v_mfma_f32_16x16x32_bf16 v[86:89], v[148:151], v[208:211], v[86:89]
	v_mfma_f32_16x16x32_bf16 v[78:81], v[156:159], v[208:211], v[78:81]
	v_mfma_f32_16x16x32_bf16 v[114:117], v[160:163], v[176:179], v[114:117]
	v_mfma_f32_16x16x32_bf16 v[106:109], v[168:171], v[176:179], v[106:109]
	v_mfma_f32_16x16x32_bf16 v[98:101], v[160:163], v[184:187], v[98:101]
	v_mfma_f32_16x16x32_bf16 v[90:93], v[168:171], v[184:187], v[90:93]
	v_mfma_f32_16x16x32_bf16 v[82:85], v[160:163], v[196:199], v[82:85]
	v_mfma_f32_16x16x32_bf16 v[74:77], v[168:171], v[196:199], v[74:77]
	v_mfma_f32_16x16x32_bf16 v[70:73], v[160:163], v[204:207], v[70:73]
	v_mfma_f32_16x16x32_bf16 v[66:69], v[168:171], v[204:207], v[66:69]
	v_mfma_f32_16x16x32_bf16 v[114:117], v[164:167], v[180:183], v[114:117]
	v_mfma_f32_16x16x32_bf16 v[106:109], v[172:175], v[180:183], v[106:109]
	v_mfma_f32_16x16x32_bf16 v[98:101], v[164:167], v[188:191], v[98:101]
	v_mfma_f32_16x16x32_bf16 v[90:93], v[172:175], v[188:191], v[90:93]
	v_mfma_f32_16x16x32_bf16 v[82:85], v[164:167], v[200:203], v[82:85]
	v_mfma_f32_16x16x32_bf16 v[74:77], v[172:175], v[200:203], v[74:77]
	v_mfma_f32_16x16x32_bf16 v[70:73], v[164:167], v[208:211], v[70:73]
	v_mfma_f32_16x16x32_bf16 v[66:69], v[172:175], v[208:211], v[66:69]
	s_setprio 0
	s_barrier
	s_add_i32 s68, s59, s51
	v_lshl_add_u64 v[192:193], s[42:43], 0, v[130:131]
	s_mov_b32 m0, s68
	ds_read_b128 v[176:179], v142 offset:16384
	ds_read_b128 v[180:183], v142 offset:17408
	ds_read_b128 v[184:187], v142 offset:18432
	ds_read_b128 v[188:191], v142 offset:19456
	ds_read_b128 v[196:199], v142 offset:20480
	ds_read_b128 v[200:203], v142 offset:21504
	ds_read_b128 v[204:207], v142 offset:22528
	ds_read_b128 v[208:211], v142 offset:23552
	global_load_lds_dwordx4 v[192:193], off
	s_add_i32 m0, s68, 0x2000
	s_add_u32 s68, s42, 0x100000
	v_lshl_add_u64 v[212:213], s[42:43], 0, v[132:133]
	s_addc_u32 s69, s43, 0
	s_add_i32 s70, s60, s51
	global_load_lds_dwordx4 v[212:213], off
	v_lshl_add_u64 v[214:215], s[68:69], 0, v[130:131]
	s_mov_b32 m0, s70
	v_lshl_add_u64 v[216:217], s[46:47], 0, v[132:133]
	global_load_lds_dwordx4 v[214:215], off
	v_lshl_add_u64 v[214:215], s[68:69], 0, v[132:133]
	s_add_i32 m0, s70, 0x2000
	s_nop 0
	global_load_lds_dwordx4 v[214:215], off
	v_lshl_add_u64 v[214:215], s[46:47], 0, v[130:131]
	s_mov_b32 m0, s29
	s_nop 0
	global_load_lds_dwordx4 v[214:215], off
	s_mov_b32 m0, s52
	s_nop 0
	global_load_lds_dwordx4 v[216:217], off
	s_waitcnt vmcnt(8)
	s_waitcnt lgkmcnt(0)
	s_setprio 1
	s_barrier
	v_mfma_f32_16x16x32_bf16 v[62:65], v[144:147], v[176:179], v[62:65]
	v_mfma_f32_16x16x32_bf16 v[58:61], v[152:155], v[176:179], v[58:61]
	v_mfma_f32_16x16x32_bf16 v[54:57], v[144:147], v[184:187], v[54:57]
	v_mfma_f32_16x16x32_bf16 v[46:49], v[152:155], v[184:187], v[46:49]
	v_mfma_f32_16x16x32_bf16 v[38:41], v[144:147], v[196:199], v[38:41]
	v_mfma_f32_16x16x32_bf16 v[30:33], v[152:155], v[196:199], v[30:33]
	v_mfma_f32_16x16x32_bf16 v[22:25], v[144:147], v[204:207], v[22:25]
	v_mfma_f32_16x16x32_bf16 v[14:17], v[152:155], v[204:207], v[14:17]
	v_mfma_f32_16x16x32_bf16 v[62:65], v[148:151], v[180:183], v[62:65]
	v_mfma_f32_16x16x32_bf16 v[58:61], v[156:159], v[180:183], v[58:61]
	v_mfma_f32_16x16x32_bf16 v[54:57], v[148:151], v[188:191], v[54:57]
	v_mfma_f32_16x16x32_bf16 v[46:49], v[156:159], v[188:191], v[46:49]
	v_mfma_f32_16x16x32_bf16 v[38:41], v[148:151], v[200:203], v[38:41]
	v_mfma_f32_16x16x32_bf16 v[30:33], v[156:159], v[200:203], v[30:33]
	v_mfma_f32_16x16x32_bf16 v[22:25], v[148:151], v[208:211], v[22:25]
	v_mfma_f32_16x16x32_bf16 v[14:17], v[156:159], v[208:211], v[14:17]
	v_mfma_f32_16x16x32_bf16 v[50:53], v[160:163], v[176:179], v[50:53]
	v_mfma_f32_16x16x32_bf16 v[42:45], v[168:171], v[176:179], v[42:45]
	v_mfma_f32_16x16x32_bf16 v[34:37], v[160:163], v[184:187], v[34:37]
	v_mfma_f32_16x16x32_bf16 v[26:29], v[168:171], v[184:187], v[26:29]
	v_mfma_f32_16x16x32_bf16 v[18:21], v[160:163], v[196:199], v[18:21]
	v_mfma_f32_16x16x32_bf16 v[10:13], v[168:171], v[196:199], v[10:13]
	v_mfma_f32_16x16x32_bf16 v[6:9], v[160:163], v[204:207], v[6:9]
	v_mfma_f32_16x16x32_bf16 v[2:5], v[168:171], v[204:207], v[2:5]
	v_mfma_f32_16x16x32_bf16 v[50:53], v[164:167], v[180:183], v[50:53]
	v_mfma_f32_16x16x32_bf16 v[42:45], v[172:175], v[180:183], v[42:45]
	v_mfma_f32_16x16x32_bf16 v[34:37], v[164:167], v[188:191], v[34:37]
	v_mfma_f32_16x16x32_bf16 v[26:29], v[172:175], v[188:191], v[26:29]
	v_mfma_f32_16x16x32_bf16 v[18:21], v[164:167], v[200:203], v[18:21]
	v_mfma_f32_16x16x32_bf16 v[10:13], v[172:175], v[200:203], v[10:13]
	v_mfma_f32_16x16x32_bf16 v[6:9], v[164:167], v[208:211], v[6:9]
	v_mfma_f32_16x16x32_bf16 v[2:5], v[172:175], v[208:211], v[2:5]
	s_setprio 0
	s_barrier
	s_add_i32 s68, 0, 0x18000
	v_add_u32_e32 v143, s68, v1
	s_add_i32 s69, 0, 0x1c000
	ds_read_b128 v[144:147], v143
	ds_read_b128 v[148:151], v143 offset:1024
	ds_read_b128 v[152:155], v143 offset:2048
	ds_read_b128 v[156:159], v143 offset:3072
	v_add_u32_e32 v143, s69, v1
	ds_read_b128 v[160:163], v143
	ds_read_b128 v[164:167], v143 offset:1024
	ds_read_b128 v[168:171], v143 offset:2048
	ds_read_b128 v[172:175], v143 offset:3072
	s_add_u32 s46, s46, 0x100000
	s_addc_u32 s47, s47, 0
	s_mov_b32 m0, s53
	v_lshl_add_u64 v[218:219], s[46:47], 0, v[130:131]
	ds_read_b128 v[176:179], v142 offset:32768
	ds_read_b128 v[180:183], v142 offset:33792
	ds_read_b128 v[184:187], v142 offset:34816
	ds_read_b128 v[188:191], v142 offset:35840
	ds_read_b128 v[196:199], v142 offset:36864
	ds_read_b128 v[200:203], v142 offset:37888
	ds_read_b128 v[204:207], v142 offset:38912
	ds_read_b128 v[208:211], v142 offset:39936
	global_load_lds_dwordx4 v[218:219], off
	v_lshl_add_u64 v[218:219], s[46:47], 0, v[132:133]
	s_mov_b32 m0, s54
	s_nop 0
	global_load_lds_dwordx4 v[218:219], off
	s_waitcnt vmcnt(8)
	s_waitcnt lgkmcnt(0)
	s_setprio 1
	s_barrier
	v_mfma_f32_16x16x32_bf16 v[126:129], v[144:147], v[176:179], v[126:129]
	v_mfma_f32_16x16x32_bf16 v[122:125], v[152:155], v[176:179], v[122:125]
	v_mfma_f32_16x16x32_bf16 v[118:121], v[144:147], v[184:187], v[118:121]
	v_mfma_f32_16x16x32_bf16 v[110:113], v[152:155], v[184:187], v[110:113]
	v_mfma_f32_16x16x32_bf16 v[102:105], v[144:147], v[196:199], v[102:105]
	v_mfma_f32_16x16x32_bf16 v[94:97], v[152:155], v[196:199], v[94:97]
	v_mfma_f32_16x16x32_bf16 v[86:89], v[144:147], v[204:207], v[86:89]
	v_mfma_f32_16x16x32_bf16 v[78:81], v[152:155], v[204:207], v[78:81]
	v_mfma_f32_16x16x32_bf16 v[126:129], v[148:151], v[180:183], v[126:129]
	v_mfma_f32_16x16x32_bf16 v[122:125], v[156:159], v[180:183], v[122:125]
	v_mfma_f32_16x16x32_bf16 v[118:121], v[148:151], v[188:191], v[118:121]
	v_mfma_f32_16x16x32_bf16 v[110:113], v[156:159], v[188:191], v[110:113]
	v_mfma_f32_16x16x32_bf16 v[102:105], v[148:151], v[200:203], v[102:105]
	v_mfma_f32_16x16x32_bf16 v[94:97], v[156:159], v[200:203], v[94:97]
	v_mfma_f32_16x16x32_bf16 v[86:89], v[148:151], v[208:211], v[86:89]
	v_mfma_f32_16x16x32_bf16 v[78:81], v[156:159], v[208:211], v[78:81]
	v_mfma_f32_16x16x32_bf16 v[114:117], v[160:163], v[176:179], v[114:117]
	v_mfma_f32_16x16x32_bf16 v[106:109], v[168:171], v[176:179], v[106:109]
	v_mfma_f32_16x16x32_bf16 v[98:101], v[160:163], v[184:187], v[98:101]
	v_mfma_f32_16x16x32_bf16 v[90:93], v[168:171], v[184:187], v[90:93]
	v_mfma_f32_16x16x32_bf16 v[82:85], v[160:163], v[196:199], v[82:85]
	v_mfma_f32_16x16x32_bf16 v[74:77], v[168:171], v[196:199], v[74:77]
	v_mfma_f32_16x16x32_bf16 v[70:73], v[160:163], v[204:207], v[70:73]
	v_mfma_f32_16x16x32_bf16 v[66:69], v[168:171], v[204:207], v[66:69]
	v_mfma_f32_16x16x32_bf16 v[114:117], v[164:167], v[180:183], v[114:117]
	v_mfma_f32_16x16x32_bf16 v[106:109], v[172:175], v[180:183], v[106:109]
	v_mfma_f32_16x16x32_bf16 v[98:101], v[164:167], v[188:191], v[98:101]
	v_mfma_f32_16x16x32_bf16 v[90:93], v[172:175], v[188:191], v[90:93]
	v_mfma_f32_16x16x32_bf16 v[82:85], v[164:167], v[200:203], v[82:85]
	v_mfma_f32_16x16x32_bf16 v[74:77], v[172:175], v[200:203], v[74:77]
	v_mfma_f32_16x16x32_bf16 v[70:73], v[164:167], v[208:211], v[70:73]
	v_mfma_f32_16x16x32_bf16 v[66:69], v[172:175], v[208:211], v[66:69]
	s_setprio 0
	s_barrier
	s_add_i32 s46, s68, s51
	v_lshl_add_u64 v[192:193], v[192:193], 0, s[10:11]
	s_mov_b32 m0, s46
	ds_read_b128 v[176:179], v142 offset:49152
	ds_read_b128 v[180:183], v142 offset:50176
	ds_read_b128 v[184:187], v142 offset:51200
	ds_read_b128 v[188:191], v142 offset:52224
	ds_read_b128 v[196:199], v142 offset:53248
	ds_read_b128 v[200:203], v142 offset:54272
	ds_read_b128 v[204:207], v142 offset:55296
	ds_read_b128 v[208:211], v142 offset:56320
	global_load_lds_dwordx4 v[192:193], off
	s_add_i32 m0, s46, 0x2000
	s_add_u32 s42, s42, 0x100080
	v_lshl_add_u64 v[192:193], v[212:213], 0, s[10:11]
	s_addc_u32 s43, s43, 0
	s_add_i32 s46, s69, s51
	global_load_lds_dwordx4 v[192:193], off
	v_lshl_add_u64 v[192:193], s[42:43], 0, v[130:131]
	s_mov_b32 m0, s46
	s_nop 0
	global_load_lds_dwordx4 v[192:193], off
	v_lshl_add_u64 v[192:193], s[42:43], 0, v[132:133]
	s_add_i32 m0, s46, 0x2000
	s_nop 0
	global_load_lds_dwordx4 v[192:193], off
	v_lshl_add_u64 v[192:193], v[214:215], 0, s[10:11]
	s_mov_b32 m0, s56
	s_nop 0
	global_load_lds_dwordx4 v[192:193], off
	v_lshl_add_u64 v[192:193], v[216:217], 0, s[10:11]
	s_mov_b32 m0, s57
	s_nop 0
	global_load_lds_dwordx4 v[192:193], off
	s_nop 0
	s_waitcnt vmcnt(8)
	s_waitcnt lgkmcnt(0)
	s_setprio 1
	s_barrier
	v_mfma_f32_16x16x32_bf16 v[62:65], v[144:147], v[176:179], v[62:65]
	v_mfma_f32_16x16x32_bf16 v[58:61], v[152:155], v[176:179], v[58:61]
	v_mfma_f32_16x16x32_bf16 v[54:57], v[144:147], v[184:187], v[54:57]
	v_mfma_f32_16x16x32_bf16 v[46:49], v[152:155], v[184:187], v[46:49]
	v_mfma_f32_16x16x32_bf16 v[38:41], v[144:147], v[196:199], v[38:41]
	v_mfma_f32_16x16x32_bf16 v[30:33], v[152:155], v[196:199], v[30:33]
	v_mfma_f32_16x16x32_bf16 v[22:25], v[144:147], v[204:207], v[22:25]
	v_mfma_f32_16x16x32_bf16 v[14:17], v[152:155], v[204:207], v[14:17]
	v_mfma_f32_16x16x32_bf16 v[62:65], v[148:151], v[180:183], v[62:65]
	v_mfma_f32_16x16x32_bf16 v[58:61], v[156:159], v[180:183], v[58:61]
	v_mfma_f32_16x16x32_bf16 v[54:57], v[148:151], v[188:191], v[54:57]
	v_mfma_f32_16x16x32_bf16 v[46:49], v[156:159], v[188:191], v[46:49]
	v_mfma_f32_16x16x32_bf16 v[38:41], v[148:151], v[200:203], v[38:41]
	v_mfma_f32_16x16x32_bf16 v[30:33], v[156:159], v[200:203], v[30:33]
	v_mfma_f32_16x16x32_bf16 v[22:25], v[148:151], v[208:211], v[22:25]
	v_mfma_f32_16x16x32_bf16 v[14:17], v[156:159], v[208:211], v[14:17]
	v_mfma_f32_16x16x32_bf16 v[50:53], v[160:163], v[176:179], v[50:53]
	v_mfma_f32_16x16x32_bf16 v[42:45], v[168:171], v[176:179], v[42:45]
	v_mfma_f32_16x16x32_bf16 v[34:37], v[160:163], v[184:187], v[34:37]
	v_mfma_f32_16x16x32_bf16 v[26:29], v[168:171], v[184:187], v[26:29]
	v_mfma_f32_16x16x32_bf16 v[18:21], v[160:163], v[196:199], v[18:21]
	v_mfma_f32_16x16x32_bf16 v[10:13], v[168:171], v[196:199], v[10:13]
	v_mfma_f32_16x16x32_bf16 v[6:9], v[160:163], v[204:207], v[6:9]
	v_mfma_f32_16x16x32_bf16 v[2:5], v[168:171], v[204:207], v[2:5]
	v_mfma_f32_16x16x32_bf16 v[50:53], v[164:167], v[180:183], v[50:53]
	v_mfma_f32_16x16x32_bf16 v[42:45], v[172:175], v[180:183], v[42:45]
	v_mfma_f32_16x16x32_bf16 v[34:37], v[164:167], v[188:191], v[34:37]
	v_mfma_f32_16x16x32_bf16 v[26:29], v[172:175], v[188:191], v[26:29]
	v_mfma_f32_16x16x32_bf16 v[18:21], v[164:167], v[200:203], v[18:21]
	v_mfma_f32_16x16x32_bf16 v[10:13], v[172:175], v[200:203], v[10:13]
	v_mfma_f32_16x16x32_bf16 v[6:9], v[164:167], v[208:211], v[6:9]
	v_mfma_f32_16x16x32_bf16 v[2:5], v[172:175], v[208:211], v[2:5]
	s_setprio 0
	s_barrier
	s_add_i32 s67, s67, 2
	s_add_u32 s40, s40, 0x100
	s_addc_u32 s41, s41, 0
	s_add_u32 s65, s65, 0x100
	s_addc_u32 s66, s66, 0
	s_cmp_gt_u32 s67, 61
	s_cbranch_scc0 .LBB0_705
	s_and_b64 vcc, exec, s[12:13]
	s_cbranch_vccz .LBB0_708
	s_barrier

.LBB0_967:
	ds_read_b128 v[146:149], v152
	ds_read_b128 v[156:159], v152 offset:1024
	ds_read_b128 v[160:163], v152 offset:2048
	ds_read_b128 v[164:167], v152 offset:3072
	ds_read_b128 v[168:171], v153
	ds_read_b128 v[172:175], v153 offset:1024
	ds_read_b128 v[176:179], v153 offset:2048
	ds_read_b128 v[180:183], v153 offset:3072
	s_add_u32 s30, s28, 0xfff80080
	s_addc_u32 s31, s29, -1
	s_cmp_eq_u32 s57, 28
	s_cselect_b32 s35, s21, s31
	s_cselect_b32 s34, s53, s30
	s_cselect_b32 s31, s19, s56
	s_cselect_b32 s30, s54, s55
	v_lshl_add_u64 v[192:193], s[28:29], 0, v[138:139]
	s_add_i32 m0, s27, 0xc000
	ds_read_b128 v[184:187], v154
	ds_read_b128 v[188:191], v154 offset:1024
	ds_read_b128 v[196:199], v154 offset:2048
	ds_read_b128 v[200:203], v154 offset:3072
	ds_read_b128 v[206:209], v154 offset:4096
	ds_read_b128 v[210:213], v154 offset:5120
	ds_read_b128 v[214:217], v154 offset:6144
	ds_read_b128 v[218:221], v154 offset:7168
	global_load_lds_dwordx4 v[192:193], off
	v_lshl_add_u64 v[192:193], s[28:29], 0, v[140:141]
	s_add_i32 m0, s27, 0xe000
	s_nop 0
	global_load_lds_dwordx4 v[192:193], off
	s_nop 0
	s_waitcnt vmcnt(8)
	s_waitcnt lgkmcnt(0)
	s_setprio 1
	s_barrier
	v_mfma_f32_16x16x32_bf16 v[126:129], v[146:149], v[184:187], v[126:129]
	v_mfma_f32_16x16x32_bf16 v[122:125], v[160:163], v[184:187], v[122:125]
	v_mfma_f32_16x16x32_bf16 v[110:113], v[146:149], v[196:199], v[110:113]
	v_mfma_f32_16x16x32_bf16 v[106:109], v[160:163], v[196:199], v[106:109]
	v_mfma_f32_16x16x32_bf16 v[98:101], v[146:149], v[206:209], v[98:101]
	v_mfma_f32_16x16x32_bf16 v[90:93], v[160:163], v[206:209], v[90:93]
	v_mfma_f32_16x16x32_bf16 v[78:81], v[146:149], v[214:217], v[78:81]
	v_mfma_f32_16x16x32_bf16 v[74:77], v[160:163], v[214:217], v[74:77]
	v_mfma_f32_16x16x32_bf16 v[126:129], v[156:159], v[188:191], v[126:129]
	v_mfma_f32_16x16x32_bf16 v[122:125], v[164:167], v[188:191], v[122:125]
	v_mfma_f32_16x16x32_bf16 v[110:113], v[156:159], v[200:203], v[110:113]
	v_mfma_f32_16x16x32_bf16 v[106:109], v[164:167], v[200:203], v[106:109]
	v_mfma_f32_16x16x32_bf16 v[98:101], v[156:159], v[210:213], v[98:101]
	v_mfma_f32_16x16x32_bf16 v[90:93], v[164:167], v[210:213], v[90:93]
	v_mfma_f32_16x16x32_bf16 v[78:81], v[156:159], v[218:221], v[78:81]
	v_mfma_f32_16x16x32_bf16 v[74:77], v[164:167], v[218:221], v[74:77]
	v_mfma_f32_16x16x32_bf16 v[118:121], v[168:171], v[184:187], v[118:121]
	v_mfma_f32_16x16x32_bf16 v[114:117], v[176:179], v[184:187], v[114:117]
	v_mfma_f32_16x16x32_bf16 v[102:105], v[168:171], v[196:199], v[102:105]
	v_mfma_f32_16x16x32_bf16 v[94:97], v[176:179], v[196:199], v[94:97]
	v_mfma_f32_16x16x32_bf16 v[86:89], v[168:171], v[206:209], v[86:89]
	v_mfma_f32_16x16x32_bf16 v[82:85], v[176:179], v[206:209], v[82:85]
	v_mfma_f32_16x16x32_bf16 v[70:73], v[168:171], v[214:217], v[70:73]
	v_mfma_f32_16x16x32_bf16 v[66:69], v[176:179], v[214:217], v[66:69]
	v_mfma_f32_16x16x32_bf16 v[118:121], v[172:175], v[188:191], v[118:121]
	v_mfma_f32_16x16x32_bf16 v[114:117], v[180:183], v[188:191], v[114:117]
	v_mfma_f32_16x16x32_bf16 v[102:105], v[172:175], v[200:203], v[102:105]
	v_mfma_f32_16x16x32_bf16 v[94:97], v[180:183], v[200:203], v[94:97]
	v_mfma_f32_16x16x32_bf16 v[86:89], v[172:175], v[210:213], v[86:89]
	v_mfma_f32_16x16x32_bf16 v[82:85], v[180:183], v[210:213], v[82:85]
	v_mfma_f32_16x16x32_bf16 v[70:73], v[172:175], v[218:221], v[70:73]
	v_mfma_f32_16x16x32_bf16 v[66:69], v[180:183], v[218:221], v[66:69]
	s_setprio 0
	s_barrier
	s_add_i32 s58, s50, s40
	v_lshl_add_u64 v[192:193], s[30:31], 0, v[134:135]
	s_mov_b32 m0, s58
	ds_read_b128 v[184:187], v154 offset:16384
	ds_read_b128 v[188:191], v154 offset:17408
	ds_read_b128 v[196:199], v154 offset:18432
	ds_read_b128 v[200:203], v154 offset:19456
	ds_read_b128 v[206:209], v154 offset:20480
	ds_read_b128 v[210:213], v154 offset:21504
	ds_read_b128 v[214:217], v154 offset:22528
	ds_read_b128 v[218:221], v154 offset:23552
	global_load_lds_dwordx4 v[192:193], off
	s_add_i32 m0, s58, 0x2000
	s_add_u32 s58, s30, 0x80000
	v_lshl_add_u64 v[222:223], s[30:31], 0, v[130:131]
	s_addc_u32 s59, s31, 0
	s_add_i32 s60, s51, s40
	global_load_lds_dwordx4 v[222:223], off
	v_lshl_add_u64 v[224:225], s[58:59], 0, v[134:135]
	s_mov_b32 m0, s60
	v_lshl_add_u64 v[226:227], s[34:35], 0, v[132:133]
	global_load_lds_dwordx4 v[224:225], off
	v_lshl_add_u64 v[224:225], s[58:59], 0, v[130:131]
	s_add_i32 m0, s60, 0x2000
	s_nop 0
	global_load_lds_dwordx4 v[224:225], off
	v_lshl_add_u64 v[224:225], s[34:35], 0, v[136:137]
	s_mov_b32 m0, s27
	s_nop 0
	global_load_lds_dwordx4 v[224:225], off
	s_mov_b32 m0, s42
	s_nop 0
	global_load_lds_dwordx4 v[226:227], off
	s_waitcnt vmcnt(8)
	s_waitcnt lgkmcnt(0)
	s_setprio 1
	s_barrier
	v_mfma_f32_16x16x32_bf16 v[62:65], v[146:149], v[184:187], v[62:65]
	v_mfma_f32_16x16x32_bf16 v[58:61], v[160:163], v[184:187], v[58:61]
	v_mfma_f32_16x16x32_bf16 v[46:49], v[146:149], v[196:199], v[46:49]
	v_mfma_f32_16x16x32_bf16 v[42:45], v[160:163], v[196:199], v[42:45]
	v_mfma_f32_16x16x32_bf16 v[30:33], v[146:149], v[206:209], v[30:33]
	v_mfma_f32_16x16x32_bf16 v[26:29], v[160:163], v[206:209], v[26:29]
	v_mfma_f32_16x16x32_bf16 v[14:17], v[146:149], v[214:217], v[14:17]
	v_mfma_f32_16x16x32_bf16 v[10:13], v[160:163], v[214:217], v[10:13]
	v_mfma_f32_16x16x32_bf16 v[62:65], v[156:159], v[188:191], v[62:65]
	v_mfma_f32_16x16x32_bf16 v[58:61], v[164:167], v[188:191], v[58:61]
	v_mfma_f32_16x16x32_bf16 v[46:49], v[156:159], v[200:203], v[46:49]
	v_mfma_f32_16x16x32_bf16 v[42:45], v[164:167], v[200:203], v[42:45]
	v_mfma_f32_16x16x32_bf16 v[30:33], v[156:159], v[210:213], v[30:33]
	v_mfma_f32_16x16x32_bf16 v[26:29], v[164:167], v[210:213], v[26:29]
	v_mfma_f32_16x16x32_bf16 v[14:17], v[156:159], v[218:221], v[14:17]
	v_mfma_f32_16x16x32_bf16 v[10:13], v[164:167], v[218:221], v[10:13]
	v_mfma_f32_16x16x32_bf16 v[54:57], v[168:171], v[184:187], v[54:57]
	v_mfma_f32_16x16x32_bf16 v[50:53], v[176:179], v[184:187], v[50:53]
	v_mfma_f32_16x16x32_bf16 v[38:41], v[168:171], v[196:199], v[38:41]
	v_mfma_f32_16x16x32_bf16 v[34:37], v[176:179], v[196:199], v[34:37]
	v_mfma_f32_16x16x32_bf16 v[22:25], v[168:171], v[206:209], v[22:25]
	v_mfma_f32_16x16x32_bf16 v[18:21], v[176:179], v[206:209], v[18:21]
	v_mfma_f32_16x16x32_bf16 v[6:9], v[168:171], v[214:217], v[6:9]
	v_mfma_f32_16x16x32_bf16 v[2:5], v[176:179], v[214:217], v[2:5]
	v_mfma_f32_16x16x32_bf16 v[54:57], v[172:175], v[188:191], v[54:57]
	v_mfma_f32_16x16x32_bf16 v[50:53], v[180:183], v[188:191], v[50:53]
	v_mfma_f32_16x16x32_bf16 v[38:41], v[172:175], v[200:203], v[38:41]
	v_mfma_f32_16x16x32_bf16 v[34:37], v[180:183], v[200:203], v[34:37]
	v_mfma_f32_16x16x32_bf16 v[22:25], v[172:175], v[210:213], v[22:25]
	v_mfma_f32_16x16x32_bf16 v[18:21], v[180:183], v[210:213], v[18:21]
	v_mfma_f32_16x16x32_bf16 v[6:9], v[172:175], v[218:221], v[6:9]
	v_mfma_f32_16x16x32_bf16 v[2:5], v[180:183], v[218:221], v[2:5]
	s_setprio 0
	s_barrier
	s_add_i32 s58, 0, 0x18000
	v_add_u32_e32 v155, s58, v150
	s_add_i32 s59, 0, 0x1c000
	ds_read_b128 v[146:149], v155
	ds_read_b128 v[156:159], v155 offset:1024
	ds_read_b128 v[160:163], v155 offset:2048
	ds_read_b128 v[164:167], v155 offset:3072
	v_add_u32_e32 v155, s59, v150
	ds_read_b128 v[168:171], v155
	ds_read_b128 v[172:175], v155 offset:1024
	ds_read_b128 v[176:179], v155 offset:2048
	ds_read_b128 v[180:183], v155 offset:3072
	s_add_u32 s34, s34, 0x80000
	s_addc_u32 s35, s35, 0
	s_mov_b32 m0, s43
	v_lshl_add_u64 v[228:229], s[34:35], 0, v[136:137]
	ds_read_b128 v[184:187], v154 offset:32768
	ds_read_b128 v[188:191], v154 offset:33792
	ds_read_b128 v[196:199], v154 offset:34816
	ds_read_b128 v[200:203], v154 offset:35840
	ds_read_b128 v[206:209], v154 offset:36864
	ds_read_b128 v[210:213], v154 offset:37888
	ds_read_b128 v[214:217], v154 offset:38912
	ds_read_b128 v[218:221], v154 offset:39936
	global_load_lds_dwordx4 v[228:229], off
	v_lshl_add_u64 v[228:229], s[34:35], 0, v[132:133]
	s_mov_b32 m0, s45
	s_nop 0
	global_load_lds_dwordx4 v[228:229], off
	s_waitcnt vmcnt(8)
	s_waitcnt lgkmcnt(0)
	s_setprio 1
	s_barrier
	v_mfma_f32_16x16x32_bf16 v[126:129], v[146:149], v[184:187], v[126:129]
	v_mfma_f32_16x16x32_bf16 v[122:125], v[160:163], v[184:187], v[122:125]
	v_mfma_f32_16x16x32_bf16 v[110:113], v[146:149], v[196:199], v[110:113]
	v_mfma_f32_16x16x32_bf16 v[106:109], v[160:163], v[196:199], v[106:109]
	v_mfma_f32_16x16x32_bf16 v[98:101], v[146:149], v[206:209], v[98:101]
	v_mfma_f32_16x16x32_bf16 v[90:93], v[160:163], v[206:209], v[90:93]
	v_mfma_f32_16x16x32_bf16 v[78:81], v[146:149], v[214:217], v[78:81]
	v_mfma_f32_16x16x32_bf16 v[74:77], v[160:163], v[214:217], v[74:77]
	v_mfma_f32_16x16x32_bf16 v[126:129], v[156:159], v[188:191], v[126:129]
	v_mfma_f32_16x16x32_bf16 v[122:125], v[164:167], v[188:191], v[122:125]
	v_mfma_f32_16x16x32_bf16 v[110:113], v[156:159], v[200:203], v[110:113]
	v_mfma_f32_16x16x32_bf16 v[106:109], v[164:167], v[200:203], v[106:109]
	v_mfma_f32_16x16x32_bf16 v[98:101], v[156:159], v[210:213], v[98:101]
	v_mfma_f32_16x16x32_bf16 v[90:93], v[164:167], v[210:213], v[90:93]
	v_mfma_f32_16x16x32_bf16 v[78:81], v[156:159], v[218:221], v[78:81]
	v_mfma_f32_16x16x32_bf16 v[74:77], v[164:167], v[218:221], v[74:77]
	v_mfma_f32_16x16x32_bf16 v[118:121], v[168:171], v[184:187], v[118:121]
	v_mfma_f32_16x16x32_bf16 v[114:117], v[176:179], v[184:187], v[114:117]
	v_mfma_f32_16x16x32_bf16 v[102:105], v[168:171], v[196:199], v[102:105]
	v_mfma_f32_16x16x32_bf16 v[94:97], v[176:179], v[196:199], v[94:97]
	v_mfma_f32_16x16x32_bf16 v[86:89], v[168:171], v[206:209], v[86:89]
	v_mfma_f32_16x16x32_bf16 v[82:85], v[176:179], v[206:209], v[82:85]
	v_mfma_f32_16x16x32_bf16 v[70:73], v[168:171], v[214:217], v[70:73]
	v_mfma_f32_16x16x32_bf16 v[66:69], v[176:179], v[214:217], v[66:69]
	v_mfma_f32_16x16x32_bf16 v[118:121], v[172:175], v[188:191], v[118:121]
	v_mfma_f32_16x16x32_bf16 v[114:117], v[180:183], v[188:191], v[114:117]
	v_mfma_f32_16x16x32_bf16 v[102:105], v[172:175], v[200:203], v[102:105]
	v_mfma_f32_16x16x32_bf16 v[94:97], v[180:183], v[200:203], v[94:97]
	v_mfma_f32_16x16x32_bf16 v[86:89], v[172:175], v[210:213], v[86:89]
	v_mfma_f32_16x16x32_bf16 v[82:85], v[180:183], v[210:213], v[82:85]
	v_mfma_f32_16x16x32_bf16 v[70:73], v[172:175], v[218:221], v[70:73]
	v_mfma_f32_16x16x32_bf16 v[66:69], v[180:183], v[218:221], v[66:69]
	s_setprio 0
	s_barrier
	s_add_i32 s34, s58, s40
	v_lshl_add_u64 v[192:193], v[192:193], 0, s[14:15]
	s_mov_b32 m0, s34
	ds_read_b128 v[184:187], v154 offset:49152
	ds_read_b128 v[188:191], v154 offset:50176
	ds_read_b128 v[196:199], v154 offset:51200
	ds_read_b128 v[200:203], v154 offset:52224
	ds_read_b128 v[206:209], v154 offset:53248
	ds_read_b128 v[210:213], v154 offset:54272
	ds_read_b128 v[214:217], v154 offset:55296
	ds_read_b128 v[218:221], v154 offset:56320
	global_load_lds_dwordx4 v[192:193], off
	s_add_i32 m0, s34, 0x2000
	s_add_u32 s30, s30, 0x80080
	v_lshl_add_u64 v[192:193], v[222:223], 0, s[14:15]
	s_addc_u32 s31, s31, 0
	s_add_i32 s34, s59, s40
	global_load_lds_dwordx4 v[192:193], off
	v_lshl_add_u64 v[192:193], s[30:31], 0, v[134:135]
	s_mov_b32 m0, s34
	s_nop 0
	global_load_lds_dwordx4 v[192:193], off
	v_lshl_add_u64 v[192:193], s[30:31], 0, v[130:131]
	s_add_i32 m0, s34, 0x2000
	s_nop 0
	global_load_lds_dwordx4 v[192:193], off
	v_lshl_add_u64 v[192:193], v[224:225], 0, s[14:15]
	s_mov_b32 m0, s47
	s_nop 0
	global_load_lds_dwordx4 v[192:193], off
	v_lshl_add_u64 v[192:193], v[226:227], 0, s[14:15]
	s_mov_b32 m0, s48
	s_nop 0
	global_load_lds_dwordx4 v[192:193], off
	s_nop 0
	s_waitcnt vmcnt(8)
	s_waitcnt lgkmcnt(0)
	s_setprio 1
	s_barrier
	v_mfma_f32_16x16x32_bf16 v[62:65], v[146:149], v[184:187], v[62:65]
	v_mfma_f32_16x16x32_bf16 v[58:61], v[160:163], v[184:187], v[58:61]
	v_mfma_f32_16x16x32_bf16 v[46:49], v[146:149], v[196:199], v[46:49]
	v_mfma_f32_16x16x32_bf16 v[42:45], v[160:163], v[196:199], v[42:45]
	v_mfma_f32_16x16x32_bf16 v[30:33], v[146:149], v[206:209], v[30:33]
	v_mfma_f32_16x16x32_bf16 v[26:29], v[160:163], v[206:209], v[26:29]
	v_mfma_f32_16x16x32_bf16 v[14:17], v[146:149], v[214:217], v[14:17]
	v_mfma_f32_16x16x32_bf16 v[10:13], v[160:163], v[214:217], v[10:13]
	v_mfma_f32_16x16x32_bf16 v[62:65], v[156:159], v[188:191], v[62:65]
	v_mfma_f32_16x16x32_bf16 v[58:61], v[164:167], v[188:191], v[58:61]
	v_mfma_f32_16x16x32_bf16 v[46:49], v[156:159], v[200:203], v[46:49]
	v_mfma_f32_16x16x32_bf16 v[42:45], v[164:167], v[200:203], v[42:45]
	v_mfma_f32_16x16x32_bf16 v[30:33], v[156:159], v[210:213], v[30:33]
	v_mfma_f32_16x16x32_bf16 v[26:29], v[164:167], v[210:213], v[26:29]
	v_mfma_f32_16x16x32_bf16 v[14:17], v[156:159], v[218:221], v[14:17]
	v_mfma_f32_16x16x32_bf16 v[10:13], v[164:167], v[218:221], v[10:13]
	v_mfma_f32_16x16x32_bf16 v[54:57], v[168:171], v[184:187], v[54:57]
	v_mfma_f32_16x16x32_bf16 v[50:53], v[176:179], v[184:187], v[50:53]
	v_mfma_f32_16x16x32_bf16 v[38:41], v[168:171], v[196:199], v[38:41]
	v_mfma_f32_16x16x32_bf16 v[34:37], v[176:179], v[196:199], v[34:37]
	v_mfma_f32_16x16x32_bf16 v[22:25], v[168:171], v[206:209], v[22:25]
	v_mfma_f32_16x16x32_bf16 v[18:21], v[176:179], v[206:209], v[18:21]
	v_mfma_f32_16x16x32_bf16 v[6:9], v[168:171], v[214:217], v[6:9]
	v_mfma_f32_16x16x32_bf16 v[2:5], v[176:179], v[214:217], v[2:5]
	v_mfma_f32_16x16x32_bf16 v[54:57], v[172:175], v[188:191], v[54:57]
	v_mfma_f32_16x16x32_bf16 v[50:53], v[180:183], v[188:191], v[50:53]
	v_mfma_f32_16x16x32_bf16 v[38:41], v[172:175], v[200:203], v[38:41]
	v_mfma_f32_16x16x32_bf16 v[34:37], v[180:183], v[200:203], v[34:37]
	v_mfma_f32_16x16x32_bf16 v[22:25], v[172:175], v[210:213], v[22:25]
	v_mfma_f32_16x16x32_bf16 v[18:21], v[180:183], v[210:213], v[18:21]
	v_mfma_f32_16x16x32_bf16 v[6:9], v[172:175], v[218:221], v[6:9]
	v_mfma_f32_16x16x32_bf16 v[2:5], v[180:183], v[218:221], v[2:5]
	s_setprio 0
	s_barrier
	s_add_i32 s57, s57, 2
	s_add_u32 s28, s28, 0x100
	s_addc_u32 s29, s29, 0
	s_add_u32 s55, s55, 0x100
	s_addc_u32 s56, s56, 0
	s_cmp_gt_u32 s57, 29
	s_cbranch_scc0 .LBB0_967
	s_and_b64 vcc, exec, s[16:17]
	s_cbranch_vccz .LBB0_970
	s_barrier

.LBB0_1057:
	ds_read_b128 v[150:153], v158
	ds_read_b128 v[162:165], v158 offset:1024
	ds_read_b128 v[166:169], v158 offset:2048
	ds_read_b128 v[170:173], v158 offset:3072
	ds_read_b128 v[174:177], v159
	ds_read_b128 v[178:181], v159 offset:1024
	ds_read_b128 v[182:185], v159 offset:2048
	ds_read_b128 v[186:189], v159 offset:3072
	s_add_i32 s84, s48, 2
	s_add_u32 s49, s62, 0xfff00080
	s_addc_u32 s64, s63, -1
	s_cmp_eq_u32 s51, s48
	s_cselect_b32 s48, s56, s53
	s_cselect_b32 s65, s9, s64
	s_cselect_b32 s64, s8, s49
	s_cselect_b32 s49, s57, s55
	v_lshl_add_u64 v[154:155], s[62:63], 0, v[138:139]
	s_add_i32 m0, s59, 0xc000
	ds_read_b128 v[190:193], v160
	ds_read_b128 v[196:199], v160 offset:1024
	ds_read_b128 v[200:203], v160 offset:2048
	ds_read_b128 v[206:209], v160 offset:3072
	ds_read_b128 v[210:213], v160 offset:4096
	ds_read_b128 v[214:217], v160 offset:5120
	ds_read_b128 v[218:221], v160 offset:6144
	ds_read_b128 v[222:225], v160 offset:7168
	global_load_lds_dwordx4 v[154:155], off
	v_lshl_add_u64 v[154:155], s[62:63], 0, v[140:141]
	s_add_i32 m0, s59, 0xe000
	s_nop 0
	global_load_lds_dwordx4 v[154:155], off
	s_nop 0
	s_waitcnt vmcnt(8)
	s_waitcnt lgkmcnt(0)
	s_setprio 1
	s_barrier
	v_mfma_f32_16x16x32_bf16 v[126:129], v[150:153], v[190:193], v[126:129]
	v_mfma_f32_16x16x32_bf16 v[122:125], v[166:169], v[190:193], v[122:125]
	v_mfma_f32_16x16x32_bf16 v[110:113], v[150:153], v[200:203], v[110:113]
	v_mfma_f32_16x16x32_bf16 v[106:109], v[166:169], v[200:203], v[106:109]
	v_mfma_f32_16x16x32_bf16 v[94:97], v[150:153], v[210:213], v[94:97]
	v_mfma_f32_16x16x32_bf16 v[90:93], v[166:169], v[210:213], v[90:93]
	v_mfma_f32_16x16x32_bf16 v[78:81], v[150:153], v[218:221], v[78:81]
	v_mfma_f32_16x16x32_bf16 v[74:77], v[166:169], v[218:221], v[74:77]
	v_mfma_f32_16x16x32_bf16 v[126:129], v[162:165], v[196:199], v[126:129]
	v_mfma_f32_16x16x32_bf16 v[122:125], v[170:173], v[196:199], v[122:125]
	v_mfma_f32_16x16x32_bf16 v[110:113], v[162:165], v[206:209], v[110:113]
	v_mfma_f32_16x16x32_bf16 v[106:109], v[170:173], v[206:209], v[106:109]
	v_mfma_f32_16x16x32_bf16 v[94:97], v[162:165], v[214:217], v[94:97]
	v_mfma_f32_16x16x32_bf16 v[90:93], v[170:173], v[214:217], v[90:93]
	v_mfma_f32_16x16x32_bf16 v[78:81], v[162:165], v[222:225], v[78:81]
	v_mfma_f32_16x16x32_bf16 v[74:77], v[170:173], v[222:225], v[74:77]
	v_mfma_f32_16x16x32_bf16 v[118:121], v[174:177], v[190:193], v[118:121]
	v_mfma_f32_16x16x32_bf16 v[114:117], v[182:185], v[190:193], v[114:117]
	v_mfma_f32_16x16x32_bf16 v[102:105], v[174:177], v[200:203], v[102:105]
	v_mfma_f32_16x16x32_bf16 v[98:101], v[182:185], v[200:203], v[98:101]
	v_mfma_f32_16x16x32_bf16 v[86:89], v[174:177], v[210:213], v[86:89]
	v_mfma_f32_16x16x32_bf16 v[82:85], v[182:185], v[210:213], v[82:85]
	v_mfma_f32_16x16x32_bf16 v[70:73], v[174:177], v[218:221], v[70:73]
	v_mfma_f32_16x16x32_bf16 v[66:69], v[182:185], v[218:221], v[66:69]
	v_mfma_f32_16x16x32_bf16 v[118:121], v[178:181], v[196:199], v[118:121]
	v_mfma_f32_16x16x32_bf16 v[114:117], v[186:189], v[196:199], v[114:117]
	v_mfma_f32_16x16x32_bf16 v[102:105], v[178:181], v[206:209], v[102:105]
	v_mfma_f32_16x16x32_bf16 v[98:101], v[186:189], v[206:209], v[98:101]
	v_mfma_f32_16x16x32_bf16 v[86:89], v[178:181], v[214:217], v[86:89]
	v_mfma_f32_16x16x32_bf16 v[82:85], v[186:189], v[214:217], v[82:85]
	v_mfma_f32_16x16x32_bf16 v[70:73], v[178:181], v[222:225], v[70:73]
	v_mfma_f32_16x16x32_bf16 v[66:69], v[186:189], v[222:225], v[66:69]
	s_setprio 0
	s_barrier
	s_add_i32 s85, s75, s66
	v_lshl_add_u64 v[154:155], s[48:49], 0, v[132:133]
	s_mov_b32 m0, s85
	ds_read_b128 v[190:193], v160 offset:16384
	ds_read_b128 v[196:199], v160 offset:17408
	ds_read_b128 v[200:203], v160 offset:18432
	ds_read_b128 v[206:209], v160 offset:19456
	ds_read_b128 v[210:213], v160 offset:20480
	ds_read_b128 v[214:217], v160 offset:21504
	ds_read_b128 v[218:221], v160 offset:22528
	ds_read_b128 v[222:225], v160 offset:23552
	global_load_lds_dwordx4 v[154:155], off
	s_add_i32 m0, s85, 0x2000
	s_add_u32 s86, s48, 0x100000
	v_lshl_add_u64 v[226:227], s[48:49], 0, v[136:137]
	s_addc_u32 s87, s49, 0
	s_add_i32 s85, s76, s66
	global_load_lds_dwordx4 v[226:227], off
	v_lshl_add_u64 v[228:229], s[86:87], 0, v[132:133]
	s_mov_b32 m0, s85
	v_lshl_add_u64 v[230:231], s[64:65], 0, v[134:135]
	global_load_lds_dwordx4 v[228:229], off
	v_lshl_add_u64 v[228:229], s[86:87], 0, v[136:137]
	s_add_i32 m0, s85, 0x2000
	s_nop 0
	global_load_lds_dwordx4 v[228:229], off
	v_lshl_add_u64 v[228:229], s[64:65], 0, v[130:131]
	s_mov_b32 m0, s59
	s_nop 0
	global_load_lds_dwordx4 v[228:229], off
	s_mov_b32 m0, s61
	s_nop 0
	global_load_lds_dwordx4 v[230:231], off
	s_waitcnt vmcnt(8)
	s_waitcnt lgkmcnt(0)
	s_setprio 1
	s_barrier
	v_mfma_f32_16x16x32_bf16 v[62:65], v[150:153], v[190:193], v[62:65]
	v_mfma_f32_16x16x32_bf16 v[58:61], v[166:169], v[190:193], v[58:61]
	v_mfma_f32_16x16x32_bf16 v[46:49], v[150:153], v[200:203], v[46:49]
	v_mfma_f32_16x16x32_bf16 v[42:45], v[166:169], v[200:203], v[42:45]
	v_mfma_f32_16x16x32_bf16 v[30:33], v[150:153], v[210:213], v[30:33]
	v_mfma_f32_16x16x32_bf16 v[26:29], v[166:169], v[210:213], v[26:29]
	v_mfma_f32_16x16x32_bf16 v[14:17], v[150:153], v[218:221], v[14:17]
	v_mfma_f32_16x16x32_bf16 v[10:13], v[166:169], v[218:221], v[10:13]
	v_mfma_f32_16x16x32_bf16 v[62:65], v[162:165], v[196:199], v[62:65]
	v_mfma_f32_16x16x32_bf16 v[58:61], v[170:173], v[196:199], v[58:61]
	v_mfma_f32_16x16x32_bf16 v[46:49], v[162:165], v[206:209], v[46:49]
	v_mfma_f32_16x16x32_bf16 v[42:45], v[170:173], v[206:209], v[42:45]
	v_mfma_f32_16x16x32_bf16 v[30:33], v[162:165], v[214:217], v[30:33]
	v_mfma_f32_16x16x32_bf16 v[26:29], v[170:173], v[214:217], v[26:29]
	v_mfma_f32_16x16x32_bf16 v[14:17], v[162:165], v[222:225], v[14:17]
	v_mfma_f32_16x16x32_bf16 v[10:13], v[170:173], v[222:225], v[10:13]
	v_mfma_f32_16x16x32_bf16 v[54:57], v[174:177], v[190:193], v[54:57]
	v_mfma_f32_16x16x32_bf16 v[50:53], v[182:185], v[190:193], v[50:53]
	v_mfma_f32_16x16x32_bf16 v[38:41], v[174:177], v[200:203], v[38:41]
	v_mfma_f32_16x16x32_bf16 v[34:37], v[182:185], v[200:203], v[34:37]
	v_mfma_f32_16x16x32_bf16 v[22:25], v[174:177], v[210:213], v[22:25]
	v_mfma_f32_16x16x32_bf16 v[18:21], v[182:185], v[210:213], v[18:21]
	v_mfma_f32_16x16x32_bf16 v[6:9], v[174:177], v[218:221], v[6:9]
	v_mfma_f32_16x16x32_bf16 v[2:5], v[182:185], v[218:221], v[2:5]
	v_mfma_f32_16x16x32_bf16 v[54:57], v[178:181], v[196:199], v[54:57]
	v_mfma_f32_16x16x32_bf16 v[50:53], v[186:189], v[196:199], v[50:53]
	v_mfma_f32_16x16x32_bf16 v[38:41], v[178:181], v[206:209], v[38:41]
	v_mfma_f32_16x16x32_bf16 v[34:37], v[186:189], v[206:209], v[34:37]
	v_mfma_f32_16x16x32_bf16 v[22:25], v[178:181], v[214:217], v[22:25]
	v_mfma_f32_16x16x32_bf16 v[18:21], v[186:189], v[214:217], v[18:21]
	v_mfma_f32_16x16x32_bf16 v[6:9], v[178:181], v[222:225], v[6:9]
	v_mfma_f32_16x16x32_bf16 v[2:5], v[186:189], v[222:225], v[2:5]
	s_setprio 0
	s_barrier
	s_add_i32 s85, 0, 0x18000
	v_add_u32_e32 v161, s85, v156
	s_add_i32 s86, 0, 0x1c000
	ds_read_b128 v[150:153], v161
	ds_read_b128 v[162:165], v161 offset:1024
	ds_read_b128 v[166:169], v161 offset:2048
	ds_read_b128 v[170:173], v161 offset:3072
	v_add_u32_e32 v161, s86, v156
	ds_read_b128 v[174:177], v161
	ds_read_b128 v[178:181], v161 offset:1024
	ds_read_b128 v[182:185], v161 offset:2048
	ds_read_b128 v[186:189], v161 offset:3072
	s_add_u32 s64, s64, 0x100000
	s_addc_u32 s65, s65, 0
	s_mov_b32 m0, s67
	v_lshl_add_u64 v[232:233], s[64:65], 0, v[130:131]
	ds_read_b128 v[190:193], v160 offset:32768
	ds_read_b128 v[196:199], v160 offset:33792
	ds_read_b128 v[200:203], v160 offset:34816
	ds_read_b128 v[206:209], v160 offset:35840
	ds_read_b128 v[210:213], v160 offset:36864
	ds_read_b128 v[214:217], v160 offset:37888
	ds_read_b128 v[218:221], v160 offset:38912
	ds_read_b128 v[222:225], v160 offset:39936
	global_load_lds_dwordx4 v[232:233], off
	v_lshl_add_u64 v[232:233], s[64:65], 0, v[134:135]
	s_mov_b32 m0, s68
	s_nop 0
	global_load_lds_dwordx4 v[232:233], off
	s_waitcnt vmcnt(8)
	s_waitcnt lgkmcnt(0)
	s_setprio 1
	s_barrier
	v_mfma_f32_16x16x32_bf16 v[126:129], v[150:153], v[190:193], v[126:129]
	v_mfma_f32_16x16x32_bf16 v[122:125], v[166:169], v[190:193], v[122:125]
	v_mfma_f32_16x16x32_bf16 v[110:113], v[150:153], v[200:203], v[110:113]
	v_mfma_f32_16x16x32_bf16 v[106:109], v[166:169], v[200:203], v[106:109]
	v_mfma_f32_16x16x32_bf16 v[94:97], v[150:153], v[210:213], v[94:97]
	v_mfma_f32_16x16x32_bf16 v[90:93], v[166:169], v[210:213], v[90:93]
	v_mfma_f32_16x16x32_bf16 v[78:81], v[150:153], v[218:221], v[78:81]
	v_mfma_f32_16x16x32_bf16 v[74:77], v[166:169], v[218:221], v[74:77]
	v_mfma_f32_16x16x32_bf16 v[126:129], v[162:165], v[196:199], v[126:129]
	v_mfma_f32_16x16x32_bf16 v[122:125], v[170:173], v[196:199], v[122:125]
	v_mfma_f32_16x16x32_bf16 v[110:113], v[162:165], v[206:209], v[110:113]
	v_mfma_f32_16x16x32_bf16 v[106:109], v[170:173], v[206:209], v[106:109]
	v_mfma_f32_16x16x32_bf16 v[94:97], v[162:165], v[214:217], v[94:97]
	v_mfma_f32_16x16x32_bf16 v[90:93], v[170:173], v[214:217], v[90:93]
	v_mfma_f32_16x16x32_bf16 v[78:81], v[162:165], v[222:225], v[78:81]
	v_mfma_f32_16x16x32_bf16 v[74:77], v[170:173], v[222:225], v[74:77]
	v_mfma_f32_16x16x32_bf16 v[118:121], v[174:177], v[190:193], v[118:121]
	v_mfma_f32_16x16x32_bf16 v[114:117], v[182:185], v[190:193], v[114:117]
	v_mfma_f32_16x16x32_bf16 v[102:105], v[174:177], v[200:203], v[102:105]
	v_mfma_f32_16x16x32_bf16 v[98:101], v[182:185], v[200:203], v[98:101]
	v_mfma_f32_16x16x32_bf16 v[86:89], v[174:177], v[210:213], v[86:89]
	v_mfma_f32_16x16x32_bf16 v[82:85], v[182:185], v[210:213], v[82:85]
	v_mfma_f32_16x16x32_bf16 v[70:73], v[174:177], v[218:221], v[70:73]
	v_mfma_f32_16x16x32_bf16 v[66:69], v[182:185], v[218:221], v[66:69]
	v_mfma_f32_16x16x32_bf16 v[118:121], v[178:181], v[196:199], v[118:121]
	v_mfma_f32_16x16x32_bf16 v[114:117], v[186:189], v[196:199], v[114:117]
	v_mfma_f32_16x16x32_bf16 v[102:105], v[178:181], v[206:209], v[102:105]
	v_mfma_f32_16x16x32_bf16 v[98:101], v[186:189], v[206:209], v[98:101]
	v_mfma_f32_16x16x32_bf16 v[86:89], v[178:181], v[214:217], v[86:89]
	v_mfma_f32_16x16x32_bf16 v[82:85], v[186:189], v[214:217], v[82:85]
	v_mfma_f32_16x16x32_bf16 v[70:73], v[178:181], v[222:225], v[70:73]
	v_mfma_f32_16x16x32_bf16 v[66:69], v[186:189], v[222:225], v[66:69]
	s_setprio 0
	s_barrier
	s_add_i32 s64, s85, s66
	v_lshl_add_u64 v[154:155], v[154:155], 0, s[20:21]
	s_mov_b32 m0, s64
	ds_read_b128 v[190:193], v160 offset:49152
	ds_read_b128 v[196:199], v160 offset:50176
	ds_read_b128 v[200:203], v160 offset:51200
	ds_read_b128 v[206:209], v160 offset:52224
	ds_read_b128 v[210:213], v160 offset:53248
	ds_read_b128 v[214:217], v160 offset:54272
	ds_read_b128 v[218:221], v160 offset:55296
	ds_read_b128 v[222:225], v160 offset:56320
	global_load_lds_dwordx4 v[154:155], off
	s_add_i32 m0, s64, 0x2000
	s_add_u32 s48, s48, 0x100080
	v_lshl_add_u64 v[154:155], v[226:227], 0, s[20:21]
	s_addc_u32 s49, s49, 0
	s_add_i32 s64, s86, s66
	global_load_lds_dwordx4 v[154:155], off
	v_lshl_add_u64 v[154:155], s[48:49], 0, v[132:133]
	s_mov_b32 m0, s64
	s_nop 0
	global_load_lds_dwordx4 v[154:155], off
	v_lshl_add_u64 v[154:155], s[48:49], 0, v[136:137]
	s_add_i32 m0, s64, 0x2000
	s_nop 0
	global_load_lds_dwordx4 v[154:155], off
	v_lshl_add_u64 v[154:155], v[228:229], 0, s[20:21]
	s_mov_b32 m0, s72
	s_nop 0
	global_load_lds_dwordx4 v[154:155], off
	v_lshl_add_u64 v[154:155], v[230:231], 0, s[20:21]
	s_mov_b32 m0, s73
	s_nop 0
	global_load_lds_dwordx4 v[154:155], off
	s_nop 0
	s_waitcnt vmcnt(8)
	s_waitcnt lgkmcnt(0)
	s_setprio 1
	s_barrier
	v_mfma_f32_16x16x32_bf16 v[62:65], v[150:153], v[190:193], v[62:65]
	v_mfma_f32_16x16x32_bf16 v[58:61], v[166:169], v[190:193], v[58:61]
	v_mfma_f32_16x16x32_bf16 v[46:49], v[150:153], v[200:203], v[46:49]
	v_mfma_f32_16x16x32_bf16 v[42:45], v[166:169], v[200:203], v[42:45]
	v_mfma_f32_16x16x32_bf16 v[30:33], v[150:153], v[210:213], v[30:33]
	v_mfma_f32_16x16x32_bf16 v[26:29], v[166:169], v[210:213], v[26:29]
	v_mfma_f32_16x16x32_bf16 v[14:17], v[150:153], v[218:221], v[14:17]
	v_mfma_f32_16x16x32_bf16 v[10:13], v[166:169], v[218:221], v[10:13]
	v_mfma_f32_16x16x32_bf16 v[62:65], v[162:165], v[196:199], v[62:65]
	v_mfma_f32_16x16x32_bf16 v[58:61], v[170:173], v[196:199], v[58:61]
	v_mfma_f32_16x16x32_bf16 v[46:49], v[162:165], v[206:209], v[46:49]
	v_mfma_f32_16x16x32_bf16 v[42:45], v[170:173], v[206:209], v[42:45]
	v_mfma_f32_16x16x32_bf16 v[30:33], v[162:165], v[214:217], v[30:33]
	v_mfma_f32_16x16x32_bf16 v[26:29], v[170:173], v[214:217], v[26:29]
	v_mfma_f32_16x16x32_bf16 v[14:17], v[162:165], v[222:225], v[14:17]
	v_mfma_f32_16x16x32_bf16 v[10:13], v[170:173], v[222:225], v[10:13]
	v_mfma_f32_16x16x32_bf16 v[54:57], v[174:177], v[190:193], v[54:57]
	v_mfma_f32_16x16x32_bf16 v[50:53], v[182:185], v[190:193], v[50:53]
	v_mfma_f32_16x16x32_bf16 v[38:41], v[174:177], v[200:203], v[38:41]
	v_mfma_f32_16x16x32_bf16 v[34:37], v[182:185], v[200:203], v[34:37]
	v_mfma_f32_16x16x32_bf16 v[22:25], v[174:177], v[210:213], v[22:25]
	v_mfma_f32_16x16x32_bf16 v[18:21], v[182:185], v[210:213], v[18:21]
	v_mfma_f32_16x16x32_bf16 v[6:9], v[174:177], v[218:221], v[6:9]
	v_mfma_f32_16x16x32_bf16 v[2:5], v[182:185], v[218:221], v[2:5]
	v_mfma_f32_16x16x32_bf16 v[54:57], v[178:181], v[196:199], v[54:57]
	v_mfma_f32_16x16x32_bf16 v[50:53], v[186:189], v[196:199], v[50:53]
	v_mfma_f32_16x16x32_bf16 v[38:41], v[178:181], v[206:209], v[38:41]
	v_mfma_f32_16x16x32_bf16 v[34:37], v[186:189], v[206:209], v[34:37]
	v_mfma_f32_16x16x32_bf16 v[22:25], v[178:181], v[214:217], v[22:25]
	v_mfma_f32_16x16x32_bf16 v[18:21], v[186:189], v[214:217], v[18:21]
	v_mfma_f32_16x16x32_bf16 v[6:9], v[178:181], v[222:225], v[6:9]
	v_mfma_f32_16x16x32_bf16 v[2:5], v[186:189], v[222:225], v[2:5]
	s_setprio 0
	s_barrier
	s_add_u32 s62, s62, 0x100
	s_addc_u32 s63, s63, 0
	s_add_u32 s53, s53, 0x100
	s_addc_u32 s55, s55, 0
	s_cmp_ge_i32 s84, s83
	s_mov_b32 s48, s84
	s_cbranch_scc0 .LBB0_1057
	s_and_b64 vcc, exec, s[22:23]
	s_cbranch_vccz .LBB0_1060
	s_barrier

.LBB0_1197:
	ds_read_b128 v[162:165], v141
	ds_read_b128 v[166:169], v141 offset:1024
	ds_read_b128 v[170:173], v141 offset:2048
	ds_read_b128 v[174:177], v141 offset:3072
	ds_read_b128 v[178:181], v145
	ds_read_b128 v[182:185], v145 offset:1024
	ds_read_b128 v[186:189], v145 offset:2048
	ds_read_b128 v[190:193], v145 offset:3072
	s_add_i32 s65, s34, 2
	s_add_u32 s35, s30, 0xfff00080
	s_addc_u32 s40, s31, -1
	s_cmp_eq_u32 s62, s34
	s_cselect_b32 s34, s61, s63
	s_cselect_b32 s41, s21, s40
	s_cselect_b32 s40, s25, s35
	s_cselect_b32 s35, s23, s64
	v_lshl_add_u64 v[158:159], s[30:31], 0, v[148:149]
	s_add_i32 m0, s8, 0xc000
	ds_read_b128 v[196:199], v160
	ds_read_b128 v[200:203], v160 offset:1024
	ds_read_b128 v[206:209], v160 offset:2048
	ds_read_b128 v[210:213], v160 offset:3072
	ds_read_b128 v[214:217], v160 offset:4096
	ds_read_b128 v[218:221], v160 offset:5120
	ds_read_b128 v[222:225], v160 offset:6144
	ds_read_b128 v[226:229], v160 offset:7168
	global_load_lds_dwordx4 v[158:159], off
	v_lshl_add_u64 v[158:159], s[30:31], 0, v[150:151]
	s_add_i32 m0, s8, 0xe000
	s_nop 0
	global_load_lds_dwordx4 v[158:159], off
	s_nop 0
	s_waitcnt vmcnt(8)
	s_waitcnt lgkmcnt(0)
	s_setprio 1
	s_barrier
	v_mfma_f32_16x16x32_bf16 v[126:129], v[162:165], v[196:199], v[126:129]
	v_mfma_f32_16x16x32_bf16 v[122:125], v[170:173], v[196:199], v[122:125]
	v_mfma_f32_16x16x32_bf16 v[118:121], v[162:165], v[206:209], v[118:121]
	v_mfma_f32_16x16x32_bf16 v[114:117], v[170:173], v[206:209], v[114:117]
	v_mfma_f32_16x16x32_bf16 v[102:105], v[162:165], v[214:217], v[102:105]
	v_mfma_f32_16x16x32_bf16 v[98:101], v[170:173], v[214:217], v[98:101]
	v_mfma_f32_16x16x32_bf16 v[42:45], v[162:165], v[222:225], v[42:45]
	v_mfma_f32_16x16x32_bf16 v[34:37], v[170:173], v[222:225], v[34:37]
	v_mfma_f32_16x16x32_bf16 v[126:129], v[166:169], v[200:203], v[126:129]
	v_mfma_f32_16x16x32_bf16 v[122:125], v[174:177], v[200:203], v[122:125]
	v_mfma_f32_16x16x32_bf16 v[118:121], v[166:169], v[210:213], v[118:121]
	v_mfma_f32_16x16x32_bf16 v[114:117], v[174:177], v[210:213], v[114:117]
	v_mfma_f32_16x16x32_bf16 v[102:105], v[166:169], v[218:221], v[102:105]
	v_mfma_f32_16x16x32_bf16 v[98:101], v[174:177], v[218:221], v[98:101]
	v_mfma_f32_16x16x32_bf16 v[42:45], v[166:169], v[226:229], v[42:45]
	v_mfma_f32_16x16x32_bf16 v[34:37], v[174:177], v[226:229], v[34:37]
	v_mfma_f32_16x16x32_bf16 v[110:113], v[178:181], v[196:199], v[110:113]
	v_mfma_f32_16x16x32_bf16 v[106:109], v[186:189], v[196:199], v[106:109]
	v_mfma_f32_16x16x32_bf16 v[94:97], v[178:181], v[206:209], v[94:97]
	v_mfma_f32_16x16x32_bf16 v[90:93], v[186:189], v[206:209], v[90:93]
	v_mfma_f32_16x16x32_bf16 v[86:89], v[178:181], v[214:217], v[86:89]
	v_mfma_f32_16x16x32_bf16 v[82:85], v[186:189], v[214:217], v[82:85]
	v_mfma_f32_16x16x32_bf16 v[30:33], v[178:181], v[222:225], v[30:33]
	v_mfma_f32_16x16x32_bf16 v[26:29], v[186:189], v[222:225], v[26:29]
	v_mfma_f32_16x16x32_bf16 v[110:113], v[182:185], v[200:203], v[110:113]
	v_mfma_f32_16x16x32_bf16 v[106:109], v[190:193], v[200:203], v[106:109]
	v_mfma_f32_16x16x32_bf16 v[94:97], v[182:185], v[210:213], v[94:97]
	v_mfma_f32_16x16x32_bf16 v[90:93], v[190:193], v[210:213], v[90:93]
	v_mfma_f32_16x16x32_bf16 v[86:89], v[182:185], v[218:221], v[86:89]
	v_mfma_f32_16x16x32_bf16 v[82:85], v[190:193], v[218:221], v[82:85]
	v_mfma_f32_16x16x32_bf16 v[30:33], v[182:185], v[226:229], v[30:33]
	v_mfma_f32_16x16x32_bf16 v[26:29], v[190:193], v[226:229], v[26:29]
	s_setprio 0
	s_barrier
	s_add_i32 s66, s56, s42
	v_lshl_add_u64 v[158:159], s[34:35], 0, v[134:135]
	s_mov_b32 m0, s66
	ds_read_b128 v[196:199], v160 offset:16384
	ds_read_b128 v[200:203], v160 offset:17408
	ds_read_b128 v[206:209], v160 offset:18432
	ds_read_b128 v[210:213], v160 offset:19456
	ds_read_b128 v[214:217], v160 offset:20480
	ds_read_b128 v[218:221], v160 offset:21504
	ds_read_b128 v[222:225], v160 offset:22528
	ds_read_b128 v[226:229], v160 offset:23552
	global_load_lds_dwordx4 v[158:159], off
	s_add_i32 m0, s66, 0x2000
	s_add_u32 s66, s34, 0x100000
	v_lshl_add_u64 v[230:231], s[34:35], 0, v[132:133]
	s_addc_u32 s67, s35, 0
	s_add_i32 s68, s57, s42
	global_load_lds_dwordx4 v[230:231], off
	v_lshl_add_u64 v[232:233], s[66:67], 0, v[134:135]
	s_mov_b32 m0, s68
	v_lshl_add_u64 v[234:235], s[40:41], 0, v[132:133]
	global_load_lds_dwordx4 v[232:233], off
	v_lshl_add_u64 v[232:233], s[66:67], 0, v[132:133]
	s_add_i32 m0, s68, 0x2000
	s_nop 0
	global_load_lds_dwordx4 v[232:233], off
	v_lshl_add_u64 v[232:233], s[40:41], 0, v[134:135]
	s_mov_b32 m0, s8
	s_nop 0
	global_load_lds_dwordx4 v[232:233], off
	s_mov_b32 m0, s15
	s_nop 0
	global_load_lds_dwordx4 v[234:235], off
	s_waitcnt vmcnt(8)
	s_waitcnt lgkmcnt(0)
	s_setprio 1
	s_barrier
	v_mfma_f32_16x16x32_bf16 v[78:81], v[162:165], v[196:199], v[78:81]
	v_mfma_f32_16x16x32_bf16 v[74:77], v[170:173], v[196:199], v[74:77]
	v_mfma_f32_16x16x32_bf16 v[70:73], v[162:165], v[206:209], v[70:73]
	v_mfma_f32_16x16x32_bf16 v[66:69], v[170:173], v[206:209], v[66:69]
	v_mfma_f32_16x16x32_bf16 v[54:57], v[162:165], v[214:217], v[54:57]
	v_mfma_f32_16x16x32_bf16 v[50:53], v[170:173], v[214:217], v[50:53]
	v_mfma_f32_16x16x32_bf16 v[14:17], v[162:165], v[222:225], v[14:17]
	v_mfma_f32_16x16x32_bf16 v[10:13], v[170:173], v[222:225], v[10:13]
	v_mfma_f32_16x16x32_bf16 v[78:81], v[166:169], v[200:203], v[78:81]
	v_mfma_f32_16x16x32_bf16 v[74:77], v[174:177], v[200:203], v[74:77]
	v_mfma_f32_16x16x32_bf16 v[70:73], v[166:169], v[210:213], v[70:73]
	v_mfma_f32_16x16x32_bf16 v[66:69], v[174:177], v[210:213], v[66:69]
	v_mfma_f32_16x16x32_bf16 v[54:57], v[166:169], v[218:221], v[54:57]
	v_mfma_f32_16x16x32_bf16 v[50:53], v[174:177], v[218:221], v[50:53]
	v_mfma_f32_16x16x32_bf16 v[14:17], v[166:169], v[226:229], v[14:17]
	v_mfma_f32_16x16x32_bf16 v[10:13], v[174:177], v[226:229], v[10:13]
	v_mfma_f32_16x16x32_bf16 v[62:65], v[178:181], v[196:199], v[62:65]
	v_mfma_f32_16x16x32_bf16 v[58:61], v[186:189], v[196:199], v[58:61]
	v_mfma_f32_16x16x32_bf16 v[46:49], v[178:181], v[206:209], v[46:49]
	v_mfma_f32_16x16x32_bf16 v[38:41], v[186:189], v[206:209], v[38:41]
	v_mfma_f32_16x16x32_bf16 v[22:25], v[178:181], v[214:217], v[22:25]
	v_mfma_f32_16x16x32_bf16 v[18:21], v[186:189], v[214:217], v[18:21]
	v_mfma_f32_16x16x32_bf16 v[6:9], v[178:181], v[222:225], v[6:9]
	v_mfma_f32_16x16x32_bf16 v[2:5], v[186:189], v[222:225], v[2:5]
	v_mfma_f32_16x16x32_bf16 v[62:65], v[182:185], v[200:203], v[62:65]
	v_mfma_f32_16x16x32_bf16 v[58:61], v[190:193], v[200:203], v[58:61]
	v_mfma_f32_16x16x32_bf16 v[46:49], v[182:185], v[210:213], v[46:49]
	v_mfma_f32_16x16x32_bf16 v[38:41], v[190:193], v[210:213], v[38:41]
	v_mfma_f32_16x16x32_bf16 v[22:25], v[182:185], v[218:221], v[22:25]
	v_mfma_f32_16x16x32_bf16 v[18:21], v[190:193], v[218:221], v[18:21]
	v_mfma_f32_16x16x32_bf16 v[6:9], v[182:185], v[226:229], v[6:9]
	v_mfma_f32_16x16x32_bf16 v[2:5], v[190:193], v[226:229], v[2:5]
	s_setprio 0
	s_barrier
	s_add_i32 s66, 0, 0x18000
	v_add_u32_e32 v161, s66, v1
	s_add_i32 s67, 0, 0x1c000
	ds_read_b128 v[162:165], v161
	ds_read_b128 v[166:169], v161 offset:1024
	ds_read_b128 v[170:173], v161 offset:2048
	ds_read_b128 v[174:177], v161 offset:3072
	v_add_u32_e32 v161, s67, v1
	ds_read_b128 v[178:181], v161
	ds_read_b128 v[182:185], v161 offset:1024
	ds_read_b128 v[186:189], v161 offset:2048
	ds_read_b128 v[190:193], v161 offset:3072
	s_add_u32 s40, s40, 0x100000
	s_addc_u32 s41, s41, 0
	s_mov_b32 m0, s46
	v_lshl_add_u64 v[236:237], s[40:41], 0, v[134:135]
	ds_read_b128 v[196:199], v160 offset:32768
	ds_read_b128 v[200:203], v160 offset:33792
	ds_read_b128 v[206:209], v160 offset:34816
	ds_read_b128 v[210:213], v160 offset:35840
	ds_read_b128 v[214:217], v160 offset:36864
	ds_read_b128 v[218:221], v160 offset:37888
	ds_read_b128 v[222:225], v160 offset:38912
	ds_read_b128 v[226:229], v160 offset:39936
	global_load_lds_dwordx4 v[236:237], off
	v_lshl_add_u64 v[236:237], s[40:41], 0, v[132:133]
	s_mov_b32 m0, s47
	s_nop 0
	global_load_lds_dwordx4 v[236:237], off
	s_waitcnt vmcnt(8)
	s_waitcnt lgkmcnt(0)
	s_setprio 1
	s_barrier
	v_mfma_f32_16x16x32_bf16 v[126:129], v[162:165], v[196:199], v[126:129]
	v_mfma_f32_16x16x32_bf16 v[122:125], v[170:173], v[196:199], v[122:125]
	v_mfma_f32_16x16x32_bf16 v[118:121], v[162:165], v[206:209], v[118:121]
	v_mfma_f32_16x16x32_bf16 v[114:117], v[170:173], v[206:209], v[114:117]
	v_mfma_f32_16x16x32_bf16 v[102:105], v[162:165], v[214:217], v[102:105]
	v_mfma_f32_16x16x32_bf16 v[98:101], v[170:173], v[214:217], v[98:101]
	v_mfma_f32_16x16x32_bf16 v[42:45], v[162:165], v[222:225], v[42:45]
	v_mfma_f32_16x16x32_bf16 v[34:37], v[170:173], v[222:225], v[34:37]
	v_mfma_f32_16x16x32_bf16 v[126:129], v[166:169], v[200:203], v[126:129]
	v_mfma_f32_16x16x32_bf16 v[122:125], v[174:177], v[200:203], v[122:125]
	v_mfma_f32_16x16x32_bf16 v[118:121], v[166:169], v[210:213], v[118:121]
	v_mfma_f32_16x16x32_bf16 v[114:117], v[174:177], v[210:213], v[114:117]
	v_mfma_f32_16x16x32_bf16 v[102:105], v[166:169], v[218:221], v[102:105]
	v_mfma_f32_16x16x32_bf16 v[98:101], v[174:177], v[218:221], v[98:101]
	v_mfma_f32_16x16x32_bf16 v[42:45], v[166:169], v[226:229], v[42:45]
	v_mfma_f32_16x16x32_bf16 v[34:37], v[174:177], v[226:229], v[34:37]
	v_mfma_f32_16x16x32_bf16 v[110:113], v[178:181], v[196:199], v[110:113]
	v_mfma_f32_16x16x32_bf16 v[106:109], v[186:189], v[196:199], v[106:109]
	v_mfma_f32_16x16x32_bf16 v[94:97], v[178:181], v[206:209], v[94:97]
	v_mfma_f32_16x16x32_bf16 v[90:93], v[186:189], v[206:209], v[90:93]
	v_mfma_f32_16x16x32_bf16 v[86:89], v[178:181], v[214:217], v[86:89]
	v_mfma_f32_16x16x32_bf16 v[82:85], v[186:189], v[214:217], v[82:85]
	v_mfma_f32_16x16x32_bf16 v[30:33], v[178:181], v[222:225], v[30:33]
	v_mfma_f32_16x16x32_bf16 v[26:29], v[186:189], v[222:225], v[26:29]
	v_mfma_f32_16x16x32_bf16 v[110:113], v[182:185], v[200:203], v[110:113]
	v_mfma_f32_16x16x32_bf16 v[106:109], v[190:193], v[200:203], v[106:109]
	v_mfma_f32_16x16x32_bf16 v[94:97], v[182:185], v[210:213], v[94:97]
	v_mfma_f32_16x16x32_bf16 v[90:93], v[190:193], v[210:213], v[90:93]
	v_mfma_f32_16x16x32_bf16 v[86:89], v[182:185], v[218:221], v[86:89]
	v_mfma_f32_16x16x32_bf16 v[82:85], v[190:193], v[218:221], v[82:85]
	v_mfma_f32_16x16x32_bf16 v[30:33], v[182:185], v[226:229], v[30:33]
	v_mfma_f32_16x16x32_bf16 v[26:29], v[190:193], v[226:229], v[26:29]
	s_setprio 0
	s_barrier
	s_add_i32 s40, s66, s42
	v_lshl_add_u64 v[158:159], v[158:159], 0, s[12:13]
	s_mov_b32 m0, s40
	ds_read_b128 v[196:199], v160 offset:49152
	ds_read_b128 v[200:203], v160 offset:50176
	ds_read_b128 v[206:209], v160 offset:51200
	ds_read_b128 v[210:213], v160 offset:52224
	ds_read_b128 v[214:217], v160 offset:53248
	ds_read_b128 v[218:221], v160 offset:54272
	ds_read_b128 v[222:225], v160 offset:55296
	ds_read_b128 v[226:229], v160 offset:56320
	global_load_lds_dwordx4 v[158:159], off
	s_add_i32 m0, s40, 0x2000
	s_add_u32 s34, s34, 0x100080
	v_lshl_add_u64 v[158:159], v[230:231], 0, s[12:13]
	s_addc_u32 s35, s35, 0
	s_add_i32 s40, s67, s42
	global_load_lds_dwordx4 v[158:159], off
	v_lshl_add_u64 v[158:159], s[34:35], 0, v[134:135]
	s_mov_b32 m0, s40
	s_nop 0
	global_load_lds_dwordx4 v[158:159], off
	v_lshl_add_u64 v[158:159], s[34:35], 0, v[132:133]
	s_add_i32 m0, s40, 0x2000
	s_nop 0
	global_load_lds_dwordx4 v[158:159], off
	v_lshl_add_u64 v[158:159], v[232:233], 0, s[12:13]
	s_mov_b32 m0, s52
	s_nop 0
	global_load_lds_dwordx4 v[158:159], off
	v_lshl_add_u64 v[158:159], v[234:235], 0, s[12:13]
	s_mov_b32 m0, s53
	s_nop 0
	global_load_lds_dwordx4 v[158:159], off
	s_nop 0
	s_waitcnt vmcnt(8)
	s_waitcnt lgkmcnt(0)
	s_setprio 1
	s_barrier
	v_mfma_f32_16x16x32_bf16 v[78:81], v[162:165], v[196:199], v[78:81]
	v_mfma_f32_16x16x32_bf16 v[74:77], v[170:173], v[196:199], v[74:77]
	v_mfma_f32_16x16x32_bf16 v[70:73], v[162:165], v[206:209], v[70:73]
	v_mfma_f32_16x16x32_bf16 v[66:69], v[170:173], v[206:209], v[66:69]
	v_mfma_f32_16x16x32_bf16 v[54:57], v[162:165], v[214:217], v[54:57]
	v_mfma_f32_16x16x32_bf16 v[50:53], v[170:173], v[214:217], v[50:53]
	v_mfma_f32_16x16x32_bf16 v[14:17], v[162:165], v[222:225], v[14:17]
	v_mfma_f32_16x16x32_bf16 v[10:13], v[170:173], v[222:225], v[10:13]
	v_mfma_f32_16x16x32_bf16 v[78:81], v[166:169], v[200:203], v[78:81]
	v_mfma_f32_16x16x32_bf16 v[74:77], v[174:177], v[200:203], v[74:77]
	v_mfma_f32_16x16x32_bf16 v[70:73], v[166:169], v[210:213], v[70:73]
	v_mfma_f32_16x16x32_bf16 v[66:69], v[174:177], v[210:213], v[66:69]
	v_mfma_f32_16x16x32_bf16 v[54:57], v[166:169], v[218:221], v[54:57]
	v_mfma_f32_16x16x32_bf16 v[50:53], v[174:177], v[218:221], v[50:53]
	v_mfma_f32_16x16x32_bf16 v[14:17], v[166:169], v[226:229], v[14:17]
	v_mfma_f32_16x16x32_bf16 v[10:13], v[174:177], v[226:229], v[10:13]
	v_mfma_f32_16x16x32_bf16 v[62:65], v[178:181], v[196:199], v[62:65]
	v_mfma_f32_16x16x32_bf16 v[58:61], v[186:189], v[196:199], v[58:61]
	v_mfma_f32_16x16x32_bf16 v[46:49], v[178:181], v[206:209], v[46:49]
	v_mfma_f32_16x16x32_bf16 v[38:41], v[186:189], v[206:209], v[38:41]
	v_mfma_f32_16x16x32_bf16 v[22:25], v[178:181], v[214:217], v[22:25]
	v_mfma_f32_16x16x32_bf16 v[18:21], v[186:189], v[214:217], v[18:21]
	v_mfma_f32_16x16x32_bf16 v[6:9], v[178:181], v[222:225], v[6:9]
	v_mfma_f32_16x16x32_bf16 v[2:5], v[186:189], v[222:225], v[2:5]
	v_mfma_f32_16x16x32_bf16 v[62:65], v[182:185], v[200:203], v[62:65]
	v_mfma_f32_16x16x32_bf16 v[58:61], v[190:193], v[200:203], v[58:61]
	v_mfma_f32_16x16x32_bf16 v[46:49], v[182:185], v[210:213], v[46:49]
	v_mfma_f32_16x16x32_bf16 v[38:41], v[190:193], v[210:213], v[38:41]
	v_mfma_f32_16x16x32_bf16 v[22:25], v[182:185], v[218:221], v[22:25]
	v_mfma_f32_16x16x32_bf16 v[18:21], v[190:193], v[218:221], v[18:21]
	v_mfma_f32_16x16x32_bf16 v[6:9], v[182:185], v[226:229], v[6:9]
	v_mfma_f32_16x16x32_bf16 v[2:5], v[190:193], v[226:229], v[2:5]
	s_setprio 0
	s_barrier
	s_add_u32 s30, s30, 0x100
	s_addc_u32 s31, s31, 0
	s_add_u32 s63, s63, 0x100
	s_addc_u32 s64, s64, 0
	s_cmp_ge_i32 s65, s60
	s_mov_b32 s34, s65
	s_cbranch_scc0 .LBB0_1197
	s_and_b64 vcc, exec, s[18:19]
	s_cbranch_vccz .LBB0_1200
	s_barrier

.LBB0_1391:
	ds_read_b128 v[152:155], v159
	ds_read_b128 v[162:165], v159 offset:1024
	ds_read_b128 v[166:169], v159 offset:2048
	ds_read_b128 v[170:173], v159 offset:3072
	ds_read_b128 v[174:177], v160
	ds_read_b128 v[178:181], v160 offset:1024
	ds_read_b128 v[182:185], v160 offset:2048
	ds_read_b128 v[186:189], v160 offset:3072
	s_add_i32 s82, s48, 2
	s_add_u32 s49, s60, 0xfffe0080
	s_addc_u32 s62, s61, -1
	s_cmp_eq_u32 s47, s48
	s_cselect_b32 s48, s54, s51
	s_cselect_b32 s63, s9, s62
	s_cselect_b32 s62, s8, s49
	s_cselect_b32 s49, s55, s53
	v_lshl_add_u64 v[156:157], s[60:61], 0, v[140:141]
	s_add_i32 m0, s57, 0xc000
	ds_read_b128 v[190:193], v161
	ds_read_b128 v[196:199], v161 offset:1024
	ds_read_b128 v[200:203], v161 offset:2048
	ds_read_b128 v[206:209], v161 offset:3072
	ds_read_b128 v[210:213], v161 offset:4096
	ds_read_b128 v[214:217], v161 offset:5120
	ds_read_b128 v[218:221], v161 offset:6144
	ds_read_b128 v[222:225], v161 offset:7168
	global_load_lds_dwordx4 v[156:157], off
	v_lshl_add_u64 v[156:157], s[60:61], 0, v[142:143]
	s_add_i32 m0, s57, 0xe000
	s_nop 0
	global_load_lds_dwordx4 v[156:157], off
	s_nop 0
	s_waitcnt vmcnt(8)
	s_waitcnt lgkmcnt(0)
	s_setprio 1
	s_barrier
	v_mfma_f32_16x16x32_bf16 v[126:129], v[152:155], v[190:193], v[126:129]
	v_mfma_f32_16x16x32_bf16 v[122:125], v[166:169], v[190:193], v[122:125]
	v_mfma_f32_16x16x32_bf16 v[110:113], v[152:155], v[200:203], v[110:113]
	v_mfma_f32_16x16x32_bf16 v[106:109], v[166:169], v[200:203], v[106:109]
	v_mfma_f32_16x16x32_bf16 v[94:97], v[152:155], v[210:213], v[94:97]
	v_mfma_f32_16x16x32_bf16 v[90:93], v[166:169], v[210:213], v[90:93]
	v_mfma_f32_16x16x32_bf16 v[78:81], v[152:155], v[218:221], v[78:81]
	v_mfma_f32_16x16x32_bf16 v[74:77], v[166:169], v[218:221], v[74:77]
	v_mfma_f32_16x16x32_bf16 v[126:129], v[162:165], v[196:199], v[126:129]
	v_mfma_f32_16x16x32_bf16 v[122:125], v[170:173], v[196:199], v[122:125]
	v_mfma_f32_16x16x32_bf16 v[110:113], v[162:165], v[206:209], v[110:113]
	v_mfma_f32_16x16x32_bf16 v[106:109], v[170:173], v[206:209], v[106:109]
	v_mfma_f32_16x16x32_bf16 v[94:97], v[162:165], v[214:217], v[94:97]
	v_mfma_f32_16x16x32_bf16 v[90:93], v[170:173], v[214:217], v[90:93]
	v_mfma_f32_16x16x32_bf16 v[78:81], v[162:165], v[222:225], v[78:81]
	v_mfma_f32_16x16x32_bf16 v[74:77], v[170:173], v[222:225], v[74:77]
	v_mfma_f32_16x16x32_bf16 v[118:121], v[174:177], v[190:193], v[118:121]
	v_mfma_f32_16x16x32_bf16 v[114:117], v[182:185], v[190:193], v[114:117]
	v_mfma_f32_16x16x32_bf16 v[102:105], v[174:177], v[200:203], v[102:105]
	v_mfma_f32_16x16x32_bf16 v[98:101], v[182:185], v[200:203], v[98:101]
	v_mfma_f32_16x16x32_bf16 v[86:89], v[174:177], v[210:213], v[86:89]
	v_mfma_f32_16x16x32_bf16 v[82:85], v[182:185], v[210:213], v[82:85]
	v_mfma_f32_16x16x32_bf16 v[70:73], v[174:177], v[218:221], v[70:73]
	v_mfma_f32_16x16x32_bf16 v[66:69], v[182:185], v[218:221], v[66:69]
	v_mfma_f32_16x16x32_bf16 v[118:121], v[178:181], v[196:199], v[118:121]
	v_mfma_f32_16x16x32_bf16 v[114:117], v[186:189], v[196:199], v[114:117]
	v_mfma_f32_16x16x32_bf16 v[102:105], v[178:181], v[206:209], v[102:105]
	v_mfma_f32_16x16x32_bf16 v[98:101], v[186:189], v[206:209], v[98:101]
	v_mfma_f32_16x16x32_bf16 v[86:89], v[178:181], v[214:217], v[86:89]
	v_mfma_f32_16x16x32_bf16 v[82:85], v[186:189], v[214:217], v[82:85]
	v_mfma_f32_16x16x32_bf16 v[70:73], v[178:181], v[222:225], v[70:73]
	v_mfma_f32_16x16x32_bf16 v[66:69], v[186:189], v[222:225], v[66:69]
	s_setprio 0
	s_barrier
	s_add_i32 s83, s73, s64
	v_lshl_add_u64 v[156:157], s[48:49], 0, v[134:135]
	s_mov_b32 m0, s83
	ds_read_b128 v[190:193], v161 offset:16384
	ds_read_b128 v[196:199], v161 offset:17408
	ds_read_b128 v[200:203], v161 offset:18432
	ds_read_b128 v[206:209], v161 offset:19456
	ds_read_b128 v[210:213], v161 offset:20480
	ds_read_b128 v[214:217], v161 offset:21504
	ds_read_b128 v[218:221], v161 offset:22528
	ds_read_b128 v[222:225], v161 offset:23552
	global_load_lds_dwordx4 v[156:157], off
	s_add_i32 m0, s83, 0x2000
	s_add_u32 s84, s48, 0x20000
	v_lshl_add_u64 v[226:227], s[48:49], 0, v[138:139]
	s_addc_u32 s85, s49, 0
	s_add_i32 s83, s74, s64
	global_load_lds_dwordx4 v[226:227], off
	v_lshl_add_u64 v[228:229], s[84:85], 0, v[134:135]
	s_mov_b32 m0, s83
	v_lshl_add_u64 v[230:231], s[62:63], 0, v[136:137]
	global_load_lds_dwordx4 v[228:229], off
	v_lshl_add_u64 v[228:229], s[84:85], 0, v[138:139]
	s_add_i32 m0, s83, 0x2000
	s_nop 0
	global_load_lds_dwordx4 v[228:229], off
	v_lshl_add_u64 v[228:229], s[62:63], 0, v[132:133]
	s_mov_b32 m0, s57
	s_nop 0
	global_load_lds_dwordx4 v[228:229], off
	s_mov_b32 m0, s59
	s_nop 0
	global_load_lds_dwordx4 v[230:231], off
	s_waitcnt vmcnt(8)
	s_waitcnt lgkmcnt(0)
	s_setprio 1
	s_barrier
	v_mfma_f32_16x16x32_bf16 v[62:65], v[152:155], v[190:193], v[62:65]
	v_mfma_f32_16x16x32_bf16 v[58:61], v[166:169], v[190:193], v[58:61]
	v_mfma_f32_16x16x32_bf16 v[46:49], v[152:155], v[200:203], v[46:49]
	v_mfma_f32_16x16x32_bf16 v[42:45], v[166:169], v[200:203], v[42:45]
	v_mfma_f32_16x16x32_bf16 v[30:33], v[152:155], v[210:213], v[30:33]
	v_mfma_f32_16x16x32_bf16 v[26:29], v[166:169], v[210:213], v[26:29]
	v_mfma_f32_16x16x32_bf16 v[14:17], v[152:155], v[218:221], v[14:17]
	v_mfma_f32_16x16x32_bf16 v[10:13], v[166:169], v[218:221], v[10:13]
	v_mfma_f32_16x16x32_bf16 v[62:65], v[162:165], v[196:199], v[62:65]
	v_mfma_f32_16x16x32_bf16 v[58:61], v[170:173], v[196:199], v[58:61]
	v_mfma_f32_16x16x32_bf16 v[46:49], v[162:165], v[206:209], v[46:49]
	v_mfma_f32_16x16x32_bf16 v[42:45], v[170:173], v[206:209], v[42:45]
	v_mfma_f32_16x16x32_bf16 v[30:33], v[162:165], v[214:217], v[30:33]
	v_mfma_f32_16x16x32_bf16 v[26:29], v[170:173], v[214:217], v[26:29]
	v_mfma_f32_16x16x32_bf16 v[14:17], v[162:165], v[222:225], v[14:17]
	v_mfma_f32_16x16x32_bf16 v[10:13], v[170:173], v[222:225], v[10:13]
	v_mfma_f32_16x16x32_bf16 v[54:57], v[174:177], v[190:193], v[54:57]
	v_mfma_f32_16x16x32_bf16 v[50:53], v[182:185], v[190:193], v[50:53]
	v_mfma_f32_16x16x32_bf16 v[38:41], v[174:177], v[200:203], v[38:41]
	v_mfma_f32_16x16x32_bf16 v[34:37], v[182:185], v[200:203], v[34:37]
	v_mfma_f32_16x16x32_bf16 v[22:25], v[174:177], v[210:213], v[22:25]
	v_mfma_f32_16x16x32_bf16 v[18:21], v[182:185], v[210:213], v[18:21]
	v_mfma_f32_16x16x32_bf16 v[6:9], v[174:177], v[218:221], v[6:9]
	v_mfma_f32_16x16x32_bf16 v[2:5], v[182:185], v[218:221], v[2:5]
	v_mfma_f32_16x16x32_bf16 v[54:57], v[178:181], v[196:199], v[54:57]
	v_mfma_f32_16x16x32_bf16 v[50:53], v[186:189], v[196:199], v[50:53]
	v_mfma_f32_16x16x32_bf16 v[38:41], v[178:181], v[206:209], v[38:41]
	v_mfma_f32_16x16x32_bf16 v[34:37], v[186:189], v[206:209], v[34:37]
	v_mfma_f32_16x16x32_bf16 v[22:25], v[178:181], v[214:217], v[22:25]
	v_mfma_f32_16x16x32_bf16 v[18:21], v[186:189], v[214:217], v[18:21]
	v_mfma_f32_16x16x32_bf16 v[6:9], v[178:181], v[222:225], v[6:9]
	v_mfma_f32_16x16x32_bf16 v[2:5], v[186:189], v[222:225], v[2:5]
	s_setprio 0
	s_barrier
	s_add_i32 s83, 0, 0x18000
	s_add_i32 s84, 0, 0x1c000
	v_add_u32_e32 v170, s83, v131
	v_add_u32_e32 v186, s84, v131
	ds_read_b128 v[152:155], v170
	ds_read_b128 v[162:165], v170 offset:1024
	ds_read_b128 v[166:169], v170 offset:2048
	ds_read_b128 v[170:173], v170 offset:3072
	ds_read_b128 v[174:177], v186
	ds_read_b128 v[178:181], v186 offset:1024
	ds_read_b128 v[182:185], v186 offset:2048
	ds_read_b128 v[186:189], v186 offset:3072
	s_add_u32 s62, s62, 0x20000
	s_addc_u32 s63, s63, 0
	s_mov_b32 m0, s65
	v_lshl_add_u64 v[232:233], s[62:63], 0, v[132:133]
	ds_read_b128 v[190:193], v161 offset:32768
	ds_read_b128 v[196:199], v161 offset:33792
	ds_read_b128 v[200:203], v161 offset:34816
	ds_read_b128 v[206:209], v161 offset:35840
	ds_read_b128 v[210:213], v161 offset:36864
	ds_read_b128 v[214:217], v161 offset:37888
	ds_read_b128 v[218:221], v161 offset:38912
	ds_read_b128 v[222:225], v161 offset:39936
	global_load_lds_dwordx4 v[232:233], off
	v_lshl_add_u64 v[232:233], s[62:63], 0, v[136:137]
	s_mov_b32 m0, s66
	s_nop 0
	global_load_lds_dwordx4 v[232:233], off
	s_waitcnt vmcnt(8)
	s_waitcnt lgkmcnt(0)
	s_setprio 1
	s_barrier
	v_mfma_f32_16x16x32_bf16 v[126:129], v[152:155], v[190:193], v[126:129]
	v_mfma_f32_16x16x32_bf16 v[122:125], v[166:169], v[190:193], v[122:125]
	v_mfma_f32_16x16x32_bf16 v[110:113], v[152:155], v[200:203], v[110:113]
	v_mfma_f32_16x16x32_bf16 v[106:109], v[166:169], v[200:203], v[106:109]
	v_mfma_f32_16x16x32_bf16 v[94:97], v[152:155], v[210:213], v[94:97]
	v_mfma_f32_16x16x32_bf16 v[90:93], v[166:169], v[210:213], v[90:93]
	v_mfma_f32_16x16x32_bf16 v[78:81], v[152:155], v[218:221], v[78:81]
	v_mfma_f32_16x16x32_bf16 v[74:77], v[166:169], v[218:221], v[74:77]
	v_mfma_f32_16x16x32_bf16 v[126:129], v[162:165], v[196:199], v[126:129]
	v_mfma_f32_16x16x32_bf16 v[122:125], v[170:173], v[196:199], v[122:125]
	v_mfma_f32_16x16x32_bf16 v[110:113], v[162:165], v[206:209], v[110:113]
	v_mfma_f32_16x16x32_bf16 v[106:109], v[170:173], v[206:209], v[106:109]
	v_mfma_f32_16x16x32_bf16 v[94:97], v[162:165], v[214:217], v[94:97]
	v_mfma_f32_16x16x32_bf16 v[90:93], v[170:173], v[214:217], v[90:93]
	v_mfma_f32_16x16x32_bf16 v[78:81], v[162:165], v[222:225], v[78:81]
	v_mfma_f32_16x16x32_bf16 v[74:77], v[170:173], v[222:225], v[74:77]
	v_mfma_f32_16x16x32_bf16 v[118:121], v[174:177], v[190:193], v[118:121]
	v_mfma_f32_16x16x32_bf16 v[114:117], v[182:185], v[190:193], v[114:117]
	v_mfma_f32_16x16x32_bf16 v[102:105], v[174:177], v[200:203], v[102:105]
	v_mfma_f32_16x16x32_bf16 v[98:101], v[182:185], v[200:203], v[98:101]
	v_mfma_f32_16x16x32_bf16 v[86:89], v[174:177], v[210:213], v[86:89]
	v_mfma_f32_16x16x32_bf16 v[82:85], v[182:185], v[210:213], v[82:85]
	v_mfma_f32_16x16x32_bf16 v[70:73], v[174:177], v[218:221], v[70:73]
	v_mfma_f32_16x16x32_bf16 v[66:69], v[182:185], v[218:221], v[66:69]
	v_mfma_f32_16x16x32_bf16 v[118:121], v[178:181], v[196:199], v[118:121]
	v_mfma_f32_16x16x32_bf16 v[114:117], v[186:189], v[196:199], v[114:117]
	v_mfma_f32_16x16x32_bf16 v[102:105], v[178:181], v[206:209], v[102:105]
	v_mfma_f32_16x16x32_bf16 v[98:101], v[186:189], v[206:209], v[98:101]
	v_mfma_f32_16x16x32_bf16 v[86:89], v[178:181], v[214:217], v[86:89]
	v_mfma_f32_16x16x32_bf16 v[82:85], v[186:189], v[214:217], v[82:85]
	v_mfma_f32_16x16x32_bf16 v[70:73], v[178:181], v[222:225], v[70:73]
	v_mfma_f32_16x16x32_bf16 v[66:69], v[186:189], v[222:225], v[66:69]
	s_setprio 0
	s_barrier
	s_add_i32 s62, s83, s64
	v_lshl_add_u64 v[156:157], v[156:157], 0, s[18:19]
	s_mov_b32 m0, s62
	ds_read_b128 v[190:193], v161 offset:49152
	ds_read_b128 v[196:199], v161 offset:50176
	ds_read_b128 v[200:203], v161 offset:51200
	ds_read_b128 v[206:209], v161 offset:52224
	ds_read_b128 v[210:213], v161 offset:53248
	ds_read_b128 v[214:217], v161 offset:54272
	ds_read_b128 v[218:221], v161 offset:55296
	ds_read_b128 v[222:225], v161 offset:56320
	global_load_lds_dwordx4 v[156:157], off
	s_add_i32 m0, s62, 0x2000
	s_add_u32 s48, s48, 0x20080
	v_lshl_add_u64 v[156:157], v[226:227], 0, s[18:19]
	s_addc_u32 s49, s49, 0
	s_add_i32 s62, s84, s64
	global_load_lds_dwordx4 v[156:157], off
	v_lshl_add_u64 v[156:157], s[48:49], 0, v[134:135]
	s_mov_b32 m0, s62
	s_nop 0
	global_load_lds_dwordx4 v[156:157], off
	v_lshl_add_u64 v[156:157], s[48:49], 0, v[138:139]
	s_add_i32 m0, s62, 0x2000
	s_nop 0
	global_load_lds_dwordx4 v[156:157], off
	v_lshl_add_u64 v[156:157], v[228:229], 0, s[18:19]
	s_mov_b32 m0, s70
	s_nop 0
	global_load_lds_dwordx4 v[156:157], off
	v_lshl_add_u64 v[156:157], v[230:231], 0, s[18:19]
	s_mov_b32 m0, s71
	s_nop 0
	global_load_lds_dwordx4 v[156:157], off
	s_nop 0
	s_waitcnt vmcnt(8)
	s_waitcnt lgkmcnt(0)
	s_setprio 1
	s_barrier
	v_mfma_f32_16x16x32_bf16 v[62:65], v[152:155], v[190:193], v[62:65]
	v_mfma_f32_16x16x32_bf16 v[58:61], v[166:169], v[190:193], v[58:61]
	v_mfma_f32_16x16x32_bf16 v[46:49], v[152:155], v[200:203], v[46:49]
	v_mfma_f32_16x16x32_bf16 v[42:45], v[166:169], v[200:203], v[42:45]
	v_mfma_f32_16x16x32_bf16 v[30:33], v[152:155], v[210:213], v[30:33]
	v_mfma_f32_16x16x32_bf16 v[26:29], v[166:169], v[210:213], v[26:29]
	v_mfma_f32_16x16x32_bf16 v[14:17], v[152:155], v[218:221], v[14:17]
	v_mfma_f32_16x16x32_bf16 v[10:13], v[166:169], v[218:221], v[10:13]
	v_mfma_f32_16x16x32_bf16 v[62:65], v[162:165], v[196:199], v[62:65]
	v_mfma_f32_16x16x32_bf16 v[58:61], v[170:173], v[196:199], v[58:61]
	v_mfma_f32_16x16x32_bf16 v[46:49], v[162:165], v[206:209], v[46:49]
	v_mfma_f32_16x16x32_bf16 v[42:45], v[170:173], v[206:209], v[42:45]
	v_mfma_f32_16x16x32_bf16 v[30:33], v[162:165], v[214:217], v[30:33]
	v_mfma_f32_16x16x32_bf16 v[26:29], v[170:173], v[214:217], v[26:29]
	v_mfma_f32_16x16x32_bf16 v[14:17], v[162:165], v[222:225], v[14:17]
	v_mfma_f32_16x16x32_bf16 v[10:13], v[170:173], v[222:225], v[10:13]
	v_mfma_f32_16x16x32_bf16 v[54:57], v[174:177], v[190:193], v[54:57]
	v_mfma_f32_16x16x32_bf16 v[50:53], v[182:185], v[190:193], v[50:53]
	v_mfma_f32_16x16x32_bf16 v[38:41], v[174:177], v[200:203], v[38:41]
	v_mfma_f32_16x16x32_bf16 v[34:37], v[182:185], v[200:203], v[34:37]
	v_mfma_f32_16x16x32_bf16 v[22:25], v[174:177], v[210:213], v[22:25]
	v_mfma_f32_16x16x32_bf16 v[18:21], v[182:185], v[210:213], v[18:21]
	v_mfma_f32_16x16x32_bf16 v[6:9], v[174:177], v[218:221], v[6:9]
	v_mfma_f32_16x16x32_bf16 v[2:5], v[182:185], v[218:221], v[2:5]
	v_mfma_f32_16x16x32_bf16 v[54:57], v[178:181], v[196:199], v[54:57]
	v_mfma_f32_16x16x32_bf16 v[50:53], v[186:189], v[196:199], v[50:53]
	v_mfma_f32_16x16x32_bf16 v[38:41], v[178:181], v[206:209], v[38:41]
	v_mfma_f32_16x16x32_bf16 v[34:37], v[186:189], v[206:209], v[34:37]
	v_mfma_f32_16x16x32_bf16 v[22:25], v[178:181], v[214:217], v[22:25]
	v_mfma_f32_16x16x32_bf16 v[18:21], v[186:189], v[214:217], v[18:21]
	v_mfma_f32_16x16x32_bf16 v[6:9], v[178:181], v[222:225], v[6:9]
	v_mfma_f32_16x16x32_bf16 v[2:5], v[186:189], v[222:225], v[2:5]
	s_setprio 0
	s_barrier
	s_add_u32 s60, s60, 0x100
	s_addc_u32 s61, s61, 0
	s_add_u32 s51, s51, 0x100
	s_addc_u32 s53, s53, 0
	s_cmp_ge_i32 s82, s81
	s_mov_b32 s48, s82
	s_cbranch_scc0 .LBB0_1391
	s_and_b64 vcc, exec, s[20:21]
	s_cbranch_vccz .LBB0_1394
	s_barrier

.LBB0_1553:
	ds_read_b128 v[156:159], v161
	ds_read_b128 v[164:167], v161 offset:1024
	ds_read_b128 v[168:171], v161 offset:2048
	ds_read_b128 v[172:175], v161 offset:3072
	ds_read_b128 v[176:179], v162
	ds_read_b128 v[180:183], v162 offset:1024
	ds_read_b128 v[184:187], v162 offset:2048
	ds_read_b128 v[188:191], v162 offset:3072
	s_add_i32 s76, s48, 2
	s_add_u32 s49, s46, 0xfff00080
	s_addc_u32 s50, s47, -1
	s_cmp_eq_u32 s73, s48
	s_cselect_b32 s48, s29, s74
	s_cselect_b32 s51, s9, s50
	s_cselect_b32 s50, s27, s49
	s_cselect_b32 s49, s25, s75
	v_lshl_add_u64 v[192:193], s[46:47], 0, v[148:149]
	s_add_i32 m0, s43, 0xc000
	ds_read_b128 v[196:199], v163
	ds_read_b128 v[200:203], v163 offset:1024
	ds_read_b128 v[206:209], v163 offset:2048
	ds_read_b128 v[210:213], v163 offset:3072
	ds_read_b128 v[214:217], v163 offset:4096
	ds_read_b128 v[218:221], v163 offset:5120
	ds_read_b128 v[222:225], v163 offset:6144
	ds_read_b128 v[226:229], v163 offset:7168
	global_load_lds_dwordx4 v[192:193], off
	v_lshl_add_u64 v[192:193], s[46:47], 0, v[150:151]
	s_add_i32 m0, s43, 0xe000
	s_nop 0
	global_load_lds_dwordx4 v[192:193], off
	s_nop 0
	s_waitcnt vmcnt(8)
	s_waitcnt lgkmcnt(0)
	s_setprio 1
	s_barrier
	v_mfma_f32_16x16x32_bf16 v[78:81], v[156:159], v[196:199], v[78:81]
	v_mfma_f32_16x16x32_bf16 v[74:77], v[168:171], v[196:199], v[74:77]
	v_mfma_f32_16x16x32_bf16 v[70:73], v[156:159], v[206:209], v[70:73]
	v_mfma_f32_16x16x32_bf16 v[62:65], v[168:171], v[206:209], v[62:65]
	v_mfma_f32_16x16x32_bf16 v[58:61], v[156:159], v[214:217], v[58:61]
	v_mfma_f32_16x16x32_bf16 v[54:57], v[168:171], v[214:217], v[54:57]
	v_mfma_f32_16x16x32_bf16 v[46:49], v[156:159], v[222:225], v[46:49]
	v_mfma_f32_16x16x32_bf16 v[38:41], v[168:171], v[222:225], v[38:41]
	v_mfma_f32_16x16x32_bf16 v[78:81], v[164:167], v[200:203], v[78:81]
	v_mfma_f32_16x16x32_bf16 v[74:77], v[172:175], v[200:203], v[74:77]
	v_mfma_f32_16x16x32_bf16 v[70:73], v[164:167], v[210:213], v[70:73]
	v_mfma_f32_16x16x32_bf16 v[62:65], v[172:175], v[210:213], v[62:65]
	v_mfma_f32_16x16x32_bf16 v[58:61], v[164:167], v[218:221], v[58:61]
	v_mfma_f32_16x16x32_bf16 v[54:57], v[172:175], v[218:221], v[54:57]
	v_mfma_f32_16x16x32_bf16 v[46:49], v[164:167], v[226:229], v[46:49]
	v_mfma_f32_16x16x32_bf16 v[38:41], v[172:175], v[226:229], v[38:41]
	v_mfma_f32_16x16x32_bf16 v[50:53], v[176:179], v[196:199], v[50:53]
	v_mfma_f32_16x16x32_bf16 v[42:45], v[184:187], v[196:199], v[42:45]
	v_mfma_f32_16x16x32_bf16 v[34:37], v[176:179], v[206:209], v[34:37]
	v_mfma_f32_16x16x32_bf16 v[26:29], v[184:187], v[206:209], v[26:29]
	v_mfma_f32_16x16x32_bf16 v[18:21], v[176:179], v[214:217], v[18:21]
	v_mfma_f32_16x16x32_bf16 v[14:17], v[184:187], v[214:217], v[14:17]
	v_mfma_f32_16x16x32_bf16 v[10:13], v[176:179], v[222:225], v[10:13]
	v_mfma_f32_16x16x32_bf16 v[6:9], v[184:187], v[222:225], v[6:9]
	v_mfma_f32_16x16x32_bf16 v[50:53], v[180:183], v[200:203], v[50:53]
	v_mfma_f32_16x16x32_bf16 v[42:45], v[188:191], v[200:203], v[42:45]
	v_mfma_f32_16x16x32_bf16 v[34:37], v[180:183], v[210:213], v[34:37]
	v_mfma_f32_16x16x32_bf16 v[26:29], v[188:191], v[210:213], v[26:29]
	v_mfma_f32_16x16x32_bf16 v[18:21], v[180:183], v[218:221], v[18:21]
	v_mfma_f32_16x16x32_bf16 v[14:17], v[188:191], v[218:221], v[14:17]
	v_mfma_f32_16x16x32_bf16 v[10:13], v[180:183], v[226:229], v[10:13]
	v_mfma_f32_16x16x32_bf16 v[6:9], v[188:191], v[226:229], v[6:9]
	s_setprio 0
	s_barrier
	s_add_i32 s77, s66, s53
	v_lshl_add_u64 v[192:193], s[48:49], 0, v[134:135]
	s_mov_b32 m0, s77
	ds_read_b128 v[196:199], v163 offset:16384
	ds_read_b128 v[200:203], v163 offset:17408
	ds_read_b128 v[206:209], v163 offset:18432
	ds_read_b128 v[210:213], v163 offset:19456
	ds_read_b128 v[214:217], v163 offset:20480
	ds_read_b128 v[218:221], v163 offset:21504
	ds_read_b128 v[222:225], v163 offset:22528
	ds_read_b128 v[226:229], v163 offset:23552
	global_load_lds_dwordx4 v[192:193], off
	s_add_i32 m0, s77, 0x2000
	s_add_u32 s78, s48, 0x100000
	v_lshl_add_u64 v[230:231], s[48:49], 0, v[138:139]
	s_addc_u32 s79, s49, 0
	s_add_i32 s77, s67, s53
	global_load_lds_dwordx4 v[230:231], off
	v_lshl_add_u64 v[232:233], s[78:79], 0, v[134:135]
	s_mov_b32 m0, s77
	v_lshl_add_u64 v[234:235], s[50:51], 0, v[136:137]
	global_load_lds_dwordx4 v[232:233], off
	v_lshl_add_u64 v[232:233], s[78:79], 0, v[138:139]
	s_add_i32 m0, s77, 0x2000
	s_nop 0
	global_load_lds_dwordx4 v[232:233], off
	v_lshl_add_u64 v[232:233], s[50:51], 0, v[132:133]
	s_mov_b32 m0, s43
	s_nop 0
	global_load_lds_dwordx4 v[232:233], off
	s_mov_b32 m0, s54
	s_nop 0
	global_load_lds_dwordx4 v[234:235], off
	s_waitcnt vmcnt(8)
	s_waitcnt lgkmcnt(0)
	s_setprio 1
	s_barrier
	v_mfma_f32_16x16x32_bf16 v[126:129], v[156:159], v[196:199], v[126:129]
	v_mfma_f32_16x16x32_bf16 v[118:121], v[168:171], v[196:199], v[118:121]
	v_mfma_f32_16x16x32_bf16 v[110:113], v[156:159], v[206:209], v[110:113]
	v_mfma_f32_16x16x32_bf16 v[102:105], v[168:171], v[206:209], v[102:105]
	v_mfma_f32_16x16x32_bf16 v[94:97], v[156:159], v[214:217], v[94:97]
	v_mfma_f32_16x16x32_bf16 v[86:89], v[168:171], v[214:217], v[86:89]
	v_mfma_f32_16x16x32_bf16 v[66:69], v[156:159], v[222:225], v[66:69]
	v_mfma_f32_16x16x32_bf16 v[22:25], v[168:171], v[222:225], v[22:25]
	v_mfma_f32_16x16x32_bf16 v[126:129], v[164:167], v[200:203], v[126:129]
	v_mfma_f32_16x16x32_bf16 v[118:121], v[172:175], v[200:203], v[118:121]
	v_mfma_f32_16x16x32_bf16 v[110:113], v[164:167], v[210:213], v[110:113]
	v_mfma_f32_16x16x32_bf16 v[102:105], v[172:175], v[210:213], v[102:105]
	v_mfma_f32_16x16x32_bf16 v[94:97], v[164:167], v[218:221], v[94:97]
	v_mfma_f32_16x16x32_bf16 v[86:89], v[172:175], v[218:221], v[86:89]
	v_mfma_f32_16x16x32_bf16 v[66:69], v[164:167], v[226:229], v[66:69]
	v_mfma_f32_16x16x32_bf16 v[22:25], v[172:175], v[226:229], v[22:25]
	v_mfma_f32_16x16x32_bf16 v[122:125], v[176:179], v[196:199], v[122:125]
	v_mfma_f32_16x16x32_bf16 v[114:117], v[184:187], v[196:199], v[114:117]
	v_mfma_f32_16x16x32_bf16 v[106:109], v[176:179], v[206:209], v[106:109]
	v_mfma_f32_16x16x32_bf16 v[98:101], v[184:187], v[206:209], v[98:101]
	v_mfma_f32_16x16x32_bf16 v[90:93], v[176:179], v[214:217], v[90:93]
	v_mfma_f32_16x16x32_bf16 v[82:85], v[184:187], v[214:217], v[82:85]
	v_mfma_f32_16x16x32_bf16 v[30:33], v[176:179], v[222:225], v[30:33]
	v_mfma_f32_16x16x32_bf16 v[2:5], v[184:187], v[222:225], v[2:5]
	v_mfma_f32_16x16x32_bf16 v[122:125], v[180:183], v[200:203], v[122:125]
	v_mfma_f32_16x16x32_bf16 v[114:117], v[188:191], v[200:203], v[114:117]
	v_mfma_f32_16x16x32_bf16 v[106:109], v[180:183], v[210:213], v[106:109]
	v_mfma_f32_16x16x32_bf16 v[98:101], v[188:191], v[210:213], v[98:101]
	v_mfma_f32_16x16x32_bf16 v[90:93], v[180:183], v[218:221], v[90:93]
	v_mfma_f32_16x16x32_bf16 v[82:85], v[188:191], v[218:221], v[82:85]
	v_mfma_f32_16x16x32_bf16 v[30:33], v[180:183], v[226:229], v[30:33]
	v_mfma_f32_16x16x32_bf16 v[2:5], v[188:191], v[226:229], v[2:5]
	s_setprio 0
	s_barrier
	s_add_i32 s77, 0, 0x18000
	s_add_i32 s78, 0, 0x1c000
	v_add_u32_e32 v172, s77, v131
	v_add_u32_e32 v188, s78, v131
	ds_read_b128 v[156:159], v172
	ds_read_b128 v[164:167], v172 offset:1024
	ds_read_b128 v[168:171], v172 offset:2048
	ds_read_b128 v[172:175], v172 offset:3072
	ds_read_b128 v[176:179], v188
	ds_read_b128 v[180:183], v188 offset:1024
	ds_read_b128 v[184:187], v188 offset:2048
	ds_read_b128 v[188:191], v188 offset:3072
	s_add_u32 s50, s50, 0x100000
	s_addc_u32 s51, s51, 0
	s_mov_b32 m0, s55
	v_lshl_add_u64 v[236:237], s[50:51], 0, v[132:133]
	ds_read_b128 v[196:199], v163 offset:32768
	ds_read_b128 v[200:203], v163 offset:33792
	ds_read_b128 v[206:209], v163 offset:34816
	ds_read_b128 v[210:213], v163 offset:35840
	ds_read_b128 v[214:217], v163 offset:36864
	ds_read_b128 v[218:221], v163 offset:37888
	ds_read_b128 v[222:225], v163 offset:38912
	ds_read_b128 v[226:229], v163 offset:39936
	global_load_lds_dwordx4 v[236:237], off
	v_lshl_add_u64 v[236:237], s[50:51], 0, v[136:137]
	s_mov_b32 m0, s56
	s_nop 0
	global_load_lds_dwordx4 v[236:237], off
	s_waitcnt vmcnt(8)
	s_waitcnt lgkmcnt(0)
	s_setprio 1
	s_barrier
	v_mfma_f32_16x16x32_bf16 v[78:81], v[156:159], v[196:199], v[78:81]
	v_mfma_f32_16x16x32_bf16 v[74:77], v[168:171], v[196:199], v[74:77]
	v_mfma_f32_16x16x32_bf16 v[70:73], v[156:159], v[206:209], v[70:73]
	v_mfma_f32_16x16x32_bf16 v[62:65], v[168:171], v[206:209], v[62:65]
	v_mfma_f32_16x16x32_bf16 v[58:61], v[156:159], v[214:217], v[58:61]
	v_mfma_f32_16x16x32_bf16 v[54:57], v[168:171], v[214:217], v[54:57]
	v_mfma_f32_16x16x32_bf16 v[46:49], v[156:159], v[222:225], v[46:49]
	v_mfma_f32_16x16x32_bf16 v[38:41], v[168:171], v[222:225], v[38:41]
	v_mfma_f32_16x16x32_bf16 v[78:81], v[164:167], v[200:203], v[78:81]
	v_mfma_f32_16x16x32_bf16 v[74:77], v[172:175], v[200:203], v[74:77]
	v_mfma_f32_16x16x32_bf16 v[70:73], v[164:167], v[210:213], v[70:73]
	v_mfma_f32_16x16x32_bf16 v[62:65], v[172:175], v[210:213], v[62:65]
	v_mfma_f32_16x16x32_bf16 v[58:61], v[164:167], v[218:221], v[58:61]
	v_mfma_f32_16x16x32_bf16 v[54:57], v[172:175], v[218:221], v[54:57]
	v_mfma_f32_16x16x32_bf16 v[46:49], v[164:167], v[226:229], v[46:49]
	v_mfma_f32_16x16x32_bf16 v[38:41], v[172:175], v[226:229], v[38:41]
	v_mfma_f32_16x16x32_bf16 v[50:53], v[176:179], v[196:199], v[50:53]
	v_mfma_f32_16x16x32_bf16 v[42:45], v[184:187], v[196:199], v[42:45]
	v_mfma_f32_16x16x32_bf16 v[34:37], v[176:179], v[206:209], v[34:37]
	v_mfma_f32_16x16x32_bf16 v[26:29], v[184:187], v[206:209], v[26:29]
	v_mfma_f32_16x16x32_bf16 v[18:21], v[176:179], v[214:217], v[18:21]
	v_mfma_f32_16x16x32_bf16 v[14:17], v[184:187], v[214:217], v[14:17]
	v_mfma_f32_16x16x32_bf16 v[10:13], v[176:179], v[222:225], v[10:13]
	v_mfma_f32_16x16x32_bf16 v[6:9], v[184:187], v[222:225], v[6:9]
	v_mfma_f32_16x16x32_bf16 v[50:53], v[180:183], v[200:203], v[50:53]
	v_mfma_f32_16x16x32_bf16 v[42:45], v[188:191], v[200:203], v[42:45]
	v_mfma_f32_16x16x32_bf16 v[34:37], v[180:183], v[210:213], v[34:37]
	v_mfma_f32_16x16x32_bf16 v[26:29], v[188:191], v[210:213], v[26:29]
	v_mfma_f32_16x16x32_bf16 v[18:21], v[180:183], v[218:221], v[18:21]
	v_mfma_f32_16x16x32_bf16 v[14:17], v[188:191], v[218:221], v[14:17]
	v_mfma_f32_16x16x32_bf16 v[10:13], v[180:183], v[226:229], v[10:13]
	v_mfma_f32_16x16x32_bf16 v[6:9], v[188:191], v[226:229], v[6:9]
	s_setprio 0
	s_barrier
	s_add_i32 s50, s77, s53
	v_lshl_add_u64 v[192:193], v[192:193], 0, s[14:15]
	s_mov_b32 m0, s50
	ds_read_b128 v[196:199], v163 offset:49152
	ds_read_b128 v[200:203], v163 offset:50176
	ds_read_b128 v[206:209], v163 offset:51200
	ds_read_b128 v[210:213], v163 offset:52224
	ds_read_b128 v[214:217], v163 offset:53248
	ds_read_b128 v[218:221], v163 offset:54272
	ds_read_b128 v[222:225], v163 offset:55296
	ds_read_b128 v[226:229], v163 offset:56320
	global_load_lds_dwordx4 v[192:193], off
	s_add_i32 m0, s50, 0x2000
	s_add_u32 s48, s48, 0x100080
	v_lshl_add_u64 v[192:193], v[230:231], 0, s[14:15]
	s_addc_u32 s49, s49, 0
	s_add_i32 s50, s78, s53
	global_load_lds_dwordx4 v[192:193], off
	v_lshl_add_u64 v[192:193], s[48:49], 0, v[134:135]
	s_mov_b32 m0, s50
	s_nop 0
	global_load_lds_dwordx4 v[192:193], off
	v_lshl_add_u64 v[192:193], s[48:49], 0, v[138:139]
	s_add_i32 m0, s50, 0x2000
	s_nop 0
	global_load_lds_dwordx4 v[192:193], off
	v_lshl_add_u64 v[192:193], v[232:233], 0, s[14:15]
	s_mov_b32 m0, s59
	s_nop 0
	global_load_lds_dwordx4 v[192:193], off
	v_lshl_add_u64 v[192:193], v[234:235], 0, s[14:15]
	s_mov_b32 m0, s60
	s_nop 0
	global_load_lds_dwordx4 v[192:193], off
	s_nop 0
	s_waitcnt vmcnt(8)
	s_waitcnt lgkmcnt(0)
	s_setprio 1
	s_barrier
	v_mfma_f32_16x16x32_bf16 v[126:129], v[156:159], v[196:199], v[126:129]
	v_mfma_f32_16x16x32_bf16 v[118:121], v[168:171], v[196:199], v[118:121]
	v_mfma_f32_16x16x32_bf16 v[110:113], v[156:159], v[206:209], v[110:113]
	v_mfma_f32_16x16x32_bf16 v[102:105], v[168:171], v[206:209], v[102:105]
	v_mfma_f32_16x16x32_bf16 v[94:97], v[156:159], v[214:217], v[94:97]
	v_mfma_f32_16x16x32_bf16 v[86:89], v[168:171], v[214:217], v[86:89]
	v_mfma_f32_16x16x32_bf16 v[66:69], v[156:159], v[222:225], v[66:69]
	v_mfma_f32_16x16x32_bf16 v[22:25], v[168:171], v[222:225], v[22:25]
	v_mfma_f32_16x16x32_bf16 v[126:129], v[164:167], v[200:203], v[126:129]
	v_mfma_f32_16x16x32_bf16 v[118:121], v[172:175], v[200:203], v[118:121]
	v_mfma_f32_16x16x32_bf16 v[110:113], v[164:167], v[210:213], v[110:113]
	v_mfma_f32_16x16x32_bf16 v[102:105], v[172:175], v[210:213], v[102:105]
	v_mfma_f32_16x16x32_bf16 v[94:97], v[164:167], v[218:221], v[94:97]
	v_mfma_f32_16x16x32_bf16 v[86:89], v[172:175], v[218:221], v[86:89]
	v_mfma_f32_16x16x32_bf16 v[66:69], v[164:167], v[226:229], v[66:69]
	v_mfma_f32_16x16x32_bf16 v[22:25], v[172:175], v[226:229], v[22:25]
	v_mfma_f32_16x16x32_bf16 v[122:125], v[176:179], v[196:199], v[122:125]
	v_mfma_f32_16x16x32_bf16 v[114:117], v[184:187], v[196:199], v[114:117]
	v_mfma_f32_16x16x32_bf16 v[106:109], v[176:179], v[206:209], v[106:109]
	v_mfma_f32_16x16x32_bf16 v[98:101], v[184:187], v[206:209], v[98:101]
	v_mfma_f32_16x16x32_bf16 v[90:93], v[176:179], v[214:217], v[90:93]
	v_mfma_f32_16x16x32_bf16 v[82:85], v[184:187], v[214:217], v[82:85]
	v_mfma_f32_16x16x32_bf16 v[30:33], v[176:179], v[222:225], v[30:33]
	v_mfma_f32_16x16x32_bf16 v[2:5], v[184:187], v[222:225], v[2:5]
	v_mfma_f32_16x16x32_bf16 v[122:125], v[180:183], v[200:203], v[122:125]
	v_mfma_f32_16x16x32_bf16 v[114:117], v[188:191], v[200:203], v[114:117]
	v_mfma_f32_16x16x32_bf16 v[106:109], v[180:183], v[210:213], v[106:109]
	v_mfma_f32_16x16x32_bf16 v[98:101], v[188:191], v[210:213], v[98:101]
	v_mfma_f32_16x16x32_bf16 v[90:93], v[180:183], v[218:221], v[90:93]
	v_mfma_f32_16x16x32_bf16 v[82:85], v[188:191], v[218:221], v[82:85]
	v_mfma_f32_16x16x32_bf16 v[30:33], v[180:183], v[226:229], v[30:33]
	v_mfma_f32_16x16x32_bf16 v[2:5], v[188:191], v[226:229], v[2:5]
	s_setprio 0
	s_barrier
	s_add_u32 s46, s46, 0x100
	s_addc_u32 s47, s47, 0
	s_add_u32 s74, s74, 0x100
	s_addc_u32 s75, s75, 0
	s_cmp_ge_i32 s76, s72
	s_mov_b32 s48, s76
	s_cbranch_scc0 .LBB0_1553
	s_and_b64 vcc, exec, s[16:17]
	s_cbranch_vccz .LBB0_1558
	s_barrier
	s_cmp_lt_i32 s52, 0
	s_mov_b64 s[46:47], -1
	s_cbranch_scc1 .LBB0_1559

.LBB0_1712:
	ds_read_b128 v[152:155], v160
	ds_read_b128 v[164:167], v160 offset:1024
	ds_read_b128 v[168:171], v160 offset:2048
	ds_read_b128 v[172:175], v160 offset:3072
	ds_read_b128 v[176:179], v161
	ds_read_b128 v[180:183], v161 offset:1024
	ds_read_b128 v[184:187], v161 offset:2048
	ds_read_b128 v[188:191], v161 offset:3072
	s_add_i32 s82, s48, 2
	s_add_u32 s49, s52, 0xffd50080
	s_addc_u32 s54, s53, -1
	s_cmp_eq_u32 s47, s48
	s_cselect_b32 s48, s50, s80
	s_cselect_b32 s55, s9, s54
	s_cselect_b32 s54, s8, s49
	s_cselect_b32 s49, s51, s81
	v_lshl_add_u64 v[156:157], s[52:53], 0, v[140:141]
	s_add_i32 m0, s57, 0xc000
	ds_read_b128 v[196:199], v162
	ds_read_b128 v[200:203], v162 offset:1024
	ds_read_b128 v[206:209], v162 offset:2048
	ds_read_b128 v[210:213], v162 offset:3072
	ds_read_b128 v[214:217], v162 offset:4096
	ds_read_b128 v[218:221], v162 offset:5120
	ds_read_b128 v[222:225], v162 offset:6144
	ds_read_b128 v[226:229], v162 offset:7168
	global_load_lds_dwordx4 v[156:157], off
	v_lshl_add_u64 v[156:157], s[52:53], 0, v[142:143]
	s_add_i32 m0, s57, 0xe000
	s_nop 0
	global_load_lds_dwordx4 v[156:157], off
	s_waitcnt vmcnt(8)
	s_waitcnt lgkmcnt(0)
	s_setprio 1
	s_barrier
	v_mfma_f32_16x16x32_bf16 v[126:129], v[152:155], v[196:199], v[126:129]
	v_mfma_f32_16x16x32_bf16 v[122:125], v[168:171], v[196:199], v[122:125]
	v_mfma_f32_16x16x32_bf16 v[110:113], v[152:155], v[206:209], v[110:113]
	v_mfma_f32_16x16x32_bf16 v[106:109], v[168:171], v[206:209], v[106:109]
	v_mfma_f32_16x16x32_bf16 v[94:97], v[152:155], v[214:217], v[94:97]
	v_mfma_f32_16x16x32_bf16 v[90:93], v[168:171], v[214:217], v[90:93]
	v_mfma_f32_16x16x32_bf16 v[78:81], v[152:155], v[222:225], v[78:81]
	v_mfma_f32_16x16x32_bf16 v[74:77], v[168:171], v[222:225], v[74:77]
	v_mfma_f32_16x16x32_bf16 v[126:129], v[164:167], v[200:203], v[126:129]
	v_mfma_f32_16x16x32_bf16 v[122:125], v[172:175], v[200:203], v[122:125]
	v_mfma_f32_16x16x32_bf16 v[110:113], v[164:167], v[210:213], v[110:113]
	v_mfma_f32_16x16x32_bf16 v[106:109], v[172:175], v[210:213], v[106:109]
	v_mfma_f32_16x16x32_bf16 v[94:97], v[164:167], v[218:221], v[94:97]
	v_mfma_f32_16x16x32_bf16 v[90:93], v[172:175], v[218:221], v[90:93]
	v_mfma_f32_16x16x32_bf16 v[78:81], v[164:167], v[226:229], v[78:81]
	v_mfma_f32_16x16x32_bf16 v[74:77], v[172:175], v[226:229], v[74:77]
	v_mfma_f32_16x16x32_bf16 v[118:121], v[176:179], v[196:199], v[118:121]
	v_mfma_f32_16x16x32_bf16 v[114:117], v[184:187], v[196:199], v[114:117]
	v_mfma_f32_16x16x32_bf16 v[102:105], v[176:179], v[206:209], v[102:105]
	v_mfma_f32_16x16x32_bf16 v[98:101], v[184:187], v[206:209], v[98:101]
	v_mfma_f32_16x16x32_bf16 v[86:89], v[176:179], v[214:217], v[86:89]
	v_mfma_f32_16x16x32_bf16 v[82:85], v[184:187], v[214:217], v[82:85]
	v_mfma_f32_16x16x32_bf16 v[70:73], v[176:179], v[222:225], v[70:73]
	v_mfma_f32_16x16x32_bf16 v[66:69], v[184:187], v[222:225], v[66:69]
	v_mfma_f32_16x16x32_bf16 v[118:121], v[180:183], v[200:203], v[118:121]
	v_mfma_f32_16x16x32_bf16 v[114:117], v[188:191], v[200:203], v[114:117]
	v_mfma_f32_16x16x32_bf16 v[102:105], v[180:183], v[210:213], v[102:105]
	v_mfma_f32_16x16x32_bf16 v[98:101], v[188:191], v[210:213], v[98:101]
	v_mfma_f32_16x16x32_bf16 v[86:89], v[180:183], v[218:221], v[86:89]
	v_mfma_f32_16x16x32_bf16 v[82:85], v[188:191], v[218:221], v[82:85]
	v_mfma_f32_16x16x32_bf16 v[70:73], v[180:183], v[226:229], v[70:73]
	v_mfma_f32_16x16x32_bf16 v[66:69], v[188:191], v[226:229], v[66:69]
	s_setprio 0
	s_barrier
	s_add_i32 s83, s67, s56
	v_lshl_add_u64 v[156:157], s[48:49], 0, v[134:135]
	s_mov_b32 m0, s83
	ds_read_b128 v[196:199], v162 offset:16384
	ds_read_b128 v[200:203], v162 offset:17408
	ds_read_b128 v[206:209], v162 offset:18432
	ds_read_b128 v[210:213], v162 offset:19456
	ds_read_b128 v[214:217], v162 offset:20480
	ds_read_b128 v[218:221], v162 offset:21504
	ds_read_b128 v[222:225], v162 offset:22528
	ds_read_b128 v[226:229], v162 offset:23552
	global_load_lds_dwordx4 v[156:157], off
	s_add_i32 m0, s83, 0x2000
	s_add_u32 s84, s48, 0x2b0000
	v_lshl_add_u64 v[192:193], s[48:49], 0, v[138:139]
	s_addc_u32 s85, s49, 0
	s_add_i32 s83, s68, s56
	global_load_lds_dwordx4 v[192:193], off
	v_lshl_add_u64 v[230:231], s[84:85], 0, v[134:135]
	s_mov_b32 m0, s83
	v_lshl_add_u64 v[232:233], s[54:55], 0, v[136:137]
	global_load_lds_dwordx4 v[230:231], off
	v_lshl_add_u64 v[230:231], s[84:85], 0, v[138:139]
	s_add_i32 m0, s83, 0x2000
	s_nop 0
	global_load_lds_dwordx4 v[230:231], off
	v_lshl_add_u64 v[230:231], s[54:55], 0, v[132:133]
	s_mov_b32 m0, s57
	s_nop 0
	global_load_lds_dwordx4 v[230:231], off
	s_mov_b32 m0, s58
	s_nop 0
	global_load_lds_dwordx4 v[232:233], off
	s_waitcnt vmcnt(8)
	s_waitcnt lgkmcnt(0)
	s_setprio 1
	s_barrier
	v_mfma_f32_16x16x32_bf16 v[62:65], v[152:155], v[196:199], v[62:65]
	v_mfma_f32_16x16x32_bf16 v[58:61], v[168:171], v[196:199], v[58:61]
	v_mfma_f32_16x16x32_bf16 v[46:49], v[152:155], v[206:209], v[46:49]
	v_mfma_f32_16x16x32_bf16 v[42:45], v[168:171], v[206:209], v[42:45]
	v_mfma_f32_16x16x32_bf16 v[30:33], v[152:155], v[214:217], v[30:33]
	v_mfma_f32_16x16x32_bf16 v[26:29], v[168:171], v[214:217], v[26:29]
	v_mfma_f32_16x16x32_bf16 v[14:17], v[152:155], v[222:225], v[14:17]
	v_mfma_f32_16x16x32_bf16 v[10:13], v[168:171], v[222:225], v[10:13]
	v_mfma_f32_16x16x32_bf16 v[62:65], v[164:167], v[200:203], v[62:65]
	v_mfma_f32_16x16x32_bf16 v[58:61], v[172:175], v[200:203], v[58:61]
	v_mfma_f32_16x16x32_bf16 v[46:49], v[164:167], v[210:213], v[46:49]
	v_mfma_f32_16x16x32_bf16 v[42:45], v[172:175], v[210:213], v[42:45]
	v_mfma_f32_16x16x32_bf16 v[30:33], v[164:167], v[218:221], v[30:33]
	v_mfma_f32_16x16x32_bf16 v[26:29], v[172:175], v[218:221], v[26:29]
	v_mfma_f32_16x16x32_bf16 v[14:17], v[164:167], v[226:229], v[14:17]
	v_mfma_f32_16x16x32_bf16 v[10:13], v[172:175], v[226:229], v[10:13]
	v_mfma_f32_16x16x32_bf16 v[54:57], v[176:179], v[196:199], v[54:57]
	v_mfma_f32_16x16x32_bf16 v[50:53], v[184:187], v[196:199], v[50:53]
	v_mfma_f32_16x16x32_bf16 v[38:41], v[176:179], v[206:209], v[38:41]
	v_mfma_f32_16x16x32_bf16 v[34:37], v[184:187], v[206:209], v[34:37]
	v_mfma_f32_16x16x32_bf16 v[22:25], v[176:179], v[214:217], v[22:25]
	v_mfma_f32_16x16x32_bf16 v[18:21], v[184:187], v[214:217], v[18:21]
	v_mfma_f32_16x16x32_bf16 v[6:9], v[176:179], v[222:225], v[6:9]
	v_mfma_f32_16x16x32_bf16 v[2:5], v[184:187], v[222:225], v[2:5]
	v_mfma_f32_16x16x32_bf16 v[54:57], v[180:183], v[200:203], v[54:57]
	v_mfma_f32_16x16x32_bf16 v[50:53], v[188:191], v[200:203], v[50:53]
	v_mfma_f32_16x16x32_bf16 v[38:41], v[180:183], v[210:213], v[38:41]
	v_mfma_f32_16x16x32_bf16 v[34:37], v[188:191], v[210:213], v[34:37]
	v_mfma_f32_16x16x32_bf16 v[22:25], v[180:183], v[218:221], v[22:25]
	v_mfma_f32_16x16x32_bf16 v[18:21], v[188:191], v[218:221], v[18:21]
	v_mfma_f32_16x16x32_bf16 v[6:9], v[180:183], v[226:229], v[6:9]
	v_mfma_f32_16x16x32_bf16 v[2:5], v[188:191], v[226:229], v[2:5]
	s_setprio 0
	s_barrier
	s_add_i32 s83, 0, 0x18000
	v_add_u32_e32 v163, s83, v158
	s_add_i32 s84, 0, 0x1c000
	ds_read_b128 v[152:155], v163
	ds_read_b128 v[164:167], v163 offset:1024
	ds_read_b128 v[168:171], v163 offset:2048
	ds_read_b128 v[172:175], v163 offset:3072
	v_add_u32_e32 v163, s84, v158
	ds_read_b128 v[176:179], v163
	ds_read_b128 v[180:183], v163 offset:1024
	ds_read_b128 v[184:187], v163 offset:2048
	ds_read_b128 v[188:191], v163 offset:3072
	s_add_u32 s54, s54, 0x2b0000
	s_addc_u32 s55, s55, 0
	s_mov_b32 m0, s59
	v_lshl_add_u64 v[234:235], s[54:55], 0, v[132:133]
	ds_read_b128 v[196:199], v162 offset:32768
	ds_read_b128 v[200:203], v162 offset:33792
	ds_read_b128 v[206:209], v162 offset:34816
	ds_read_b128 v[210:213], v162 offset:35840
	ds_read_b128 v[214:217], v162 offset:36864
	ds_read_b128 v[218:221], v162 offset:37888
	ds_read_b128 v[222:225], v162 offset:38912
	ds_read_b128 v[226:229], v162 offset:39936
	global_load_lds_dwordx4 v[234:235], off
	v_lshl_add_u64 v[234:235], s[54:55], 0, v[136:137]
	s_mov_b32 m0, s60
	s_nop 0
	global_load_lds_dwordx4 v[234:235], off
	s_waitcnt vmcnt(8)
	s_waitcnt lgkmcnt(0)
	s_setprio 1
	s_barrier
	v_mfma_f32_16x16x32_bf16 v[126:129], v[152:155], v[196:199], v[126:129]
	v_mfma_f32_16x16x32_bf16 v[122:125], v[168:171], v[196:199], v[122:125]
	v_mfma_f32_16x16x32_bf16 v[110:113], v[152:155], v[206:209], v[110:113]
	v_mfma_f32_16x16x32_bf16 v[106:109], v[168:171], v[206:209], v[106:109]
	v_mfma_f32_16x16x32_bf16 v[94:97], v[152:155], v[214:217], v[94:97]
	v_mfma_f32_16x16x32_bf16 v[90:93], v[168:171], v[214:217], v[90:93]
	v_mfma_f32_16x16x32_bf16 v[78:81], v[152:155], v[222:225], v[78:81]
	v_mfma_f32_16x16x32_bf16 v[74:77], v[168:171], v[222:225], v[74:77]
	v_mfma_f32_16x16x32_bf16 v[126:129], v[164:167], v[200:203], v[126:129]
	v_mfma_f32_16x16x32_bf16 v[122:125], v[172:175], v[200:203], v[122:125]
	v_mfma_f32_16x16x32_bf16 v[110:113], v[164:167], v[210:213], v[110:113]
	v_mfma_f32_16x16x32_bf16 v[106:109], v[172:175], v[210:213], v[106:109]
	v_mfma_f32_16x16x32_bf16 v[94:97], v[164:167], v[218:221], v[94:97]
	v_mfma_f32_16x16x32_bf16 v[90:93], v[172:175], v[218:221], v[90:93]
	v_mfma_f32_16x16x32_bf16 v[78:81], v[164:167], v[226:229], v[78:81]
	v_mfma_f32_16x16x32_bf16 v[74:77], v[172:175], v[226:229], v[74:77]
	v_mfma_f32_16x16x32_bf16 v[118:121], v[176:179], v[196:199], v[118:121]
	v_mfma_f32_16x16x32_bf16 v[114:117], v[184:187], v[196:199], v[114:117]
	v_mfma_f32_16x16x32_bf16 v[102:105], v[176:179], v[206:209], v[102:105]
	v_mfma_f32_16x16x32_bf16 v[98:101], v[184:187], v[206:209], v[98:101]
	v_mfma_f32_16x16x32_bf16 v[86:89], v[176:179], v[214:217], v[86:89]
	v_mfma_f32_16x16x32_bf16 v[82:85], v[184:187], v[214:217], v[82:85]
	v_mfma_f32_16x16x32_bf16 v[70:73], v[176:179], v[222:225], v[70:73]
	v_mfma_f32_16x16x32_bf16 v[66:69], v[184:187], v[222:225], v[66:69]
	v_mfma_f32_16x16x32_bf16 v[118:121], v[180:183], v[200:203], v[118:121]
	v_mfma_f32_16x16x32_bf16 v[114:117], v[188:191], v[200:203], v[114:117]
	v_mfma_f32_16x16x32_bf16 v[102:105], v[180:183], v[210:213], v[102:105]
	v_mfma_f32_16x16x32_bf16 v[98:101], v[188:191], v[210:213], v[98:101]
	v_mfma_f32_16x16x32_bf16 v[86:89], v[180:183], v[218:221], v[86:89]
	v_mfma_f32_16x16x32_bf16 v[82:85], v[188:191], v[218:221], v[82:85]
	v_mfma_f32_16x16x32_bf16 v[70:73], v[180:183], v[226:229], v[70:73]
	v_mfma_f32_16x16x32_bf16 v[66:69], v[188:191], v[226:229], v[66:69]
	s_setprio 0
	s_barrier
	s_add_i32 s54, s83, s56
	v_lshl_add_u64 v[156:157], v[156:157], 0, s[18:19]
	s_mov_b32 m0, s54
	ds_read_b128 v[196:199], v162 offset:49152
	ds_read_b128 v[200:203], v162 offset:50176
	ds_read_b128 v[206:209], v162 offset:51200
	ds_read_b128 v[210:213], v162 offset:52224
	ds_read_b128 v[214:217], v162 offset:53248
	ds_read_b128 v[218:221], v162 offset:54272
	ds_read_b128 v[222:225], v162 offset:55296
	ds_read_b128 v[226:229], v162 offset:56320
	global_load_lds_dwordx4 v[156:157], off
	s_add_i32 m0, s54, 0x2000
	s_add_u32 s48, s48, 0x2b0080
	v_lshl_add_u64 v[156:157], v[192:193], 0, s[18:19]
	s_addc_u32 s49, s49, 0
	s_add_i32 s54, s84, s56
	global_load_lds_dwordx4 v[156:157], off
	v_lshl_add_u64 v[156:157], s[48:49], 0, v[134:135]
	s_mov_b32 m0, s54
	s_nop 0
	global_load_lds_dwordx4 v[156:157], off
	v_lshl_add_u64 v[156:157], s[48:49], 0, v[138:139]
	s_add_i32 m0, s54, 0x2000
	s_nop 0
	global_load_lds_dwordx4 v[156:157], off
	v_lshl_add_u64 v[156:157], v[230:231], 0, s[18:19]
	s_mov_b32 m0, s64
	s_nop 0
	global_load_lds_dwordx4 v[156:157], off
	v_lshl_add_u64 v[156:157], v[232:233], 0, s[18:19]
	s_mov_b32 m0, s65
	s_nop 0
	global_load_lds_dwordx4 v[156:157], off
	s_nop 0
	s_waitcnt vmcnt(8)
	s_waitcnt lgkmcnt(0)
	s_setprio 1
	s_barrier
	v_mfma_f32_16x16x32_bf16 v[62:65], v[152:155], v[196:199], v[62:65]
	v_mfma_f32_16x16x32_bf16 v[58:61], v[168:171], v[196:199], v[58:61]
	v_mfma_f32_16x16x32_bf16 v[46:49], v[152:155], v[206:209], v[46:49]
	v_mfma_f32_16x16x32_bf16 v[42:45], v[168:171], v[206:209], v[42:45]
	v_mfma_f32_16x16x32_bf16 v[30:33], v[152:155], v[214:217], v[30:33]
	v_mfma_f32_16x16x32_bf16 v[26:29], v[168:171], v[214:217], v[26:29]
	v_mfma_f32_16x16x32_bf16 v[14:17], v[152:155], v[222:225], v[14:17]
	v_mfma_f32_16x16x32_bf16 v[10:13], v[168:171], v[222:225], v[10:13]
	v_mfma_f32_16x16x32_bf16 v[62:65], v[164:167], v[200:203], v[62:65]
	v_mfma_f32_16x16x32_bf16 v[58:61], v[172:175], v[200:203], v[58:61]
	v_mfma_f32_16x16x32_bf16 v[46:49], v[164:167], v[210:213], v[46:49]
	v_mfma_f32_16x16x32_bf16 v[42:45], v[172:175], v[210:213], v[42:45]
	v_mfma_f32_16x16x32_bf16 v[30:33], v[164:167], v[218:221], v[30:33]
	v_mfma_f32_16x16x32_bf16 v[26:29], v[172:175], v[218:221], v[26:29]
	v_mfma_f32_16x16x32_bf16 v[14:17], v[164:167], v[226:229], v[14:17]
	v_mfma_f32_16x16x32_bf16 v[10:13], v[172:175], v[226:229], v[10:13]
	v_mfma_f32_16x16x32_bf16 v[54:57], v[176:179], v[196:199], v[54:57]
	v_mfma_f32_16x16x32_bf16 v[50:53], v[184:187], v[196:199], v[50:53]
	v_mfma_f32_16x16x32_bf16 v[38:41], v[176:179], v[206:209], v[38:41]
	v_mfma_f32_16x16x32_bf16 v[34:37], v[184:187], v[206:209], v[34:37]
	v_mfma_f32_16x16x32_bf16 v[22:25], v[176:179], v[214:217], v[22:25]
	v_mfma_f32_16x16x32_bf16 v[18:21], v[184:187], v[214:217], v[18:21]
	v_mfma_f32_16x16x32_bf16 v[6:9], v[176:179], v[222:225], v[6:9]
	v_mfma_f32_16x16x32_bf16 v[2:5], v[184:187], v[222:225], v[2:5]
	v_mfma_f32_16x16x32_bf16 v[54:57], v[180:183], v[200:203], v[54:57]
	v_mfma_f32_16x16x32_bf16 v[50:53], v[188:191], v[200:203], v[50:53]
	v_mfma_f32_16x16x32_bf16 v[38:41], v[180:183], v[210:213], v[38:41]
	v_mfma_f32_16x16x32_bf16 v[34:37], v[188:191], v[210:213], v[34:37]
	v_mfma_f32_16x16x32_bf16 v[22:25], v[180:183], v[218:221], v[22:25]
	v_mfma_f32_16x16x32_bf16 v[18:21], v[188:191], v[218:221], v[18:21]
	v_mfma_f32_16x16x32_bf16 v[6:9], v[180:183], v[226:229], v[6:9]
	v_mfma_f32_16x16x32_bf16 v[2:5], v[188:191], v[226:229], v[2:5]
	s_setprio 0
	s_barrier
	s_add_u32 s52, s52, 0x100
	s_addc_u32 s53, s53, 0
	s_add_u32 s80, s80, 0x100
	s_addc_u32 s81, s81, 0
	s_cmp_ge_i32 s82, s78
	s_mov_b32 s48, s82
	s_cbranch_scc0 .LBB0_1712
	s_and_b64 vcc, exec, s[20:21]
	s_cbranch_vccz .LBB0_1715
	s_barrier

.LBB0_1869:
	ds_read_b128 v[162:165], v168
	s_waitcnt vmcnt(0)
	ds_read_b128 v[172:175], v168 offset:1024
	ds_read_b128 v[176:179], v168 offset:2048
	ds_read_b128 v[180:183], v168 offset:3072
	ds_read_b128 v[184:187], v169
	ds_read_b128 v[188:191], v169 offset:1024
	ds_read_b128 v[196:199], v169 offset:2048
	ds_read_b128 v[200:203], v169 offset:3072
	s_add_i32 s55, s42, 2
	s_add_u32 s43, s8, 0xfff00080
	s_addc_u32 s46, s9, -1
	s_cmp_eq_u32 s48, s42
	s_cselect_b32 s42, s41, s49
	s_cselect_b32 s47, s31, s46
	s_cselect_b32 s46, s33, s43
	s_cselect_b32 s43, s35, s53
	v_lshl_add_u64 v[166:167], s[8:9], 0, v[150:151]
	s_add_i32 m0, s62, 0xc000
	ds_read_b128 v[206:209], v170
	ds_read_b128 v[210:213], v170 offset:1024
	ds_read_b128 v[214:217], v170 offset:2048
	ds_read_b128 v[218:221], v170 offset:3072
	ds_read_b128 v[222:225], v170 offset:4096
	ds_read_b128 v[226:229], v170 offset:5120
	ds_read_b128 v[230:233], v170 offset:6144
	ds_read_b128 v[234:237], v170 offset:7168
	global_load_lds_dwordx4 v[166:167], off
	v_lshl_add_u64 v[166:167], s[8:9], 0, v[152:153]
	s_add_i32 m0, s62, 0xe000
	s_nop 0
	global_load_lds_dwordx4 v[166:167], off
	s_waitcnt vmcnt(8)
	s_waitcnt lgkmcnt(0)
	s_setprio 1
	s_barrier
	v_mfma_f32_16x16x32_bf16 v[66:69], v[162:165], v[206:209], v[66:69]
	v_mfma_f32_16x16x32_bf16 v[62:65], v[176:179], v[206:209], v[62:65]
	v_mfma_f32_16x16x32_bf16 v[58:61], v[162:165], v[214:217], v[58:61]
	v_mfma_f32_16x16x32_bf16 v[54:57], v[176:179], v[214:217], v[54:57]
	v_mfma_f32_16x16x32_bf16 v[50:53], v[162:165], v[222:225], v[50:53]
	v_mfma_f32_16x16x32_bf16 v[46:49], v[176:179], v[222:225], v[46:49]
	v_mfma_f32_16x16x32_bf16 v[38:41], v[162:165], v[230:233], v[38:41]
	v_mfma_f32_16x16x32_bf16 v[30:33], v[176:179], v[230:233], v[30:33]
	v_mfma_f32_16x16x32_bf16 v[66:69], v[172:175], v[210:213], v[66:69]
	v_mfma_f32_16x16x32_bf16 v[62:65], v[180:183], v[210:213], v[62:65]
	v_mfma_f32_16x16x32_bf16 v[58:61], v[172:175], v[218:221], v[58:61]
	v_mfma_f32_16x16x32_bf16 v[54:57], v[180:183], v[218:221], v[54:57]
	v_mfma_f32_16x16x32_bf16 v[50:53], v[172:175], v[226:229], v[50:53]
	v_mfma_f32_16x16x32_bf16 v[46:49], v[180:183], v[226:229], v[46:49]
	v_mfma_f32_16x16x32_bf16 v[38:41], v[172:175], v[234:237], v[38:41]
	v_mfma_f32_16x16x32_bf16 v[30:33], v[180:183], v[234:237], v[30:33]
	v_mfma_f32_16x16x32_bf16 v[42:45], v[184:187], v[206:209], v[42:45]
	v_mfma_f32_16x16x32_bf16 v[34:37], v[196:199], v[206:209], v[34:37]
	v_mfma_f32_16x16x32_bf16 v[26:29], v[184:187], v[214:217], v[26:29]
	v_mfma_f32_16x16x32_bf16 v[22:25], v[196:199], v[214:217], v[22:25]
	v_mfma_f32_16x16x32_bf16 v[18:21], v[184:187], v[222:225], v[18:21]
	v_mfma_f32_16x16x32_bf16 v[14:17], v[196:199], v[222:225], v[14:17]
	v_mfma_f32_16x16x32_bf16 v[10:13], v[184:187], v[230:233], v[10:13]
	v_mfma_f32_16x16x32_bf16 v[6:9], v[196:199], v[230:233], v[6:9]
	v_mfma_f32_16x16x32_bf16 v[42:45], v[188:191], v[210:213], v[42:45]
	v_mfma_f32_16x16x32_bf16 v[34:37], v[200:203], v[210:213], v[34:37]
	v_mfma_f32_16x16x32_bf16 v[26:29], v[188:191], v[218:221], v[26:29]
	v_mfma_f32_16x16x32_bf16 v[22:25], v[200:203], v[218:221], v[22:25]
	v_mfma_f32_16x16x32_bf16 v[18:21], v[188:191], v[226:229], v[18:21]
	v_mfma_f32_16x16x32_bf16 v[14:17], v[200:203], v[226:229], v[14:17]
	v_mfma_f32_16x16x32_bf16 v[10:13], v[188:191], v[234:237], v[10:13]
	v_mfma_f32_16x16x32_bf16 v[6:9], v[200:203], v[234:237], v[6:9]
	s_setprio 0
	s_barrier
	s_add_i32 s80, s72, s61
	v_lshl_add_u64 v[166:167], s[42:43], 0, v[134:135]
	s_mov_b32 m0, s80
	ds_read_b128 v[206:209], v170 offset:16384
	ds_read_b128 v[210:213], v170 offset:17408
	ds_read_b128 v[214:217], v170 offset:18432
	ds_read_b128 v[218:221], v170 offset:19456
	ds_read_b128 v[222:225], v170 offset:20480
	ds_read_b128 v[226:229], v170 offset:21504
	ds_read_b128 v[230:233], v170 offset:22528
	ds_read_b128 v[234:237], v170 offset:23552
	global_load_lds_dwordx4 v[166:167], off
	s_add_i32 m0, s80, 0x2000
	s_add_u32 s80, s42, 0x100000
	v_lshl_add_u64 v[192:193], s[42:43], 0, v[138:139]
	s_addc_u32 s81, s43, 0
	s_add_i32 s82, s73, s61
	global_load_lds_dwordx4 v[192:193], off
	v_lshl_add_u64 v[238:239], s[80:81], 0, v[134:135]
	s_mov_b32 m0, s82
	v_lshl_add_u64 v[240:241], s[46:47], 0, v[136:137]
	global_load_lds_dwordx4 v[238:239], off
	v_lshl_add_u64 v[238:239], s[80:81], 0, v[138:139]
	s_add_i32 m0, s82, 0x2000
	s_nop 0
	global_load_lds_dwordx4 v[238:239], off
	v_lshl_add_u64 v[238:239], s[46:47], 0, v[132:133]
	s_mov_b32 m0, s62
	s_nop 0
	global_load_lds_dwordx4 v[238:239], off
	s_mov_b32 m0, s63
	s_nop 0
	global_load_lds_dwordx4 v[240:241], off
	s_waitcnt vmcnt(8)
	s_waitcnt lgkmcnt(0)
	s_setprio 1
	s_barrier
	v_mfma_f32_16x16x32_bf16 v[126:129], v[162:165], v[206:209], v[126:129]
	v_mfma_f32_16x16x32_bf16 v[122:125], v[176:179], v[206:209], v[122:125]
	v_mfma_f32_16x16x32_bf16 v[110:113], v[162:165], v[214:217], v[110:113]
	v_mfma_f32_16x16x32_bf16 v[106:109], v[176:179], v[214:217], v[106:109]
	v_mfma_f32_16x16x32_bf16 v[94:97], v[162:165], v[222:225], v[94:97]
	v_mfma_f32_16x16x32_bf16 v[90:93], v[176:179], v[222:225], v[90:93]
	v_mfma_f32_16x16x32_bf16 v[78:81], v[162:165], v[230:233], v[78:81]
	v_mfma_f32_16x16x32_bf16 v[74:77], v[176:179], v[230:233], v[74:77]
	v_mfma_f32_16x16x32_bf16 v[126:129], v[172:175], v[210:213], v[126:129]
	v_mfma_f32_16x16x32_bf16 v[122:125], v[180:183], v[210:213], v[122:125]
	v_mfma_f32_16x16x32_bf16 v[110:113], v[172:175], v[218:221], v[110:113]
	v_mfma_f32_16x16x32_bf16 v[106:109], v[180:183], v[218:221], v[106:109]
	v_mfma_f32_16x16x32_bf16 v[94:97], v[172:175], v[226:229], v[94:97]
	v_mfma_f32_16x16x32_bf16 v[90:93], v[180:183], v[226:229], v[90:93]
	v_mfma_f32_16x16x32_bf16 v[78:81], v[172:175], v[234:237], v[78:81]
	v_mfma_f32_16x16x32_bf16 v[74:77], v[180:183], v[234:237], v[74:77]
	v_mfma_f32_16x16x32_bf16 v[118:121], v[184:187], v[206:209], v[118:121]
	v_mfma_f32_16x16x32_bf16 v[114:117], v[196:199], v[206:209], v[114:117]
	v_mfma_f32_16x16x32_bf16 v[102:105], v[184:187], v[214:217], v[102:105]
	v_mfma_f32_16x16x32_bf16 v[98:101], v[196:199], v[214:217], v[98:101]
	v_mfma_f32_16x16x32_bf16 v[86:89], v[184:187], v[222:225], v[86:89]
	v_mfma_f32_16x16x32_bf16 v[82:85], v[196:199], v[222:225], v[82:85]
	v_mfma_f32_16x16x32_bf16 v[70:73], v[184:187], v[230:233], v[70:73]
	v_mfma_f32_16x16x32_bf16 v[2:5], v[196:199], v[230:233], v[2:5]
	v_mfma_f32_16x16x32_bf16 v[118:121], v[188:191], v[210:213], v[118:121]
	v_mfma_f32_16x16x32_bf16 v[114:117], v[200:203], v[210:213], v[114:117]
	v_mfma_f32_16x16x32_bf16 v[102:105], v[188:191], v[218:221], v[102:105]
	v_mfma_f32_16x16x32_bf16 v[98:101], v[200:203], v[218:221], v[98:101]
	v_mfma_f32_16x16x32_bf16 v[86:89], v[188:191], v[226:229], v[86:89]
	v_mfma_f32_16x16x32_bf16 v[82:85], v[200:203], v[226:229], v[82:85]
	v_mfma_f32_16x16x32_bf16 v[70:73], v[188:191], v[234:237], v[70:73]
	v_mfma_f32_16x16x32_bf16 v[2:5], v[200:203], v[234:237], v[2:5]
	s_setprio 0
	s_barrier
	s_add_i32 s80, 0, 0x18000
	s_add_i32 s81, 0, 0x1c000
	v_add_u32_e32 v180, s80, v131
	v_add_u32_e32 v200, s81, v131
	ds_read_b128 v[162:165], v180
	ds_read_b128 v[172:175], v180 offset:1024
	ds_read_b128 v[176:179], v180 offset:2048
	ds_read_b128 v[180:183], v180 offset:3072
	ds_read_b128 v[184:187], v200
	ds_read_b128 v[188:191], v200 offset:1024
	ds_read_b128 v[196:199], v200 offset:2048
	ds_read_b128 v[200:203], v200 offset:3072
	s_add_u32 s46, s46, 0x100000
	s_addc_u32 s47, s47, 0
	s_mov_b32 m0, s64
	v_lshl_add_u64 v[242:243], s[46:47], 0, v[132:133]
	ds_read_b128 v[206:209], v170 offset:32768
	ds_read_b128 v[210:213], v170 offset:33792
	ds_read_b128 v[214:217], v170 offset:34816
	ds_read_b128 v[218:221], v170 offset:35840
	ds_read_b128 v[222:225], v170 offset:36864
	ds_read_b128 v[226:229], v170 offset:37888
	ds_read_b128 v[230:233], v170 offset:38912
	ds_read_b128 v[234:237], v170 offset:39936
	global_load_lds_dwordx4 v[242:243], off
	v_lshl_add_u64 v[242:243], s[46:47], 0, v[136:137]
	s_mov_b32 m0, s65
	s_nop 0
	global_load_lds_dwordx4 v[242:243], off
	s_waitcnt vmcnt(8)
	s_waitcnt lgkmcnt(0)
	s_setprio 1
	s_barrier
	v_mfma_f32_16x16x32_bf16 v[66:69], v[162:165], v[206:209], v[66:69]
	v_mfma_f32_16x16x32_bf16 v[62:65], v[176:179], v[206:209], v[62:65]
	v_mfma_f32_16x16x32_bf16 v[58:61], v[162:165], v[214:217], v[58:61]
	v_mfma_f32_16x16x32_bf16 v[54:57], v[176:179], v[214:217], v[54:57]
	v_mfma_f32_16x16x32_bf16 v[50:53], v[162:165], v[222:225], v[50:53]
	v_mfma_f32_16x16x32_bf16 v[46:49], v[176:179], v[222:225], v[46:49]
	v_mfma_f32_16x16x32_bf16 v[38:41], v[162:165], v[230:233], v[38:41]
	v_mfma_f32_16x16x32_bf16 v[30:33], v[176:179], v[230:233], v[30:33]
	v_mfma_f32_16x16x32_bf16 v[66:69], v[172:175], v[210:213], v[66:69]
	v_mfma_f32_16x16x32_bf16 v[62:65], v[180:183], v[210:213], v[62:65]
	v_mfma_f32_16x16x32_bf16 v[58:61], v[172:175], v[218:221], v[58:61]
	v_mfma_f32_16x16x32_bf16 v[54:57], v[180:183], v[218:221], v[54:57]
	v_mfma_f32_16x16x32_bf16 v[50:53], v[172:175], v[226:229], v[50:53]
	v_mfma_f32_16x16x32_bf16 v[46:49], v[180:183], v[226:229], v[46:49]
	v_mfma_f32_16x16x32_bf16 v[38:41], v[172:175], v[234:237], v[38:41]
	v_mfma_f32_16x16x32_bf16 v[30:33], v[180:183], v[234:237], v[30:33]
	v_mfma_f32_16x16x32_bf16 v[42:45], v[184:187], v[206:209], v[42:45]
	v_mfma_f32_16x16x32_bf16 v[34:37], v[196:199], v[206:209], v[34:37]
	v_mfma_f32_16x16x32_bf16 v[26:29], v[184:187], v[214:217], v[26:29]
	v_mfma_f32_16x16x32_bf16 v[22:25], v[196:199], v[214:217], v[22:25]
	v_mfma_f32_16x16x32_bf16 v[18:21], v[184:187], v[222:225], v[18:21]
	v_mfma_f32_16x16x32_bf16 v[14:17], v[196:199], v[222:225], v[14:17]
	v_mfma_f32_16x16x32_bf16 v[10:13], v[184:187], v[230:233], v[10:13]
	v_mfma_f32_16x16x32_bf16 v[6:9], v[196:199], v[230:233], v[6:9]
	v_mfma_f32_16x16x32_bf16 v[42:45], v[188:191], v[210:213], v[42:45]
	v_mfma_f32_16x16x32_bf16 v[34:37], v[200:203], v[210:213], v[34:37]
	v_mfma_f32_16x16x32_bf16 v[26:29], v[188:191], v[218:221], v[26:29]
	v_mfma_f32_16x16x32_bf16 v[22:25], v[200:203], v[218:221], v[22:25]
	v_mfma_f32_16x16x32_bf16 v[18:21], v[188:191], v[226:229], v[18:21]
	v_mfma_f32_16x16x32_bf16 v[14:17], v[200:203], v[226:229], v[14:17]
	v_mfma_f32_16x16x32_bf16 v[10:13], v[188:191], v[234:237], v[10:13]
	v_mfma_f32_16x16x32_bf16 v[6:9], v[200:203], v[234:237], v[6:9]
	s_setprio 0
	s_barrier
	s_add_i32 s46, s80, s61
	v_lshl_add_u64 v[166:167], v[166:167], 0, s[18:19]
	s_mov_b32 m0, s46
	ds_read_b128 v[206:209], v170 offset:49152
	ds_read_b128 v[210:213], v170 offset:50176
	ds_read_b128 v[214:217], v170 offset:51200
	ds_read_b128 v[218:221], v170 offset:52224
	ds_read_b128 v[222:225], v170 offset:53248
	ds_read_b128 v[226:229], v170 offset:54272
	ds_read_b128 v[230:233], v170 offset:55296
	ds_read_b128 v[234:237], v170 offset:56320
	global_load_lds_dwordx4 v[166:167], off
	s_add_i32 m0, s46, 0x2000
	s_add_u32 s42, s42, 0x100080
	v_lshl_add_u64 v[166:167], v[192:193], 0, s[18:19]
	s_addc_u32 s43, s43, 0
	s_add_i32 s46, s81, s61
	global_load_lds_dwordx4 v[166:167], off
	v_lshl_add_u64 v[166:167], s[42:43], 0, v[134:135]
	s_mov_b32 m0, s46
	s_nop 0
	global_load_lds_dwordx4 v[166:167], off
	v_lshl_add_u64 v[166:167], s[42:43], 0, v[138:139]
	s_add_i32 m0, s46, 0x2000
	s_nop 0
	global_load_lds_dwordx4 v[166:167], off
	v_lshl_add_u64 v[166:167], v[238:239], 0, s[18:19]
	s_mov_b32 m0, s69
	s_nop 0
	global_load_lds_dwordx4 v[166:167], off
	v_lshl_add_u64 v[166:167], v[240:241], 0, s[18:19]
	s_mov_b32 m0, s70
	s_nop 0
	global_load_lds_dwordx4 v[166:167], off
	s_nop 0
	s_waitcnt vmcnt(8)
	s_waitcnt lgkmcnt(0)
	s_setprio 1
	s_barrier
	v_mfma_f32_16x16x32_bf16 v[126:129], v[162:165], v[206:209], v[126:129]
	v_mfma_f32_16x16x32_bf16 v[122:125], v[176:179], v[206:209], v[122:125]
	v_mfma_f32_16x16x32_bf16 v[110:113], v[162:165], v[214:217], v[110:113]
	v_mfma_f32_16x16x32_bf16 v[106:109], v[176:179], v[214:217], v[106:109]
	v_mfma_f32_16x16x32_bf16 v[94:97], v[162:165], v[222:225], v[94:97]
	v_mfma_f32_16x16x32_bf16 v[90:93], v[176:179], v[222:225], v[90:93]
	v_mfma_f32_16x16x32_bf16 v[78:81], v[162:165], v[230:233], v[78:81]
	v_mfma_f32_16x16x32_bf16 v[74:77], v[176:179], v[230:233], v[74:77]
	v_mfma_f32_16x16x32_bf16 v[126:129], v[172:175], v[210:213], v[126:129]
	v_mfma_f32_16x16x32_bf16 v[122:125], v[180:183], v[210:213], v[122:125]
	v_mfma_f32_16x16x32_bf16 v[110:113], v[172:175], v[218:221], v[110:113]
	v_mfma_f32_16x16x32_bf16 v[106:109], v[180:183], v[218:221], v[106:109]
	v_mfma_f32_16x16x32_bf16 v[94:97], v[172:175], v[226:229], v[94:97]
	v_mfma_f32_16x16x32_bf16 v[90:93], v[180:183], v[226:229], v[90:93]
	v_mfma_f32_16x16x32_bf16 v[78:81], v[172:175], v[234:237], v[78:81]
	v_mfma_f32_16x16x32_bf16 v[74:77], v[180:183], v[234:237], v[74:77]
	v_mfma_f32_16x16x32_bf16 v[118:121], v[184:187], v[206:209], v[118:121]
	v_mfma_f32_16x16x32_bf16 v[114:117], v[196:199], v[206:209], v[114:117]
	v_mfma_f32_16x16x32_bf16 v[102:105], v[184:187], v[214:217], v[102:105]
	v_mfma_f32_16x16x32_bf16 v[98:101], v[196:199], v[214:217], v[98:101]
	v_mfma_f32_16x16x32_bf16 v[86:89], v[184:187], v[222:225], v[86:89]
	v_mfma_f32_16x16x32_bf16 v[82:85], v[196:199], v[222:225], v[82:85]
	v_mfma_f32_16x16x32_bf16 v[70:73], v[184:187], v[230:233], v[70:73]
	v_mfma_f32_16x16x32_bf16 v[2:5], v[196:199], v[230:233], v[2:5]
	v_mfma_f32_16x16x32_bf16 v[118:121], v[188:191], v[210:213], v[118:121]
	v_mfma_f32_16x16x32_bf16 v[114:117], v[200:203], v[210:213], v[114:117]
	v_mfma_f32_16x16x32_bf16 v[102:105], v[188:191], v[218:221], v[102:105]
	v_mfma_f32_16x16x32_bf16 v[98:101], v[200:203], v[218:221], v[98:101]
	v_mfma_f32_16x16x32_bf16 v[86:89], v[188:191], v[226:229], v[86:89]
	v_mfma_f32_16x16x32_bf16 v[82:85], v[200:203], v[226:229], v[82:85]
	v_mfma_f32_16x16x32_bf16 v[70:73], v[188:191], v[234:237], v[70:73]
	v_mfma_f32_16x16x32_bf16 v[2:5], v[200:203], v[234:237], v[2:5]
	s_setprio 0
	s_barrier
	s_add_u32 s8, s8, 0x100
	s_addc_u32 s9, s9, 0
	s_add_u32 s49, s49, 0x100
	s_addc_u32 s53, s53, 0
	s_cmp_ge_i32 s55, s3
	s_mov_b32 s42, s55
	s_cbranch_scc0 .LBB0_1869
	s_and_b64 vcc, exec, s[20:21]
	s_cbranch_vccz .LBB0_1874
	s_barrier
	v_lshl_or_b32 v162, s40, 8, v141
	s_cmp_lt_i32 s10, 0
	s_mov_b64 s[8:9], -1
	s_cbranch_scc1 .LBB0_1875

.LBB0_3649:
	ds_read_b128 v[152:155], v162
	ds_read_b128 v[156:159], v162 offset:1024
	ds_read_b128 v[168:171], v162 offset:2048
	ds_read_b128 v[172:175], v162 offset:3072
	ds_read_b128 v[176:179], v163
	ds_read_b128 v[180:183], v163 offset:1024
	ds_read_b128 v[184:187], v163 offset:2048
	ds_read_b128 v[188:191], v163 offset:3072
	s_add_i32 s86, s48, 2
	s_add_u32 s49, s6, 0xfff00080
	s_addc_u32 s64, s7, -1
	s_cmp_eq_u32 s51, s48
	s_cselect_b32 s48, s58, s53
	s_cselect_b32 s65, s57, s64
	s_cselect_b32 s64, s56, s49
	s_cselect_b32 s49, s59, s55
	v_lshl_add_u64 v[192:193], s[6:7], 0, v[140:141]
	s_add_i32 m0, s61, 0xc000
	ds_read_b128 v[196:199], v164
	ds_read_b128 v[200:203], v164 offset:1024
	ds_read_b128 v[206:209], v164 offset:2048
	ds_read_b128 v[210:213], v164 offset:3072
	ds_read_b128 v[214:217], v164 offset:4096
	ds_read_b128 v[218:221], v164 offset:5120
	ds_read_b128 v[222:225], v164 offset:6144
	ds_read_b128 v[226:229], v164 offset:7168
	global_load_lds_dwordx4 v[192:193], off
	v_lshl_add_u64 v[192:193], s[6:7], 0, v[142:143]
	s_add_i32 m0, s61, 0xe000
	s_nop 0
	global_load_lds_dwordx4 v[192:193], off
	s_nop 0
	s_waitcnt vmcnt(8)
	s_waitcnt lgkmcnt(0)
	s_setprio 1
	s_barrier
	v_mfma_f32_16x16x32_bf16 v[126:129], v[152:155], v[196:199], v[126:129]
	v_mfma_f32_16x16x32_bf16 v[122:125], v[168:171], v[196:199], v[122:125]
	v_mfma_f32_16x16x32_bf16 v[110:113], v[152:155], v[206:209], v[110:113]
	v_mfma_f32_16x16x32_bf16 v[106:109], v[168:171], v[206:209], v[106:109]
	v_mfma_f32_16x16x32_bf16 v[94:97], v[152:155], v[214:217], v[94:97]
	v_mfma_f32_16x16x32_bf16 v[90:93], v[168:171], v[214:217], v[90:93]
	v_mfma_f32_16x16x32_bf16 v[78:81], v[152:155], v[222:225], v[78:81]
	v_mfma_f32_16x16x32_bf16 v[74:77], v[168:171], v[222:225], v[74:77]
	v_mfma_f32_16x16x32_bf16 v[126:129], v[156:159], v[200:203], v[126:129]
	v_mfma_f32_16x16x32_bf16 v[122:125], v[172:175], v[200:203], v[122:125]
	v_mfma_f32_16x16x32_bf16 v[110:113], v[156:159], v[210:213], v[110:113]
	v_mfma_f32_16x16x32_bf16 v[106:109], v[172:175], v[210:213], v[106:109]
	v_mfma_f32_16x16x32_bf16 v[94:97], v[156:159], v[218:221], v[94:97]
	v_mfma_f32_16x16x32_bf16 v[90:93], v[172:175], v[218:221], v[90:93]
	v_mfma_f32_16x16x32_bf16 v[78:81], v[156:159], v[226:229], v[78:81]
	v_mfma_f32_16x16x32_bf16 v[74:77], v[172:175], v[226:229], v[74:77]
	v_mfma_f32_16x16x32_bf16 v[118:121], v[176:179], v[196:199], v[118:121]
	v_mfma_f32_16x16x32_bf16 v[114:117], v[184:187], v[196:199], v[114:117]
	v_mfma_f32_16x16x32_bf16 v[102:105], v[176:179], v[206:209], v[102:105]
	v_mfma_f32_16x16x32_bf16 v[98:101], v[184:187], v[206:209], v[98:101]
	v_mfma_f32_16x16x32_bf16 v[86:89], v[176:179], v[214:217], v[86:89]
	v_mfma_f32_16x16x32_bf16 v[82:85], v[184:187], v[214:217], v[82:85]
	v_mfma_f32_16x16x32_bf16 v[70:73], v[176:179], v[222:225], v[70:73]
	v_mfma_f32_16x16x32_bf16 v[66:69], v[184:187], v[222:225], v[66:69]
	v_mfma_f32_16x16x32_bf16 v[118:121], v[180:183], v[200:203], v[118:121]
	v_mfma_f32_16x16x32_bf16 v[114:117], v[188:191], v[200:203], v[114:117]
	v_mfma_f32_16x16x32_bf16 v[102:105], v[180:183], v[210:213], v[102:105]
	v_mfma_f32_16x16x32_bf16 v[98:101], v[188:191], v[210:213], v[98:101]
	v_mfma_f32_16x16x32_bf16 v[86:89], v[180:183], v[218:221], v[86:89]
	v_mfma_f32_16x16x32_bf16 v[82:85], v[188:191], v[218:221], v[82:85]
	v_mfma_f32_16x16x32_bf16 v[70:73], v[180:183], v[226:229], v[70:73]
	v_mfma_f32_16x16x32_bf16 v[66:69], v[188:191], v[226:229], v[66:69]
	s_setprio 0
	s_barrier
	s_add_i32 s87, s75, s66
	v_lshl_add_u64 v[192:193], s[48:49], 0, v[134:135]
	s_mov_b32 m0, s87
	ds_read_b128 v[196:199], v164 offset:16384
	ds_read_b128 v[200:203], v164 offset:17408
	ds_read_b128 v[206:209], v164 offset:18432
	ds_read_b128 v[210:213], v164 offset:19456
	ds_read_b128 v[214:217], v164 offset:20480
	ds_read_b128 v[218:221], v164 offset:21504
	ds_read_b128 v[222:225], v164 offset:22528
	ds_read_b128 v[226:229], v164 offset:23552
	global_load_lds_dwordx4 v[192:193], off
	s_add_i32 m0, s87, 0x2000
	s_add_u32 s88, s48, 0x100000
	v_lshl_add_u64 v[230:231], s[48:49], 0, v[138:139]
	s_addc_u32 s89, s49, 0
	s_add_i32 s87, s76, s66
	global_load_lds_dwordx4 v[230:231], off
	v_lshl_add_u64 v[232:233], s[88:89], 0, v[134:135]
	s_mov_b32 m0, s87
	v_lshl_add_u64 v[234:235], s[64:65], 0, v[136:137]
	global_load_lds_dwordx4 v[232:233], off
	v_lshl_add_u64 v[232:233], s[88:89], 0, v[138:139]
	s_add_i32 m0, s87, 0x2000
	s_nop 0
	global_load_lds_dwordx4 v[232:233], off
	v_lshl_add_u64 v[232:233], s[64:65], 0, v[132:133]
	s_mov_b32 m0, s61
	s_nop 0
	global_load_lds_dwordx4 v[232:233], off
	s_mov_b32 m0, s63
	s_nop 0
	global_load_lds_dwordx4 v[234:235], off
	s_waitcnt vmcnt(8)
	s_waitcnt lgkmcnt(0)
	s_setprio 1
	s_barrier
	v_mfma_f32_16x16x32_bf16 v[62:65], v[152:155], v[196:199], v[62:65]
	v_mfma_f32_16x16x32_bf16 v[58:61], v[168:171], v[196:199], v[58:61]
	v_mfma_f32_16x16x32_bf16 v[46:49], v[152:155], v[206:209], v[46:49]
	v_mfma_f32_16x16x32_bf16 v[42:45], v[168:171], v[206:209], v[42:45]
	v_mfma_f32_16x16x32_bf16 v[30:33], v[152:155], v[214:217], v[30:33]
	v_mfma_f32_16x16x32_bf16 v[26:29], v[168:171], v[214:217], v[26:29]
	v_mfma_f32_16x16x32_bf16 v[14:17], v[152:155], v[222:225], v[14:17]
	v_mfma_f32_16x16x32_bf16 v[10:13], v[168:171], v[222:225], v[10:13]
	v_mfma_f32_16x16x32_bf16 v[62:65], v[156:159], v[200:203], v[62:65]
	v_mfma_f32_16x16x32_bf16 v[58:61], v[172:175], v[200:203], v[58:61]
	v_mfma_f32_16x16x32_bf16 v[46:49], v[156:159], v[210:213], v[46:49]
	v_mfma_f32_16x16x32_bf16 v[42:45], v[172:175], v[210:213], v[42:45]
	v_mfma_f32_16x16x32_bf16 v[30:33], v[156:159], v[218:221], v[30:33]
	v_mfma_f32_16x16x32_bf16 v[26:29], v[172:175], v[218:221], v[26:29]
	v_mfma_f32_16x16x32_bf16 v[14:17], v[156:159], v[226:229], v[14:17]
	v_mfma_f32_16x16x32_bf16 v[10:13], v[172:175], v[226:229], v[10:13]
	v_mfma_f32_16x16x32_bf16 v[54:57], v[176:179], v[196:199], v[54:57]
	v_mfma_f32_16x16x32_bf16 v[50:53], v[184:187], v[196:199], v[50:53]
	v_mfma_f32_16x16x32_bf16 v[38:41], v[176:179], v[206:209], v[38:41]
	v_mfma_f32_16x16x32_bf16 v[34:37], v[184:187], v[206:209], v[34:37]
	v_mfma_f32_16x16x32_bf16 v[22:25], v[176:179], v[214:217], v[22:25]
	v_mfma_f32_16x16x32_bf16 v[18:21], v[184:187], v[214:217], v[18:21]
	v_mfma_f32_16x16x32_bf16 v[6:9], v[176:179], v[222:225], v[6:9]
	v_mfma_f32_16x16x32_bf16 v[2:5], v[184:187], v[222:225], v[2:5]
	v_mfma_f32_16x16x32_bf16 v[54:57], v[180:183], v[200:203], v[54:57]
	v_mfma_f32_16x16x32_bf16 v[50:53], v[188:191], v[200:203], v[50:53]
	v_mfma_f32_16x16x32_bf16 v[38:41], v[180:183], v[210:213], v[38:41]
	v_mfma_f32_16x16x32_bf16 v[34:37], v[188:191], v[210:213], v[34:37]
	v_mfma_f32_16x16x32_bf16 v[22:25], v[180:183], v[218:221], v[22:25]
	v_mfma_f32_16x16x32_bf16 v[18:21], v[188:191], v[218:221], v[18:21]
	v_mfma_f32_16x16x32_bf16 v[6:9], v[180:183], v[226:229], v[6:9]
	v_mfma_f32_16x16x32_bf16 v[2:5], v[188:191], v[226:229], v[2:5]
	s_setprio 0
	s_barrier
	s_add_i32 s87, 0, 0x18000
	v_add_u32_e32 v167, s87, v160
	s_add_i32 s88, 0, 0x1c000
	ds_read_b128 v[152:155], v167
	ds_read_b128 v[156:159], v167 offset:1024
	ds_read_b128 v[168:171], v167 offset:2048
	ds_read_b128 v[172:175], v167 offset:3072
	v_add_u32_e32 v167, s88, v160
	ds_read_b128 v[176:179], v167
	ds_read_b128 v[180:183], v167 offset:1024
	ds_read_b128 v[184:187], v167 offset:2048
	ds_read_b128 v[188:191], v167 offset:3072
	s_add_u32 s64, s64, 0x100000
	s_addc_u32 s65, s65, 0
	s_mov_b32 m0, s67
	v_lshl_add_u64 v[236:237], s[64:65], 0, v[132:133]
	ds_read_b128 v[196:199], v164 offset:32768
	ds_read_b128 v[200:203], v164 offset:33792
	ds_read_b128 v[206:209], v164 offset:34816
	ds_read_b128 v[210:213], v164 offset:35840
	ds_read_b128 v[214:217], v164 offset:36864
	ds_read_b128 v[218:221], v164 offset:37888
	ds_read_b128 v[222:225], v164 offset:38912
	ds_read_b128 v[226:229], v164 offset:39936
	global_load_lds_dwordx4 v[236:237], off
	v_lshl_add_u64 v[236:237], s[64:65], 0, v[136:137]
	s_mov_b32 m0, s68
	s_nop 0
	global_load_lds_dwordx4 v[236:237], off
	s_waitcnt vmcnt(8)
	s_waitcnt lgkmcnt(0)
	s_setprio 1
	s_barrier
	v_mfma_f32_16x16x32_bf16 v[126:129], v[152:155], v[196:199], v[126:129]
	v_mfma_f32_16x16x32_bf16 v[122:125], v[168:171], v[196:199], v[122:125]
	v_mfma_f32_16x16x32_bf16 v[110:113], v[152:155], v[206:209], v[110:113]
	v_mfma_f32_16x16x32_bf16 v[106:109], v[168:171], v[206:209], v[106:109]
	v_mfma_f32_16x16x32_bf16 v[94:97], v[152:155], v[214:217], v[94:97]
	v_mfma_f32_16x16x32_bf16 v[90:93], v[168:171], v[214:217], v[90:93]
	v_mfma_f32_16x16x32_bf16 v[78:81], v[152:155], v[222:225], v[78:81]
	v_mfma_f32_16x16x32_bf16 v[74:77], v[168:171], v[222:225], v[74:77]
	v_mfma_f32_16x16x32_bf16 v[126:129], v[156:159], v[200:203], v[126:129]
	v_mfma_f32_16x16x32_bf16 v[122:125], v[172:175], v[200:203], v[122:125]
	v_mfma_f32_16x16x32_bf16 v[110:113], v[156:159], v[210:213], v[110:113]
	v_mfma_f32_16x16x32_bf16 v[106:109], v[172:175], v[210:213], v[106:109]
	v_mfma_f32_16x16x32_bf16 v[94:97], v[156:159], v[218:221], v[94:97]
	v_mfma_f32_16x16x32_bf16 v[90:93], v[172:175], v[218:221], v[90:93]
	v_mfma_f32_16x16x32_bf16 v[78:81], v[156:159], v[226:229], v[78:81]
	v_mfma_f32_16x16x32_bf16 v[74:77], v[172:175], v[226:229], v[74:77]
	v_mfma_f32_16x16x32_bf16 v[118:121], v[176:179], v[196:199], v[118:121]
	v_mfma_f32_16x16x32_bf16 v[114:117], v[184:187], v[196:199], v[114:117]
	v_mfma_f32_16x16x32_bf16 v[102:105], v[176:179], v[206:209], v[102:105]
	v_mfma_f32_16x16x32_bf16 v[98:101], v[184:187], v[206:209], v[98:101]
	v_mfma_f32_16x16x32_bf16 v[86:89], v[176:179], v[214:217], v[86:89]
	v_mfma_f32_16x16x32_bf16 v[82:85], v[184:187], v[214:217], v[82:85]
	v_mfma_f32_16x16x32_bf16 v[70:73], v[176:179], v[222:225], v[70:73]
	v_mfma_f32_16x16x32_bf16 v[66:69], v[184:187], v[222:225], v[66:69]
	v_mfma_f32_16x16x32_bf16 v[118:121], v[180:183], v[200:203], v[118:121]
	v_mfma_f32_16x16x32_bf16 v[114:117], v[188:191], v[200:203], v[114:117]
	v_mfma_f32_16x16x32_bf16 v[102:105], v[180:183], v[210:213], v[102:105]
	v_mfma_f32_16x16x32_bf16 v[98:101], v[188:191], v[210:213], v[98:101]
	v_mfma_f32_16x16x32_bf16 v[86:89], v[180:183], v[218:221], v[86:89]
	v_mfma_f32_16x16x32_bf16 v[82:85], v[188:191], v[218:221], v[82:85]
	v_mfma_f32_16x16x32_bf16 v[70:73], v[180:183], v[226:229], v[70:73]
	v_mfma_f32_16x16x32_bf16 v[66:69], v[188:191], v[226:229], v[66:69]
	s_setprio 0
	s_barrier
	s_add_i32 s64, s87, s66
	v_lshl_add_u64 v[192:193], v[192:193], 0, s[20:21]
	s_mov_b32 m0, s64
	ds_read_b128 v[196:199], v164 offset:49152
	ds_read_b128 v[200:203], v164 offset:50176
	ds_read_b128 v[206:209], v164 offset:51200
	ds_read_b128 v[210:213], v164 offset:52224
	ds_read_b128 v[214:217], v164 offset:53248
	ds_read_b128 v[218:221], v164 offset:54272
	ds_read_b128 v[222:225], v164 offset:55296
	ds_read_b128 v[226:229], v164 offset:56320
	global_load_lds_dwordx4 v[192:193], off
	s_add_i32 m0, s64, 0x2000
	s_add_u32 s48, s48, 0x100080
	v_lshl_add_u64 v[192:193], v[230:231], 0, s[20:21]
	s_addc_u32 s49, s49, 0
	s_add_i32 s64, s88, s66
	global_load_lds_dwordx4 v[192:193], off
	v_lshl_add_u64 v[192:193], s[48:49], 0, v[134:135]
	s_mov_b32 m0, s64
	s_nop 0
	global_load_lds_dwordx4 v[192:193], off
	v_lshl_add_u64 v[192:193], s[48:49], 0, v[138:139]
	s_add_i32 m0, s64, 0x2000
	s_nop 0
	global_load_lds_dwordx4 v[192:193], off
	v_lshl_add_u64 v[192:193], v[232:233], 0, s[20:21]
	s_mov_b32 m0, s72
	s_nop 0
	global_load_lds_dwordx4 v[192:193], off
	v_lshl_add_u64 v[192:193], v[234:235], 0, s[20:21]
	s_mov_b32 m0, s73
	s_nop 0
	global_load_lds_dwordx4 v[192:193], off
	s_nop 0
	s_waitcnt vmcnt(8)
	s_waitcnt lgkmcnt(0)
	s_setprio 1
	s_barrier
	v_mfma_f32_16x16x32_bf16 v[62:65], v[152:155], v[196:199], v[62:65]
	v_mfma_f32_16x16x32_bf16 v[58:61], v[168:171], v[196:199], v[58:61]
	v_mfma_f32_16x16x32_bf16 v[46:49], v[152:155], v[206:209], v[46:49]
	v_mfma_f32_16x16x32_bf16 v[42:45], v[168:171], v[206:209], v[42:45]
	v_mfma_f32_16x16x32_bf16 v[30:33], v[152:155], v[214:217], v[30:33]
	v_mfma_f32_16x16x32_bf16 v[26:29], v[168:171], v[214:217], v[26:29]
	v_mfma_f32_16x16x32_bf16 v[14:17], v[152:155], v[222:225], v[14:17]
	v_mfma_f32_16x16x32_bf16 v[10:13], v[168:171], v[222:225], v[10:13]
	v_mfma_f32_16x16x32_bf16 v[62:65], v[156:159], v[200:203], v[62:65]
	v_mfma_f32_16x16x32_bf16 v[58:61], v[172:175], v[200:203], v[58:61]
	v_mfma_f32_16x16x32_bf16 v[46:49], v[156:159], v[210:213], v[46:49]
	v_mfma_f32_16x16x32_bf16 v[42:45], v[172:175], v[210:213], v[42:45]
	v_mfma_f32_16x16x32_bf16 v[30:33], v[156:159], v[218:221], v[30:33]
	v_mfma_f32_16x16x32_bf16 v[26:29], v[172:175], v[218:221], v[26:29]
	v_mfma_f32_16x16x32_bf16 v[14:17], v[156:159], v[226:229], v[14:17]
	v_mfma_f32_16x16x32_bf16 v[10:13], v[172:175], v[226:229], v[10:13]
	v_mfma_f32_16x16x32_bf16 v[54:57], v[176:179], v[196:199], v[54:57]
	v_mfma_f32_16x16x32_bf16 v[50:53], v[184:187], v[196:199], v[50:53]
	v_mfma_f32_16x16x32_bf16 v[38:41], v[176:179], v[206:209], v[38:41]
	v_mfma_f32_16x16x32_bf16 v[34:37], v[184:187], v[206:209], v[34:37]
	v_mfma_f32_16x16x32_bf16 v[22:25], v[176:179], v[214:217], v[22:25]
	v_mfma_f32_16x16x32_bf16 v[18:21], v[184:187], v[214:217], v[18:21]
	v_mfma_f32_16x16x32_bf16 v[6:9], v[176:179], v[222:225], v[6:9]
	v_mfma_f32_16x16x32_bf16 v[2:5], v[184:187], v[222:225], v[2:5]
	v_mfma_f32_16x16x32_bf16 v[54:57], v[180:183], v[200:203], v[54:57]
	v_mfma_f32_16x16x32_bf16 v[50:53], v[188:191], v[200:203], v[50:53]
	v_mfma_f32_16x16x32_bf16 v[38:41], v[180:183], v[210:213], v[38:41]
	v_mfma_f32_16x16x32_bf16 v[34:37], v[188:191], v[210:213], v[34:37]
	v_mfma_f32_16x16x32_bf16 v[22:25], v[180:183], v[218:221], v[22:25]
	v_mfma_f32_16x16x32_bf16 v[18:21], v[188:191], v[218:221], v[18:21]
	v_mfma_f32_16x16x32_bf16 v[6:9], v[180:183], v[226:229], v[6:9]
	v_mfma_f32_16x16x32_bf16 v[2:5], v[188:191], v[226:229], v[2:5]
	s_setprio 0
	s_barrier
	s_add_u32 s6, s6, 0x100
	s_addc_u32 s7, s7, 0
	s_add_u32 s53, s53, 0x100
	s_addc_u32 s55, s55, 0
	s_cmp_ge_i32 s86, s85
	s_mov_b32 s48, s86
	s_cbranch_scc0 .LBB0_3649
	s_and_b64 vcc, exec, s[22:23]
	s_cbranch_vccz .LBB0_3652
	s_barrier

.LBB0_3789:
	ds_read_b128 v[162:165], v145
	ds_read_b128 v[166:169], v145 offset:1024
	ds_read_b128 v[170:173], v145 offset:2048
	ds_read_b128 v[174:177], v145 offset:3072
	ds_read_b128 v[178:181], v160
	ds_read_b128 v[182:185], v160 offset:1024
	ds_read_b128 v[186:189], v160 offset:2048
	ds_read_b128 v[190:193], v160 offset:3072
	s_add_i32 s63, s30, 2
	s_add_u32 s31, s28, 0xfff00080
	s_addc_u32 s34, s29, -1
	s_cmp_eq_u32 s60, s30
	s_cselect_b32 s30, s59, s61
	s_cselect_b32 s35, s19, s34
	s_cselect_b32 s34, s23, s31
	s_cselect_b32 s31, s21, s62
	v_lshl_add_u64 v[158:159], s[28:29], 0, v[148:149]
	s_add_i32 m0, s6, 0xc000
	ds_read_b128 v[196:199], v161
	ds_read_b128 v[200:203], v161 offset:1024
	ds_read_b128 v[206:209], v161 offset:2048
	ds_read_b128 v[210:213], v161 offset:3072
	ds_read_b128 v[214:217], v161 offset:4096
	ds_read_b128 v[218:221], v161 offset:5120
	ds_read_b128 v[222:225], v161 offset:6144
	ds_read_b128 v[226:229], v161 offset:7168
	global_load_lds_dwordx4 v[158:159], off
	v_lshl_add_u64 v[158:159], s[28:29], 0, v[150:151]
	s_add_i32 m0, s6, 0xe000
	s_nop 0
	global_load_lds_dwordx4 v[158:159], off
	s_waitcnt vmcnt(8)
	s_waitcnt lgkmcnt(0)
	s_setprio 1
	s_barrier
	v_mfma_f32_16x16x32_bf16 v[126:129], v[162:165], v[196:199], v[126:129]
	v_mfma_f32_16x16x32_bf16 v[122:125], v[170:173], v[196:199], v[122:125]
	v_mfma_f32_16x16x32_bf16 v[118:121], v[162:165], v[206:209], v[118:121]
	v_mfma_f32_16x16x32_bf16 v[114:117], v[170:173], v[206:209], v[114:117]
	v_mfma_f32_16x16x32_bf16 v[102:105], v[162:165], v[214:217], v[102:105]
	v_mfma_f32_16x16x32_bf16 v[98:101], v[170:173], v[214:217], v[98:101]
	v_mfma_f32_16x16x32_bf16 v[42:45], v[162:165], v[222:225], v[42:45]
	v_mfma_f32_16x16x32_bf16 v[34:37], v[170:173], v[222:225], v[34:37]
	v_mfma_f32_16x16x32_bf16 v[126:129], v[166:169], v[200:203], v[126:129]
	v_mfma_f32_16x16x32_bf16 v[122:125], v[174:177], v[200:203], v[122:125]
	v_mfma_f32_16x16x32_bf16 v[118:121], v[166:169], v[210:213], v[118:121]
	v_mfma_f32_16x16x32_bf16 v[114:117], v[174:177], v[210:213], v[114:117]
	v_mfma_f32_16x16x32_bf16 v[102:105], v[166:169], v[218:221], v[102:105]
	v_mfma_f32_16x16x32_bf16 v[98:101], v[174:177], v[218:221], v[98:101]
	v_mfma_f32_16x16x32_bf16 v[42:45], v[166:169], v[226:229], v[42:45]
	v_mfma_f32_16x16x32_bf16 v[34:37], v[174:177], v[226:229], v[34:37]
	v_mfma_f32_16x16x32_bf16 v[110:113], v[178:181], v[196:199], v[110:113]
	v_mfma_f32_16x16x32_bf16 v[106:109], v[186:189], v[196:199], v[106:109]
	v_mfma_f32_16x16x32_bf16 v[94:97], v[178:181], v[206:209], v[94:97]
	v_mfma_f32_16x16x32_bf16 v[90:93], v[186:189], v[206:209], v[90:93]
	v_mfma_f32_16x16x32_bf16 v[86:89], v[178:181], v[214:217], v[86:89]
	v_mfma_f32_16x16x32_bf16 v[82:85], v[186:189], v[214:217], v[82:85]
	v_mfma_f32_16x16x32_bf16 v[30:33], v[178:181], v[222:225], v[30:33]
	v_mfma_f32_16x16x32_bf16 v[26:29], v[186:189], v[222:225], v[26:29]
	v_mfma_f32_16x16x32_bf16 v[110:113], v[182:185], v[200:203], v[110:113]
	v_mfma_f32_16x16x32_bf16 v[106:109], v[190:193], v[200:203], v[106:109]
	v_mfma_f32_16x16x32_bf16 v[94:97], v[182:185], v[210:213], v[94:97]
	v_mfma_f32_16x16x32_bf16 v[90:93], v[190:193], v[210:213], v[90:93]
	v_mfma_f32_16x16x32_bf16 v[86:89], v[182:185], v[218:221], v[86:89]
	v_mfma_f32_16x16x32_bf16 v[82:85], v[190:193], v[218:221], v[82:85]
	v_mfma_f32_16x16x32_bf16 v[30:33], v[182:185], v[226:229], v[30:33]
	v_mfma_f32_16x16x32_bf16 v[26:29], v[190:193], v[226:229], v[26:29]
	s_setprio 0
	s_barrier
	s_add_i32 s64, s54, s40
	v_lshl_add_u64 v[158:159], s[30:31], 0, v[134:135]
	s_mov_b32 m0, s64
	ds_read_b128 v[196:199], v161 offset:16384
	ds_read_b128 v[200:203], v161 offset:17408
	ds_read_b128 v[206:209], v161 offset:18432
	ds_read_b128 v[210:213], v161 offset:19456
	ds_read_b128 v[214:217], v161 offset:20480
	ds_read_b128 v[218:221], v161 offset:21504
	ds_read_b128 v[222:225], v161 offset:22528
	ds_read_b128 v[226:229], v161 offset:23552
	global_load_lds_dwordx4 v[158:159], off
	s_add_i32 m0, s64, 0x2000
	s_add_u32 s64, s30, 0x100000
	v_lshl_add_u64 v[230:231], s[30:31], 0, v[132:133]
	s_addc_u32 s65, s31, 0
	s_add_i32 s66, s55, s40
	global_load_lds_dwordx4 v[230:231], off
	v_lshl_add_u64 v[232:233], s[64:65], 0, v[134:135]
	s_mov_b32 m0, s66
	v_lshl_add_u64 v[234:235], s[34:35], 0, v[132:133]
	global_load_lds_dwordx4 v[232:233], off
	v_lshl_add_u64 v[232:233], s[64:65], 0, v[132:133]
	s_add_i32 m0, s66, 0x2000
	s_nop 0
	global_load_lds_dwordx4 v[232:233], off
	v_lshl_add_u64 v[232:233], s[34:35], 0, v[134:135]
	s_mov_b32 m0, s6
	s_nop 0
	global_load_lds_dwordx4 v[232:233], off
	s_mov_b32 m0, s13
	s_nop 0
	global_load_lds_dwordx4 v[234:235], off
	s_waitcnt vmcnt(8)
	s_waitcnt lgkmcnt(0)
	s_setprio 1
	s_barrier
	v_mfma_f32_16x16x32_bf16 v[78:81], v[162:165], v[196:199], v[78:81]
	v_mfma_f32_16x16x32_bf16 v[74:77], v[170:173], v[196:199], v[74:77]
	v_mfma_f32_16x16x32_bf16 v[70:73], v[162:165], v[206:209], v[70:73]
	v_mfma_f32_16x16x32_bf16 v[66:69], v[170:173], v[206:209], v[66:69]
	v_mfma_f32_16x16x32_bf16 v[54:57], v[162:165], v[214:217], v[54:57]
	v_mfma_f32_16x16x32_bf16 v[50:53], v[170:173], v[214:217], v[50:53]
	v_mfma_f32_16x16x32_bf16 v[14:17], v[162:165], v[222:225], v[14:17]
	v_mfma_f32_16x16x32_bf16 v[10:13], v[170:173], v[222:225], v[10:13]
	v_mfma_f32_16x16x32_bf16 v[78:81], v[166:169], v[200:203], v[78:81]
	v_mfma_f32_16x16x32_bf16 v[74:77], v[174:177], v[200:203], v[74:77]
	v_mfma_f32_16x16x32_bf16 v[70:73], v[166:169], v[210:213], v[70:73]
	v_mfma_f32_16x16x32_bf16 v[66:69], v[174:177], v[210:213], v[66:69]
	v_mfma_f32_16x16x32_bf16 v[54:57], v[166:169], v[218:221], v[54:57]
	v_mfma_f32_16x16x32_bf16 v[50:53], v[174:177], v[218:221], v[50:53]
	v_mfma_f32_16x16x32_bf16 v[14:17], v[166:169], v[226:229], v[14:17]
	v_mfma_f32_16x16x32_bf16 v[10:13], v[174:177], v[226:229], v[10:13]
	v_mfma_f32_16x16x32_bf16 v[62:65], v[178:181], v[196:199], v[62:65]
	v_mfma_f32_16x16x32_bf16 v[58:61], v[186:189], v[196:199], v[58:61]
	v_mfma_f32_16x16x32_bf16 v[46:49], v[178:181], v[206:209], v[46:49]
	v_mfma_f32_16x16x32_bf16 v[38:41], v[186:189], v[206:209], v[38:41]
	v_mfma_f32_16x16x32_bf16 v[22:25], v[178:181], v[214:217], v[22:25]
	v_mfma_f32_16x16x32_bf16 v[18:21], v[186:189], v[214:217], v[18:21]
	v_mfma_f32_16x16x32_bf16 v[6:9], v[178:181], v[222:225], v[6:9]
	v_mfma_f32_16x16x32_bf16 v[2:5], v[186:189], v[222:225], v[2:5]
	v_mfma_f32_16x16x32_bf16 v[62:65], v[182:185], v[200:203], v[62:65]
	v_mfma_f32_16x16x32_bf16 v[58:61], v[190:193], v[200:203], v[58:61]
	v_mfma_f32_16x16x32_bf16 v[46:49], v[182:185], v[210:213], v[46:49]
	v_mfma_f32_16x16x32_bf16 v[38:41], v[190:193], v[210:213], v[38:41]
	v_mfma_f32_16x16x32_bf16 v[22:25], v[182:185], v[218:221], v[22:25]
	v_mfma_f32_16x16x32_bf16 v[18:21], v[190:193], v[218:221], v[18:21]
	v_mfma_f32_16x16x32_bf16 v[6:9], v[182:185], v[226:229], v[6:9]
	v_mfma_f32_16x16x32_bf16 v[2:5], v[190:193], v[226:229], v[2:5]
	s_setprio 0
	s_barrier
	s_add_i32 s64, 0, 0x18000
	s_add_i32 s65, 0, 0x1c000
	v_add_u32_e32 v174, s64, v131
	v_add_u32_e32 v190, s65, v131
	ds_read_b128 v[162:165], v174
	ds_read_b128 v[166:169], v174 offset:1024
	ds_read_b128 v[170:173], v174 offset:2048
	ds_read_b128 v[174:177], v174 offset:3072
	ds_read_b128 v[178:181], v190
	ds_read_b128 v[182:185], v190 offset:1024
	ds_read_b128 v[186:189], v190 offset:2048
	ds_read_b128 v[190:193], v190 offset:3072
	s_add_u32 s34, s34, 0x100000
	s_addc_u32 s35, s35, 0
	s_mov_b32 m0, s43
	v_lshl_add_u64 v[236:237], s[34:35], 0, v[134:135]
	ds_read_b128 v[196:199], v161 offset:32768
	ds_read_b128 v[200:203], v161 offset:33792
	ds_read_b128 v[206:209], v161 offset:34816
	ds_read_b128 v[210:213], v161 offset:35840
	ds_read_b128 v[214:217], v161 offset:36864
	ds_read_b128 v[218:221], v161 offset:37888
	ds_read_b128 v[222:225], v161 offset:38912
	ds_read_b128 v[226:229], v161 offset:39936
	global_load_lds_dwordx4 v[236:237], off
	v_lshl_add_u64 v[236:237], s[34:35], 0, v[132:133]
	s_mov_b32 m0, s45
	s_nop 0
	global_load_lds_dwordx4 v[236:237], off
	s_waitcnt vmcnt(8)
	s_waitcnt lgkmcnt(0)
	s_setprio 1
	s_barrier
	v_mfma_f32_16x16x32_bf16 v[126:129], v[162:165], v[196:199], v[126:129]
	v_mfma_f32_16x16x32_bf16 v[122:125], v[170:173], v[196:199], v[122:125]
	v_mfma_f32_16x16x32_bf16 v[118:121], v[162:165], v[206:209], v[118:121]
	v_mfma_f32_16x16x32_bf16 v[114:117], v[170:173], v[206:209], v[114:117]
	v_mfma_f32_16x16x32_bf16 v[102:105], v[162:165], v[214:217], v[102:105]
	v_mfma_f32_16x16x32_bf16 v[98:101], v[170:173], v[214:217], v[98:101]
	v_mfma_f32_16x16x32_bf16 v[42:45], v[162:165], v[222:225], v[42:45]
	v_mfma_f32_16x16x32_bf16 v[34:37], v[170:173], v[222:225], v[34:37]
	v_mfma_f32_16x16x32_bf16 v[126:129], v[166:169], v[200:203], v[126:129]
	v_mfma_f32_16x16x32_bf16 v[122:125], v[174:177], v[200:203], v[122:125]
	v_mfma_f32_16x16x32_bf16 v[118:121], v[166:169], v[210:213], v[118:121]
	v_mfma_f32_16x16x32_bf16 v[114:117], v[174:177], v[210:213], v[114:117]
	v_mfma_f32_16x16x32_bf16 v[102:105], v[166:169], v[218:221], v[102:105]
	v_mfma_f32_16x16x32_bf16 v[98:101], v[174:177], v[218:221], v[98:101]
	v_mfma_f32_16x16x32_bf16 v[42:45], v[166:169], v[226:229], v[42:45]
	v_mfma_f32_16x16x32_bf16 v[34:37], v[174:177], v[226:229], v[34:37]
	v_mfma_f32_16x16x32_bf16 v[110:113], v[178:181], v[196:199], v[110:113]
	v_mfma_f32_16x16x32_bf16 v[106:109], v[186:189], v[196:199], v[106:109]
	v_mfma_f32_16x16x32_bf16 v[94:97], v[178:181], v[206:209], v[94:97]
	v_mfma_f32_16x16x32_bf16 v[90:93], v[186:189], v[206:209], v[90:93]
	v_mfma_f32_16x16x32_bf16 v[86:89], v[178:181], v[214:217], v[86:89]
	v_mfma_f32_16x16x32_bf16 v[82:85], v[186:189], v[214:217], v[82:85]
	v_mfma_f32_16x16x32_bf16 v[30:33], v[178:181], v[222:225], v[30:33]
	v_mfma_f32_16x16x32_bf16 v[26:29], v[186:189], v[222:225], v[26:29]
	v_mfma_f32_16x16x32_bf16 v[110:113], v[182:185], v[200:203], v[110:113]
	v_mfma_f32_16x16x32_bf16 v[106:109], v[190:193], v[200:203], v[106:109]
	v_mfma_f32_16x16x32_bf16 v[94:97], v[182:185], v[210:213], v[94:97]
	v_mfma_f32_16x16x32_bf16 v[90:93], v[190:193], v[210:213], v[90:93]
	v_mfma_f32_16x16x32_bf16 v[86:89], v[182:185], v[218:221], v[86:89]
	v_mfma_f32_16x16x32_bf16 v[82:85], v[190:193], v[218:221], v[82:85]
	v_mfma_f32_16x16x32_bf16 v[30:33], v[182:185], v[226:229], v[30:33]
	v_mfma_f32_16x16x32_bf16 v[26:29], v[190:193], v[226:229], v[26:29]
	s_setprio 0
	s_barrier
	s_add_i32 s34, s64, s40
	v_lshl_add_u64 v[158:159], v[158:159], 0, s[10:11]
	s_mov_b32 m0, s34
	ds_read_b128 v[196:199], v161 offset:49152
	ds_read_b128 v[200:203], v161 offset:50176
	ds_read_b128 v[206:209], v161 offset:51200
	ds_read_b128 v[210:213], v161 offset:52224
	ds_read_b128 v[214:217], v161 offset:53248
	ds_read_b128 v[218:221], v161 offset:54272
	ds_read_b128 v[222:225], v161 offset:55296
	ds_read_b128 v[226:229], v161 offset:56320
	global_load_lds_dwordx4 v[158:159], off
	s_add_i32 m0, s34, 0x2000
	s_add_u32 s30, s30, 0x100080
	v_lshl_add_u64 v[158:159], v[230:231], 0, s[10:11]
	s_addc_u32 s31, s31, 0
	s_add_i32 s34, s65, s40
	global_load_lds_dwordx4 v[158:159], off
	v_lshl_add_u64 v[158:159], s[30:31], 0, v[134:135]
	s_mov_b32 m0, s34
	s_nop 0
	global_load_lds_dwordx4 v[158:159], off
	v_lshl_add_u64 v[158:159], s[30:31], 0, v[132:133]
	s_add_i32 m0, s34, 0x2000
	s_nop 0
	global_load_lds_dwordx4 v[158:159], off
	v_lshl_add_u64 v[158:159], v[232:233], 0, s[10:11]
	s_mov_b32 m0, s50
	s_nop 0
	global_load_lds_dwordx4 v[158:159], off
	v_lshl_add_u64 v[158:159], v[234:235], 0, s[10:11]
	s_mov_b32 m0, s51
	s_nop 0
	global_load_lds_dwordx4 v[158:159], off
	s_nop 0
	s_waitcnt vmcnt(8)
	s_waitcnt lgkmcnt(0)
	s_setprio 1
	s_barrier
	v_mfma_f32_16x16x32_bf16 v[78:81], v[162:165], v[196:199], v[78:81]
	v_mfma_f32_16x16x32_bf16 v[74:77], v[170:173], v[196:199], v[74:77]
	v_mfma_f32_16x16x32_bf16 v[70:73], v[162:165], v[206:209], v[70:73]
	v_mfma_f32_16x16x32_bf16 v[66:69], v[170:173], v[206:209], v[66:69]
	v_mfma_f32_16x16x32_bf16 v[54:57], v[162:165], v[214:217], v[54:57]
	v_mfma_f32_16x16x32_bf16 v[50:53], v[170:173], v[214:217], v[50:53]
	v_mfma_f32_16x16x32_bf16 v[14:17], v[162:165], v[222:225], v[14:17]
	v_mfma_f32_16x16x32_bf16 v[10:13], v[170:173], v[222:225], v[10:13]
	v_mfma_f32_16x16x32_bf16 v[78:81], v[166:169], v[200:203], v[78:81]
	v_mfma_f32_16x16x32_bf16 v[74:77], v[174:177], v[200:203], v[74:77]
	v_mfma_f32_16x16x32_bf16 v[70:73], v[166:169], v[210:213], v[70:73]
	v_mfma_f32_16x16x32_bf16 v[66:69], v[174:177], v[210:213], v[66:69]
	v_mfma_f32_16x16x32_bf16 v[54:57], v[166:169], v[218:221], v[54:57]
	v_mfma_f32_16x16x32_bf16 v[50:53], v[174:177], v[218:221], v[50:53]
	v_mfma_f32_16x16x32_bf16 v[14:17], v[166:169], v[226:229], v[14:17]
	v_mfma_f32_16x16x32_bf16 v[10:13], v[174:177], v[226:229], v[10:13]
	v_mfma_f32_16x16x32_bf16 v[62:65], v[178:181], v[196:199], v[62:65]
	v_mfma_f32_16x16x32_bf16 v[58:61], v[186:189], v[196:199], v[58:61]
	v_mfma_f32_16x16x32_bf16 v[46:49], v[178:181], v[206:209], v[46:49]
	v_mfma_f32_16x16x32_bf16 v[38:41], v[186:189], v[206:209], v[38:41]
	v_mfma_f32_16x16x32_bf16 v[22:25], v[178:181], v[214:217], v[22:25]
	v_mfma_f32_16x16x32_bf16 v[18:21], v[186:189], v[214:217], v[18:21]
	v_mfma_f32_16x16x32_bf16 v[6:9], v[178:181], v[222:225], v[6:9]
	v_mfma_f32_16x16x32_bf16 v[2:5], v[186:189], v[222:225], v[2:5]
	v_mfma_f32_16x16x32_bf16 v[62:65], v[182:185], v[200:203], v[62:65]
	v_mfma_f32_16x16x32_bf16 v[58:61], v[190:193], v[200:203], v[58:61]
	v_mfma_f32_16x16x32_bf16 v[46:49], v[182:185], v[210:213], v[46:49]
	v_mfma_f32_16x16x32_bf16 v[38:41], v[190:193], v[210:213], v[38:41]
	v_mfma_f32_16x16x32_bf16 v[22:25], v[182:185], v[218:221], v[22:25]
	v_mfma_f32_16x16x32_bf16 v[18:21], v[190:193], v[218:221], v[18:21]
	v_mfma_f32_16x16x32_bf16 v[6:9], v[182:185], v[226:229], v[6:9]
	v_mfma_f32_16x16x32_bf16 v[2:5], v[190:193], v[226:229], v[2:5]
	s_setprio 0
	s_barrier
	s_add_u32 s28, s28, 0x100
	s_addc_u32 s29, s29, 0
	s_add_u32 s61, s61, 0x100
	s_addc_u32 s62, s62, 0
	s_cmp_ge_i32 s63, s58
	s_mov_b32 s30, s63
	s_cbranch_scc0 .LBB0_3789
	s_and_b64 vcc, exec, s[16:17]
	s_cbranch_vccz .LBB0_3792
	s_barrier

.LBB0_3983:
	ds_read_b128 v[152:155], v160
	ds_read_b128 v[164:167], v160 offset:1024
	ds_read_b128 v[168:171], v160 offset:2048
	ds_read_b128 v[172:175], v160 offset:3072
	ds_read_b128 v[176:179], v161
	ds_read_b128 v[180:183], v161 offset:1024
	ds_read_b128 v[184:187], v161 offset:2048
	ds_read_b128 v[188:191], v161 offset:3072
	s_add_i32 s80, s48, 2
	s_add_u32 s49, s58, 0xfffe0080
	s_addc_u32 s60, s59, -1
	s_cmp_eq_u32 s43, s48
	s_cselect_b32 s48, s52, s47
	s_cselect_b32 s61, s5, s60
	s_cselect_b32 s60, s4, s49
	s_cselect_b32 s49, s53, s51
	v_lshl_add_u64 v[156:157], s[58:59], 0, v[140:141]
	s_add_i32 m0, s55, 0xc000
	ds_read_b128 v[196:199], v162
	ds_read_b128 v[200:203], v162 offset:1024
	ds_read_b128 v[204:207], v162 offset:2048
	ds_read_b128 v[208:211], v162 offset:3072
	ds_read_b128 v[212:215], v162 offset:4096
	ds_read_b128 v[216:219], v162 offset:5120
	ds_read_b128 v[220:223], v162 offset:6144
	ds_read_b128 v[224:227], v162 offset:7168
	global_load_lds_dwordx4 v[156:157], off
	v_lshl_add_u64 v[156:157], s[58:59], 0, v[142:143]
	s_add_i32 m0, s55, 0xe000
	s_nop 0
	global_load_lds_dwordx4 v[156:157], off
	s_waitcnt vmcnt(8)
	s_waitcnt lgkmcnt(0)
	s_setprio 1
	s_barrier
	v_mfma_f32_16x16x32_bf16 v[126:129], v[152:155], v[196:199], v[126:129]
	v_mfma_f32_16x16x32_bf16 v[122:125], v[168:171], v[196:199], v[122:125]
	v_mfma_f32_16x16x32_bf16 v[110:113], v[152:155], v[204:207], v[110:113]
	v_mfma_f32_16x16x32_bf16 v[106:109], v[168:171], v[204:207], v[106:109]
	v_mfma_f32_16x16x32_bf16 v[94:97], v[152:155], v[212:215], v[94:97]
	v_mfma_f32_16x16x32_bf16 v[90:93], v[168:171], v[212:215], v[90:93]
	v_mfma_f32_16x16x32_bf16 v[78:81], v[152:155], v[220:223], v[78:81]
	v_mfma_f32_16x16x32_bf16 v[74:77], v[168:171], v[220:223], v[74:77]
	v_mfma_f32_16x16x32_bf16 v[126:129], v[164:167], v[200:203], v[126:129]
	v_mfma_f32_16x16x32_bf16 v[122:125], v[172:175], v[200:203], v[122:125]
	v_mfma_f32_16x16x32_bf16 v[110:113], v[164:167], v[208:211], v[110:113]
	v_mfma_f32_16x16x32_bf16 v[106:109], v[172:175], v[208:211], v[106:109]
	v_mfma_f32_16x16x32_bf16 v[94:97], v[164:167], v[216:219], v[94:97]
	v_mfma_f32_16x16x32_bf16 v[90:93], v[172:175], v[216:219], v[90:93]
	v_mfma_f32_16x16x32_bf16 v[78:81], v[164:167], v[224:227], v[78:81]
	v_mfma_f32_16x16x32_bf16 v[74:77], v[172:175], v[224:227], v[74:77]
	v_mfma_f32_16x16x32_bf16 v[118:121], v[176:179], v[196:199], v[118:121]
	v_mfma_f32_16x16x32_bf16 v[114:117], v[184:187], v[196:199], v[114:117]
	v_mfma_f32_16x16x32_bf16 v[102:105], v[176:179], v[204:207], v[102:105]
	v_mfma_f32_16x16x32_bf16 v[98:101], v[184:187], v[204:207], v[98:101]
	v_mfma_f32_16x16x32_bf16 v[86:89], v[176:179], v[212:215], v[86:89]
	v_mfma_f32_16x16x32_bf16 v[82:85], v[184:187], v[212:215], v[82:85]
	v_mfma_f32_16x16x32_bf16 v[70:73], v[176:179], v[220:223], v[70:73]
	v_mfma_f32_16x16x32_bf16 v[66:69], v[184:187], v[220:223], v[66:69]
	v_mfma_f32_16x16x32_bf16 v[118:121], v[180:183], v[200:203], v[118:121]
	v_mfma_f32_16x16x32_bf16 v[114:117], v[188:191], v[200:203], v[114:117]
	v_mfma_f32_16x16x32_bf16 v[102:105], v[180:183], v[208:211], v[102:105]
	v_mfma_f32_16x16x32_bf16 v[98:101], v[188:191], v[208:211], v[98:101]
	v_mfma_f32_16x16x32_bf16 v[86:89], v[180:183], v[216:219], v[86:89]
	v_mfma_f32_16x16x32_bf16 v[82:85], v[188:191], v[216:219], v[82:85]
	v_mfma_f32_16x16x32_bf16 v[70:73], v[180:183], v[224:227], v[70:73]
	v_mfma_f32_16x16x32_bf16 v[66:69], v[188:191], v[224:227], v[66:69]
	s_setprio 0
	s_barrier
	s_add_i32 s81, s71, s62
	v_lshl_add_u64 v[156:157], s[48:49], 0, v[134:135]
	s_mov_b32 m0, s81
	ds_read_b128 v[196:199], v162 offset:16384
	ds_read_b128 v[200:203], v162 offset:17408
	ds_read_b128 v[204:207], v162 offset:18432
	ds_read_b128 v[208:211], v162 offset:19456
	ds_read_b128 v[212:215], v162 offset:20480
	ds_read_b128 v[216:219], v162 offset:21504
	ds_read_b128 v[220:223], v162 offset:22528
	ds_read_b128 v[224:227], v162 offset:23552
	global_load_lds_dwordx4 v[156:157], off
	s_add_i32 m0, s81, 0x2000
	s_add_u32 s82, s48, 0x20000
	v_lshl_add_u64 v[192:193], s[48:49], 0, v[138:139]
	s_addc_u32 s83, s49, 0
	s_add_i32 s81, s72, s62
	global_load_lds_dwordx4 v[192:193], off
	v_lshl_add_u64 v[228:229], s[82:83], 0, v[134:135]
	s_mov_b32 m0, s81
	v_lshl_add_u64 v[230:231], s[60:61], 0, v[136:137]
	global_load_lds_dwordx4 v[228:229], off
	v_lshl_add_u64 v[228:229], s[82:83], 0, v[138:139]
	s_add_i32 m0, s81, 0x2000
	s_nop 0
	global_load_lds_dwordx4 v[228:229], off
	v_lshl_add_u64 v[228:229], s[60:61], 0, v[132:133]
	s_mov_b32 m0, s55
	s_nop 0
	global_load_lds_dwordx4 v[228:229], off
	s_mov_b32 m0, s57
	s_nop 0
	global_load_lds_dwordx4 v[230:231], off
	s_waitcnt vmcnt(8)
	s_waitcnt lgkmcnt(0)
	s_setprio 1
	s_barrier
	v_mfma_f32_16x16x32_bf16 v[62:65], v[152:155], v[196:199], v[62:65]
	v_mfma_f32_16x16x32_bf16 v[58:61], v[168:171], v[196:199], v[58:61]
	v_mfma_f32_16x16x32_bf16 v[46:49], v[152:155], v[204:207], v[46:49]
	v_mfma_f32_16x16x32_bf16 v[42:45], v[168:171], v[204:207], v[42:45]
	v_mfma_f32_16x16x32_bf16 v[30:33], v[152:155], v[212:215], v[30:33]
	v_mfma_f32_16x16x32_bf16 v[26:29], v[168:171], v[212:215], v[26:29]
	v_mfma_f32_16x16x32_bf16 v[14:17], v[152:155], v[220:223], v[14:17]
	v_mfma_f32_16x16x32_bf16 v[10:13], v[168:171], v[220:223], v[10:13]
	v_mfma_f32_16x16x32_bf16 v[62:65], v[164:167], v[200:203], v[62:65]
	v_mfma_f32_16x16x32_bf16 v[58:61], v[172:175], v[200:203], v[58:61]
	v_mfma_f32_16x16x32_bf16 v[46:49], v[164:167], v[208:211], v[46:49]
	v_mfma_f32_16x16x32_bf16 v[42:45], v[172:175], v[208:211], v[42:45]
	v_mfma_f32_16x16x32_bf16 v[30:33], v[164:167], v[216:219], v[30:33]
	v_mfma_f32_16x16x32_bf16 v[26:29], v[172:175], v[216:219], v[26:29]
	v_mfma_f32_16x16x32_bf16 v[14:17], v[164:167], v[224:227], v[14:17]
	v_mfma_f32_16x16x32_bf16 v[10:13], v[172:175], v[224:227], v[10:13]
	v_mfma_f32_16x16x32_bf16 v[54:57], v[176:179], v[196:199], v[54:57]
	v_mfma_f32_16x16x32_bf16 v[50:53], v[184:187], v[196:199], v[50:53]
	v_mfma_f32_16x16x32_bf16 v[38:41], v[176:179], v[204:207], v[38:41]
	v_mfma_f32_16x16x32_bf16 v[34:37], v[184:187], v[204:207], v[34:37]
	v_mfma_f32_16x16x32_bf16 v[22:25], v[176:179], v[212:215], v[22:25]
	v_mfma_f32_16x16x32_bf16 v[18:21], v[184:187], v[212:215], v[18:21]
	v_mfma_f32_16x16x32_bf16 v[6:9], v[176:179], v[220:223], v[6:9]
	v_mfma_f32_16x16x32_bf16 v[2:5], v[184:187], v[220:223], v[2:5]
	v_mfma_f32_16x16x32_bf16 v[54:57], v[180:183], v[200:203], v[54:57]
	v_mfma_f32_16x16x32_bf16 v[50:53], v[188:191], v[200:203], v[50:53]
	v_mfma_f32_16x16x32_bf16 v[38:41], v[180:183], v[208:211], v[38:41]
	v_mfma_f32_16x16x32_bf16 v[34:37], v[188:191], v[208:211], v[34:37]
	v_mfma_f32_16x16x32_bf16 v[22:25], v[180:183], v[216:219], v[22:25]
	v_mfma_f32_16x16x32_bf16 v[18:21], v[188:191], v[216:219], v[18:21]
	v_mfma_f32_16x16x32_bf16 v[6:9], v[180:183], v[224:227], v[6:9]
	v_mfma_f32_16x16x32_bf16 v[2:5], v[188:191], v[224:227], v[2:5]
	s_setprio 0
	s_barrier
	s_add_i32 s81, 0, 0x18000
	v_add_u32_e32 v163, s81, v158
	s_add_i32 s82, 0, 0x1c000
	ds_read_b128 v[152:155], v163
	ds_read_b128 v[164:167], v163 offset:1024
	ds_read_b128 v[168:171], v163 offset:2048
	ds_read_b128 v[172:175], v163 offset:3072
	v_add_u32_e32 v163, s82, v158
	ds_read_b128 v[176:179], v163
	ds_read_b128 v[180:183], v163 offset:1024
	ds_read_b128 v[184:187], v163 offset:2048
	ds_read_b128 v[188:191], v163 offset:3072
	s_add_u32 s60, s60, 0x20000
	s_addc_u32 s61, s61, 0
	s_mov_b32 m0, s63
	v_lshl_add_u64 v[232:233], s[60:61], 0, v[132:133]
	ds_read_b128 v[196:199], v162 offset:32768
	ds_read_b128 v[200:203], v162 offset:33792
	ds_read_b128 v[204:207], v162 offset:34816
	ds_read_b128 v[208:211], v162 offset:35840
	ds_read_b128 v[212:215], v162 offset:36864
	ds_read_b128 v[216:219], v162 offset:37888
	ds_read_b128 v[220:223], v162 offset:38912
	ds_read_b128 v[224:227], v162 offset:39936
	global_load_lds_dwordx4 v[232:233], off
	v_lshl_add_u64 v[232:233], s[60:61], 0, v[136:137]
	s_mov_b32 m0, s64
	s_nop 0
	global_load_lds_dwordx4 v[232:233], off
	s_waitcnt vmcnt(8)
	s_waitcnt lgkmcnt(0)
	s_setprio 1
	s_barrier
	v_mfma_f32_16x16x32_bf16 v[126:129], v[152:155], v[196:199], v[126:129]
	v_mfma_f32_16x16x32_bf16 v[122:125], v[168:171], v[196:199], v[122:125]
	v_mfma_f32_16x16x32_bf16 v[110:113], v[152:155], v[204:207], v[110:113]
	v_mfma_f32_16x16x32_bf16 v[106:109], v[168:171], v[204:207], v[106:109]
	v_mfma_f32_16x16x32_bf16 v[94:97], v[152:155], v[212:215], v[94:97]
	v_mfma_f32_16x16x32_bf16 v[90:93], v[168:171], v[212:215], v[90:93]
	v_mfma_f32_16x16x32_bf16 v[78:81], v[152:155], v[220:223], v[78:81]
	v_mfma_f32_16x16x32_bf16 v[74:77], v[168:171], v[220:223], v[74:77]
	v_mfma_f32_16x16x32_bf16 v[126:129], v[164:167], v[200:203], v[126:129]
	v_mfma_f32_16x16x32_bf16 v[122:125], v[172:175], v[200:203], v[122:125]
	v_mfma_f32_16x16x32_bf16 v[110:113], v[164:167], v[208:211], v[110:113]
	v_mfma_f32_16x16x32_bf16 v[106:109], v[172:175], v[208:211], v[106:109]
	v_mfma_f32_16x16x32_bf16 v[94:97], v[164:167], v[216:219], v[94:97]
	v_mfma_f32_16x16x32_bf16 v[90:93], v[172:175], v[216:219], v[90:93]
	v_mfma_f32_16x16x32_bf16 v[78:81], v[164:167], v[224:227], v[78:81]
	v_mfma_f32_16x16x32_bf16 v[74:77], v[172:175], v[224:227], v[74:77]
	v_mfma_f32_16x16x32_bf16 v[118:121], v[176:179], v[196:199], v[118:121]
	v_mfma_f32_16x16x32_bf16 v[114:117], v[184:187], v[196:199], v[114:117]
	v_mfma_f32_16x16x32_bf16 v[102:105], v[176:179], v[204:207], v[102:105]
	v_mfma_f32_16x16x32_bf16 v[98:101], v[184:187], v[204:207], v[98:101]
	v_mfma_f32_16x16x32_bf16 v[86:89], v[176:179], v[212:215], v[86:89]
	v_mfma_f32_16x16x32_bf16 v[82:85], v[184:187], v[212:215], v[82:85]
	v_mfma_f32_16x16x32_bf16 v[70:73], v[176:179], v[220:223], v[70:73]
	v_mfma_f32_16x16x32_bf16 v[66:69], v[184:187], v[220:223], v[66:69]
	v_mfma_f32_16x16x32_bf16 v[118:121], v[180:183], v[200:203], v[118:121]
	v_mfma_f32_16x16x32_bf16 v[114:117], v[188:191], v[200:203], v[114:117]
	v_mfma_f32_16x16x32_bf16 v[102:105], v[180:183], v[208:211], v[102:105]
	v_mfma_f32_16x16x32_bf16 v[98:101], v[188:191], v[208:211], v[98:101]
	v_mfma_f32_16x16x32_bf16 v[86:89], v[180:183], v[216:219], v[86:89]
	v_mfma_f32_16x16x32_bf16 v[82:85], v[188:191], v[216:219], v[82:85]
	v_mfma_f32_16x16x32_bf16 v[70:73], v[180:183], v[224:227], v[70:73]
	v_mfma_f32_16x16x32_bf16 v[66:69], v[188:191], v[224:227], v[66:69]
	s_setprio 0
	s_barrier
	s_add_i32 s60, s81, s62
	v_lshl_add_u64 v[156:157], v[156:157], 0, s[14:15]
	s_mov_b32 m0, s60
	ds_read_b128 v[196:199], v162 offset:49152
	ds_read_b128 v[200:203], v162 offset:50176
	ds_read_b128 v[204:207], v162 offset:51200
	ds_read_b128 v[208:211], v162 offset:52224
	ds_read_b128 v[212:215], v162 offset:53248
	ds_read_b128 v[216:219], v162 offset:54272
	ds_read_b128 v[220:223], v162 offset:55296
	ds_read_b128 v[224:227], v162 offset:56320
	global_load_lds_dwordx4 v[156:157], off
	s_add_i32 m0, s60, 0x2000
	s_add_u32 s48, s48, 0x20080
	v_lshl_add_u64 v[156:157], v[192:193], 0, s[14:15]
	s_addc_u32 s49, s49, 0
	s_add_i32 s60, s82, s62
	global_load_lds_dwordx4 v[156:157], off
	v_lshl_add_u64 v[156:157], s[48:49], 0, v[134:135]
	s_mov_b32 m0, s60
	s_nop 0
	global_load_lds_dwordx4 v[156:157], off
	v_lshl_add_u64 v[156:157], s[48:49], 0, v[138:139]
	s_add_i32 m0, s60, 0x2000
	s_nop 0
	global_load_lds_dwordx4 v[156:157], off
	v_lshl_add_u64 v[156:157], v[228:229], 0, s[14:15]
	s_mov_b32 m0, s68
	s_nop 0
	global_load_lds_dwordx4 v[156:157], off
	v_lshl_add_u64 v[156:157], v[230:231], 0, s[14:15]
	s_mov_b32 m0, s69
	s_nop 0
	global_load_lds_dwordx4 v[156:157], off
	s_nop 0
	s_waitcnt vmcnt(8)
	s_waitcnt lgkmcnt(0)
	s_setprio 1
	s_barrier
	v_mfma_f32_16x16x32_bf16 v[62:65], v[152:155], v[196:199], v[62:65]
	v_mfma_f32_16x16x32_bf16 v[58:61], v[168:171], v[196:199], v[58:61]
	v_mfma_f32_16x16x32_bf16 v[46:49], v[152:155], v[204:207], v[46:49]
	v_mfma_f32_16x16x32_bf16 v[42:45], v[168:171], v[204:207], v[42:45]
	v_mfma_f32_16x16x32_bf16 v[30:33], v[152:155], v[212:215], v[30:33]
	v_mfma_f32_16x16x32_bf16 v[26:29], v[168:171], v[212:215], v[26:29]
	v_mfma_f32_16x16x32_bf16 v[14:17], v[152:155], v[220:223], v[14:17]
	v_mfma_f32_16x16x32_bf16 v[10:13], v[168:171], v[220:223], v[10:13]
	v_mfma_f32_16x16x32_bf16 v[62:65], v[164:167], v[200:203], v[62:65]
	v_mfma_f32_16x16x32_bf16 v[58:61], v[172:175], v[200:203], v[58:61]
	v_mfma_f32_16x16x32_bf16 v[46:49], v[164:167], v[208:211], v[46:49]
	v_mfma_f32_16x16x32_bf16 v[42:45], v[172:175], v[208:211], v[42:45]
	v_mfma_f32_16x16x32_bf16 v[30:33], v[164:167], v[216:219], v[30:33]
	v_mfma_f32_16x16x32_bf16 v[26:29], v[172:175], v[216:219], v[26:29]
	v_mfma_f32_16x16x32_bf16 v[14:17], v[164:167], v[224:227], v[14:17]
	v_mfma_f32_16x16x32_bf16 v[10:13], v[172:175], v[224:227], v[10:13]
	v_mfma_f32_16x16x32_bf16 v[54:57], v[176:179], v[196:199], v[54:57]
	v_mfma_f32_16x16x32_bf16 v[50:53], v[184:187], v[196:199], v[50:53]
	v_mfma_f32_16x16x32_bf16 v[38:41], v[176:179], v[204:207], v[38:41]
	v_mfma_f32_16x16x32_bf16 v[34:37], v[184:187], v[204:207], v[34:37]
	v_mfma_f32_16x16x32_bf16 v[22:25], v[176:179], v[212:215], v[22:25]
	v_mfma_f32_16x16x32_bf16 v[18:21], v[184:187], v[212:215], v[18:21]
	v_mfma_f32_16x16x32_bf16 v[6:9], v[176:179], v[220:223], v[6:9]
	v_mfma_f32_16x16x32_bf16 v[2:5], v[184:187], v[220:223], v[2:5]
	v_mfma_f32_16x16x32_bf16 v[54:57], v[180:183], v[200:203], v[54:57]
	v_mfma_f32_16x16x32_bf16 v[50:53], v[188:191], v[200:203], v[50:53]
	v_mfma_f32_16x16x32_bf16 v[38:41], v[180:183], v[208:211], v[38:41]
	v_mfma_f32_16x16x32_bf16 v[34:37], v[188:191], v[208:211], v[34:37]
	v_mfma_f32_16x16x32_bf16 v[22:25], v[180:183], v[216:219], v[22:25]
	v_mfma_f32_16x16x32_bf16 v[18:21], v[188:191], v[216:219], v[18:21]
	v_mfma_f32_16x16x32_bf16 v[6:9], v[180:183], v[224:227], v[6:9]
	v_mfma_f32_16x16x32_bf16 v[2:5], v[188:191], v[224:227], v[2:5]
	s_setprio 0
	s_barrier
	s_add_u32 s58, s58, 0x100
	s_addc_u32 s59, s59, 0
	s_add_u32 s47, s47, 0x100
	s_addc_u32 s51, s51, 0
	s_cmp_ge_i32 s80, s79
	s_mov_b32 s48, s80
	s_cbranch_scc0 .LBB0_3983
	s_and_b64 vcc, exec, s[16:17]
	s_cbranch_vccz .LBB0_3986
	s_barrier

.LBB0_4145:
	ds_read_b128 v[156:159], v162
	ds_read_b128 v[166:169], v162 offset:1024
	ds_read_b128 v[170:173], v162 offset:2048
	ds_read_b128 v[174:177], v162 offset:3072
	ds_read_b128 v[178:181], v163
	ds_read_b128 v[182:185], v163 offset:1024
	ds_read_b128 v[186:189], v163 offset:2048
	ds_read_b128 v[190:193], v163 offset:3072
	s_add_i32 s72, s42, 2
	s_add_u32 s43, s40, 0xfff00080
	s_addc_u32 s46, s41, -1
	s_cmp_eq_u32 s69, s42
	s_cselect_b32 s42, s25, s70
	s_cselect_b32 s47, s5, s46
	s_cselect_b32 s46, s23, s43
	s_cselect_b32 s43, s21, s71
	v_lshl_add_u64 v[228:229], s[40:41], 0, v[148:149]
	s_add_i32 m0, s35, 0xc000
	ds_read_b128 v[196:199], v164
	ds_read_b128 v[200:203], v164 offset:1024
	ds_read_b128 v[204:207], v164 offset:2048
	ds_read_b128 v[208:211], v164 offset:3072
	ds_read_b128 v[212:215], v164 offset:4096
	ds_read_b128 v[216:219], v164 offset:5120
	ds_read_b128 v[220:223], v164 offset:6144
	ds_read_b128 v[224:227], v164 offset:7168
	global_load_lds_dwordx4 v[228:229], off
	v_lshl_add_u64 v[228:229], s[40:41], 0, v[150:151]
	s_add_i32 m0, s35, 0xe000
	s_nop 0
	global_load_lds_dwordx4 v[228:229], off
	s_nop 0
	s_waitcnt vmcnt(8)
	s_waitcnt lgkmcnt(0)
	s_setprio 1
	s_barrier
	v_mfma_f32_16x16x32_bf16 v[78:81], v[156:159], v[196:199], v[78:81]
	v_mfma_f32_16x16x32_bf16 v[74:77], v[170:173], v[196:199], v[74:77]
	v_mfma_f32_16x16x32_bf16 v[70:73], v[156:159], v[204:207], v[70:73]
	v_mfma_f32_16x16x32_bf16 v[62:65], v[170:173], v[204:207], v[62:65]
	v_mfma_f32_16x16x32_bf16 v[58:61], v[156:159], v[212:215], v[58:61]
	v_mfma_f32_16x16x32_bf16 v[54:57], v[170:173], v[212:215], v[54:57]
	v_mfma_f32_16x16x32_bf16 v[46:49], v[156:159], v[220:223], v[46:49]
	v_mfma_f32_16x16x32_bf16 v[38:41], v[170:173], v[220:223], v[38:41]
	v_mfma_f32_16x16x32_bf16 v[78:81], v[166:169], v[200:203], v[78:81]
	v_mfma_f32_16x16x32_bf16 v[74:77], v[174:177], v[200:203], v[74:77]
	v_mfma_f32_16x16x32_bf16 v[70:73], v[166:169], v[208:211], v[70:73]
	v_mfma_f32_16x16x32_bf16 v[62:65], v[174:177], v[208:211], v[62:65]
	v_mfma_f32_16x16x32_bf16 v[58:61], v[166:169], v[216:219], v[58:61]
	v_mfma_f32_16x16x32_bf16 v[54:57], v[174:177], v[216:219], v[54:57]
	v_mfma_f32_16x16x32_bf16 v[46:49], v[166:169], v[224:227], v[46:49]
	v_mfma_f32_16x16x32_bf16 v[38:41], v[174:177], v[224:227], v[38:41]
	v_mfma_f32_16x16x32_bf16 v[50:53], v[178:181], v[196:199], v[50:53]
	v_mfma_f32_16x16x32_bf16 v[42:45], v[186:189], v[196:199], v[42:45]
	v_mfma_f32_16x16x32_bf16 v[34:37], v[178:181], v[204:207], v[34:37]
	v_mfma_f32_16x16x32_bf16 v[26:29], v[186:189], v[204:207], v[26:29]
	v_mfma_f32_16x16x32_bf16 v[18:21], v[178:181], v[212:215], v[18:21]
	v_mfma_f32_16x16x32_bf16 v[14:17], v[186:189], v[212:215], v[14:17]
	v_mfma_f32_16x16x32_bf16 v[10:13], v[178:181], v[220:223], v[10:13]
	v_mfma_f32_16x16x32_bf16 v[6:9], v[186:189], v[220:223], v[6:9]
	v_mfma_f32_16x16x32_bf16 v[50:53], v[182:185], v[200:203], v[50:53]
	v_mfma_f32_16x16x32_bf16 v[42:45], v[190:193], v[200:203], v[42:45]
	v_mfma_f32_16x16x32_bf16 v[34:37], v[182:185], v[208:211], v[34:37]
	v_mfma_f32_16x16x32_bf16 v[26:29], v[190:193], v[208:211], v[26:29]
	v_mfma_f32_16x16x32_bf16 v[18:21], v[182:185], v[216:219], v[18:21]
	v_mfma_f32_16x16x32_bf16 v[14:17], v[190:193], v[216:219], v[14:17]
	v_mfma_f32_16x16x32_bf16 v[10:13], v[182:185], v[224:227], v[10:13]
	v_mfma_f32_16x16x32_bf16 v[6:9], v[190:193], v[224:227], v[6:9]
	s_setprio 0
	s_barrier
	s_add_i32 s73, s62, s49
	v_lshl_add_u64 v[228:229], s[42:43], 0, v[134:135]
	s_mov_b32 m0, s73
	ds_read_b128 v[196:199], v164 offset:16384
	ds_read_b128 v[200:203], v164 offset:17408
	ds_read_b128 v[204:207], v164 offset:18432
	ds_read_b128 v[208:211], v164 offset:19456
	ds_read_b128 v[212:215], v164 offset:20480
	ds_read_b128 v[216:219], v164 offset:21504
	ds_read_b128 v[220:223], v164 offset:22528
	ds_read_b128 v[224:227], v164 offset:23552
	global_load_lds_dwordx4 v[228:229], off
	s_add_i32 m0, s73, 0x2000
	s_add_u32 s74, s42, 0x100000
	v_lshl_add_u64 v[230:231], s[42:43], 0, v[138:139]
	s_addc_u32 s75, s43, 0
	s_add_i32 s73, s63, s49
	global_load_lds_dwordx4 v[230:231], off
	v_lshl_add_u64 v[232:233], s[74:75], 0, v[134:135]
	s_mov_b32 m0, s73
	v_lshl_add_u64 v[234:235], s[46:47], 0, v[136:137]
	global_load_lds_dwordx4 v[232:233], off
	v_lshl_add_u64 v[232:233], s[74:75], 0, v[138:139]
	s_add_i32 m0, s73, 0x2000
	s_nop 0
	global_load_lds_dwordx4 v[232:233], off
	v_lshl_add_u64 v[232:233], s[46:47], 0, v[132:133]
	s_mov_b32 m0, s35
	s_nop 0
	global_load_lds_dwordx4 v[232:233], off
	s_mov_b32 m0, s50
	s_nop 0
	global_load_lds_dwordx4 v[234:235], off
	s_waitcnt vmcnt(8)
	s_waitcnt lgkmcnt(0)
	s_setprio 1
	s_barrier
	v_mfma_f32_16x16x32_bf16 v[126:129], v[156:159], v[196:199], v[126:129]
	v_mfma_f32_16x16x32_bf16 v[118:121], v[170:173], v[196:199], v[118:121]
	v_mfma_f32_16x16x32_bf16 v[110:113], v[156:159], v[204:207], v[110:113]
	v_mfma_f32_16x16x32_bf16 v[102:105], v[170:173], v[204:207], v[102:105]
	v_mfma_f32_16x16x32_bf16 v[94:97], v[156:159], v[212:215], v[94:97]
	v_mfma_f32_16x16x32_bf16 v[86:89], v[170:173], v[212:215], v[86:89]
	v_mfma_f32_16x16x32_bf16 v[66:69], v[156:159], v[220:223], v[66:69]
	v_mfma_f32_16x16x32_bf16 v[22:25], v[170:173], v[220:223], v[22:25]
	v_mfma_f32_16x16x32_bf16 v[126:129], v[166:169], v[200:203], v[126:129]
	v_mfma_f32_16x16x32_bf16 v[118:121], v[174:177], v[200:203], v[118:121]
	v_mfma_f32_16x16x32_bf16 v[110:113], v[166:169], v[208:211], v[110:113]
	v_mfma_f32_16x16x32_bf16 v[102:105], v[174:177], v[208:211], v[102:105]
	v_mfma_f32_16x16x32_bf16 v[94:97], v[166:169], v[216:219], v[94:97]
	v_mfma_f32_16x16x32_bf16 v[86:89], v[174:177], v[216:219], v[86:89]
	v_mfma_f32_16x16x32_bf16 v[66:69], v[166:169], v[224:227], v[66:69]
	v_mfma_f32_16x16x32_bf16 v[22:25], v[174:177], v[224:227], v[22:25]
	v_mfma_f32_16x16x32_bf16 v[122:125], v[178:181], v[196:199], v[122:125]
	v_mfma_f32_16x16x32_bf16 v[114:117], v[186:189], v[196:199], v[114:117]
	v_mfma_f32_16x16x32_bf16 v[106:109], v[178:181], v[204:207], v[106:109]
	v_mfma_f32_16x16x32_bf16 v[98:101], v[186:189], v[204:207], v[98:101]
	v_mfma_f32_16x16x32_bf16 v[90:93], v[178:181], v[212:215], v[90:93]
	v_mfma_f32_16x16x32_bf16 v[82:85], v[186:189], v[212:215], v[82:85]
	v_mfma_f32_16x16x32_bf16 v[30:33], v[178:181], v[220:223], v[30:33]
	v_mfma_f32_16x16x32_bf16 v[2:5], v[186:189], v[220:223], v[2:5]
	v_mfma_f32_16x16x32_bf16 v[122:125], v[182:185], v[200:203], v[122:125]
	v_mfma_f32_16x16x32_bf16 v[114:117], v[190:193], v[200:203], v[114:117]
	v_mfma_f32_16x16x32_bf16 v[106:109], v[182:185], v[208:211], v[106:109]
	v_mfma_f32_16x16x32_bf16 v[98:101], v[190:193], v[208:211], v[98:101]
	v_mfma_f32_16x16x32_bf16 v[90:93], v[182:185], v[216:219], v[90:93]
	v_mfma_f32_16x16x32_bf16 v[82:85], v[190:193], v[216:219], v[82:85]
	v_mfma_f32_16x16x32_bf16 v[30:33], v[182:185], v[224:227], v[30:33]
	v_mfma_f32_16x16x32_bf16 v[2:5], v[190:193], v[224:227], v[2:5]
	s_setprio 0
	s_barrier
	s_add_i32 s73, 0, 0x18000
	v_add_u32_e32 v165, s73, v160
	s_add_i32 s74, 0, 0x1c000
	ds_read_b128 v[156:159], v165
	ds_read_b128 v[166:169], v165 offset:1024
	ds_read_b128 v[170:173], v165 offset:2048
	ds_read_b128 v[174:177], v165 offset:3072
	v_add_u32_e32 v165, s74, v160
	ds_read_b128 v[178:181], v165
	ds_read_b128 v[182:185], v165 offset:1024
	ds_read_b128 v[186:189], v165 offset:2048
	ds_read_b128 v[190:193], v165 offset:3072
	s_add_u32 s46, s46, 0x100000
	s_addc_u32 s47, s47, 0
	s_mov_b32 m0, s51
	v_lshl_add_u64 v[236:237], s[46:47], 0, v[132:133]
	ds_read_b128 v[196:199], v164 offset:32768
	ds_read_b128 v[200:203], v164 offset:33792
	ds_read_b128 v[204:207], v164 offset:34816
	ds_read_b128 v[208:211], v164 offset:35840
	ds_read_b128 v[212:215], v164 offset:36864
	ds_read_b128 v[216:219], v164 offset:37888
	ds_read_b128 v[220:223], v164 offset:38912
	ds_read_b128 v[224:227], v164 offset:39936
	global_load_lds_dwordx4 v[236:237], off
	v_lshl_add_u64 v[236:237], s[46:47], 0, v[136:137]
	s_mov_b32 m0, s52
	s_nop 0
	global_load_lds_dwordx4 v[236:237], off
	s_waitcnt vmcnt(8)
	s_waitcnt lgkmcnt(0)
	s_setprio 1
	s_barrier
	v_mfma_f32_16x16x32_bf16 v[78:81], v[156:159], v[196:199], v[78:81]
	v_mfma_f32_16x16x32_bf16 v[74:77], v[170:173], v[196:199], v[74:77]
	v_mfma_f32_16x16x32_bf16 v[70:73], v[156:159], v[204:207], v[70:73]
	v_mfma_f32_16x16x32_bf16 v[62:65], v[170:173], v[204:207], v[62:65]
	v_mfma_f32_16x16x32_bf16 v[58:61], v[156:159], v[212:215], v[58:61]
	v_mfma_f32_16x16x32_bf16 v[54:57], v[170:173], v[212:215], v[54:57]
	v_mfma_f32_16x16x32_bf16 v[46:49], v[156:159], v[220:223], v[46:49]
	v_mfma_f32_16x16x32_bf16 v[38:41], v[170:173], v[220:223], v[38:41]
	v_mfma_f32_16x16x32_bf16 v[78:81], v[166:169], v[200:203], v[78:81]
	v_mfma_f32_16x16x32_bf16 v[74:77], v[174:177], v[200:203], v[74:77]
	v_mfma_f32_16x16x32_bf16 v[70:73], v[166:169], v[208:211], v[70:73]
	v_mfma_f32_16x16x32_bf16 v[62:65], v[174:177], v[208:211], v[62:65]
	v_mfma_f32_16x16x32_bf16 v[58:61], v[166:169], v[216:219], v[58:61]
	v_mfma_f32_16x16x32_bf16 v[54:57], v[174:177], v[216:219], v[54:57]
	v_mfma_f32_16x16x32_bf16 v[46:49], v[166:169], v[224:227], v[46:49]
	v_mfma_f32_16x16x32_bf16 v[38:41], v[174:177], v[224:227], v[38:41]
	v_mfma_f32_16x16x32_bf16 v[50:53], v[178:181], v[196:199], v[50:53]
	v_mfma_f32_16x16x32_bf16 v[42:45], v[186:189], v[196:199], v[42:45]
	v_mfma_f32_16x16x32_bf16 v[34:37], v[178:181], v[204:207], v[34:37]
	v_mfma_f32_16x16x32_bf16 v[26:29], v[186:189], v[204:207], v[26:29]
	v_mfma_f32_16x16x32_bf16 v[18:21], v[178:181], v[212:215], v[18:21]
	v_mfma_f32_16x16x32_bf16 v[14:17], v[186:189], v[212:215], v[14:17]
	v_mfma_f32_16x16x32_bf16 v[10:13], v[178:181], v[220:223], v[10:13]
	v_mfma_f32_16x16x32_bf16 v[6:9], v[186:189], v[220:223], v[6:9]
	v_mfma_f32_16x16x32_bf16 v[50:53], v[182:185], v[200:203], v[50:53]
	v_mfma_f32_16x16x32_bf16 v[42:45], v[190:193], v[200:203], v[42:45]
	v_mfma_f32_16x16x32_bf16 v[34:37], v[182:185], v[208:211], v[34:37]
	v_mfma_f32_16x16x32_bf16 v[26:29], v[190:193], v[208:211], v[26:29]
	v_mfma_f32_16x16x32_bf16 v[18:21], v[182:185], v[216:219], v[18:21]
	v_mfma_f32_16x16x32_bf16 v[14:17], v[190:193], v[216:219], v[14:17]
	v_mfma_f32_16x16x32_bf16 v[10:13], v[182:185], v[224:227], v[10:13]
	v_mfma_f32_16x16x32_bf16 v[6:9], v[190:193], v[224:227], v[6:9]
	s_setprio 0
	s_barrier
	s_add_i32 s46, s73, s49
	v_lshl_add_u64 v[228:229], v[228:229], 0, s[10:11]
	s_mov_b32 m0, s46
	ds_read_b128 v[196:199], v164 offset:49152
	ds_read_b128 v[200:203], v164 offset:50176
	ds_read_b128 v[204:207], v164 offset:51200
	ds_read_b128 v[208:211], v164 offset:52224
	ds_read_b128 v[212:215], v164 offset:53248
	ds_read_b128 v[216:219], v164 offset:54272
	ds_read_b128 v[220:223], v164 offset:55296
	ds_read_b128 v[224:227], v164 offset:56320
	global_load_lds_dwordx4 v[228:229], off
	s_add_i32 m0, s46, 0x2000
	s_add_u32 s42, s42, 0x100080
	v_lshl_add_u64 v[228:229], v[230:231], 0, s[10:11]
	s_addc_u32 s43, s43, 0
	s_add_i32 s46, s74, s49
	global_load_lds_dwordx4 v[228:229], off
	v_lshl_add_u64 v[228:229], s[42:43], 0, v[134:135]
	s_mov_b32 m0, s46
	s_nop 0
	global_load_lds_dwordx4 v[228:229], off
	v_lshl_add_u64 v[228:229], s[42:43], 0, v[138:139]
	s_add_i32 m0, s46, 0x2000
	s_nop 0
	global_load_lds_dwordx4 v[228:229], off
	v_lshl_add_u64 v[228:229], v[232:233], 0, s[10:11]
	s_mov_b32 m0, s55
	s_nop 0
	global_load_lds_dwordx4 v[228:229], off
	v_lshl_add_u64 v[228:229], v[234:235], 0, s[10:11]
	s_mov_b32 m0, s56
	s_nop 0
	global_load_lds_dwordx4 v[228:229], off
	s_nop 0
	s_waitcnt vmcnt(8)
	s_waitcnt lgkmcnt(0)
	s_setprio 1
	s_barrier
	v_mfma_f32_16x16x32_bf16 v[126:129], v[156:159], v[196:199], v[126:129]
	v_mfma_f32_16x16x32_bf16 v[118:121], v[170:173], v[196:199], v[118:121]
	v_mfma_f32_16x16x32_bf16 v[110:113], v[156:159], v[204:207], v[110:113]
	v_mfma_f32_16x16x32_bf16 v[102:105], v[170:173], v[204:207], v[102:105]
	v_mfma_f32_16x16x32_bf16 v[94:97], v[156:159], v[212:215], v[94:97]
	v_mfma_f32_16x16x32_bf16 v[86:89], v[170:173], v[212:215], v[86:89]
	v_mfma_f32_16x16x32_bf16 v[66:69], v[156:159], v[220:223], v[66:69]
	v_mfma_f32_16x16x32_bf16 v[22:25], v[170:173], v[220:223], v[22:25]
	v_mfma_f32_16x16x32_bf16 v[126:129], v[166:169], v[200:203], v[126:129]
	v_mfma_f32_16x16x32_bf16 v[118:121], v[174:177], v[200:203], v[118:121]
	v_mfma_f32_16x16x32_bf16 v[110:113], v[166:169], v[208:211], v[110:113]
	v_mfma_f32_16x16x32_bf16 v[102:105], v[174:177], v[208:211], v[102:105]
	v_mfma_f32_16x16x32_bf16 v[94:97], v[166:169], v[216:219], v[94:97]
	v_mfma_f32_16x16x32_bf16 v[86:89], v[174:177], v[216:219], v[86:89]
	v_mfma_f32_16x16x32_bf16 v[66:69], v[166:169], v[224:227], v[66:69]
	v_mfma_f32_16x16x32_bf16 v[22:25], v[174:177], v[224:227], v[22:25]
	v_mfma_f32_16x16x32_bf16 v[122:125], v[178:181], v[196:199], v[122:125]
	v_mfma_f32_16x16x32_bf16 v[114:117], v[186:189], v[196:199], v[114:117]
	v_mfma_f32_16x16x32_bf16 v[106:109], v[178:181], v[204:207], v[106:109]
	v_mfma_f32_16x16x32_bf16 v[98:101], v[186:189], v[204:207], v[98:101]
	v_mfma_f32_16x16x32_bf16 v[90:93], v[178:181], v[212:215], v[90:93]
	v_mfma_f32_16x16x32_bf16 v[82:85], v[186:189], v[212:215], v[82:85]
	v_mfma_f32_16x16x32_bf16 v[30:33], v[178:181], v[220:223], v[30:33]
	v_mfma_f32_16x16x32_bf16 v[2:5], v[186:189], v[220:223], v[2:5]
	v_mfma_f32_16x16x32_bf16 v[122:125], v[182:185], v[200:203], v[122:125]
	v_mfma_f32_16x16x32_bf16 v[114:117], v[190:193], v[200:203], v[114:117]
	v_mfma_f32_16x16x32_bf16 v[106:109], v[182:185], v[208:211], v[106:109]
	v_mfma_f32_16x16x32_bf16 v[98:101], v[190:193], v[208:211], v[98:101]
	v_mfma_f32_16x16x32_bf16 v[90:93], v[182:185], v[216:219], v[90:93]
	v_mfma_f32_16x16x32_bf16 v[82:85], v[190:193], v[216:219], v[82:85]
	v_mfma_f32_16x16x32_bf16 v[30:33], v[182:185], v[224:227], v[30:33]
	v_mfma_f32_16x16x32_bf16 v[2:5], v[190:193], v[224:227], v[2:5]
	s_setprio 0
	s_barrier
	s_add_u32 s40, s40, 0x100
	s_addc_u32 s41, s41, 0
	s_add_u32 s70, s70, 0x100
	s_addc_u32 s71, s71, 0
	s_cmp_ge_i32 s72, s68
	s_mov_b32 s42, s72
	s_cbranch_scc0 .LBB0_4145
	s_and_b64 vcc, exec, s[12:13]
	s_cbranch_vccz .LBB0_4150
	s_barrier
	s_cmp_lt_i32 s48, 0
	s_mov_b64 s[40:41], -1
	s_cbranch_scc1 .LBB0_4151

.LBB0_4304:
	ds_read_b128 v[150:153], v158
	ds_read_b128 v[162:165], v158 offset:1024
	ds_read_b128 v[166:169], v158 offset:2048
	ds_read_b128 v[170:173], v158 offset:3072
	ds_read_b128 v[174:177], v159
	ds_read_b128 v[178:181], v159 offset:1024
	ds_read_b128 v[182:185], v159 offset:2048
	ds_read_b128 v[186:189], v159 offset:3072
	s_add_i32 s80, s48, 2
	s_add_u32 s49, s50, 0xffd50080
	s_addc_u32 s52, s51, -1
	s_cmp_eq_u32 s43, s48
	s_cselect_b32 s48, s46, s78
	s_cselect_b32 s53, s5, s52
	s_cselect_b32 s52, s4, s49
	s_cselect_b32 s49, s47, s79
	v_lshl_add_u64 v[154:155], s[50:51], 0, v[138:139]
	s_add_i32 m0, s55, 0xc000
	ds_read_b128 v[190:193], v160
	ds_read_b128 v[196:199], v160 offset:1024
	ds_read_b128 v[200:203], v160 offset:2048
	ds_read_b128 v[204:207], v160 offset:3072
	ds_read_b128 v[208:211], v160 offset:4096
	ds_read_b128 v[212:215], v160 offset:5120
	ds_read_b128 v[216:219], v160 offset:6144
	ds_read_b128 v[220:223], v160 offset:7168
	global_load_lds_dwordx4 v[154:155], off
	v_lshl_add_u64 v[154:155], s[50:51], 0, v[140:141]
	s_add_i32 m0, s55, 0xe000
	s_nop 0
	global_load_lds_dwordx4 v[154:155], off
	s_nop 0
	s_waitcnt vmcnt(8)
	s_waitcnt lgkmcnt(0)
	s_setprio 1
	s_barrier
	v_mfma_f32_16x16x32_bf16 v[124:127], v[150:153], v[190:193], v[124:127]
	v_mfma_f32_16x16x32_bf16 v[120:123], v[166:169], v[190:193], v[120:123]
	v_mfma_f32_16x16x32_bf16 v[108:111], v[150:153], v[200:203], v[108:111]
	v_mfma_f32_16x16x32_bf16 v[104:107], v[166:169], v[200:203], v[104:107]
	v_mfma_f32_16x16x32_bf16 v[92:95], v[150:153], v[208:211], v[92:95]
	v_mfma_f32_16x16x32_bf16 v[88:91], v[166:169], v[208:211], v[88:91]
	v_mfma_f32_16x16x32_bf16 v[76:79], v[150:153], v[216:219], v[76:79]
	v_mfma_f32_16x16x32_bf16 v[72:75], v[166:169], v[216:219], v[72:75]
	v_mfma_f32_16x16x32_bf16 v[124:127], v[162:165], v[196:199], v[124:127]
	v_mfma_f32_16x16x32_bf16 v[120:123], v[170:173], v[196:199], v[120:123]
	v_mfma_f32_16x16x32_bf16 v[108:111], v[162:165], v[204:207], v[108:111]
	v_mfma_f32_16x16x32_bf16 v[104:107], v[170:173], v[204:207], v[104:107]
	v_mfma_f32_16x16x32_bf16 v[92:95], v[162:165], v[212:215], v[92:95]
	v_mfma_f32_16x16x32_bf16 v[88:91], v[170:173], v[212:215], v[88:91]
	v_mfma_f32_16x16x32_bf16 v[76:79], v[162:165], v[220:223], v[76:79]
	v_mfma_f32_16x16x32_bf16 v[72:75], v[170:173], v[220:223], v[72:75]
	v_mfma_f32_16x16x32_bf16 v[116:119], v[174:177], v[190:193], v[116:119]
	v_mfma_f32_16x16x32_bf16 v[112:115], v[182:185], v[190:193], v[112:115]
	v_mfma_f32_16x16x32_bf16 v[100:103], v[174:177], v[200:203], v[100:103]
	v_mfma_f32_16x16x32_bf16 v[96:99], v[182:185], v[200:203], v[96:99]
	v_mfma_f32_16x16x32_bf16 v[84:87], v[174:177], v[208:211], v[84:87]
	v_mfma_f32_16x16x32_bf16 v[80:83], v[182:185], v[208:211], v[80:83]
	v_mfma_f32_16x16x32_bf16 v[68:71], v[174:177], v[216:219], v[68:71]
	v_mfma_f32_16x16x32_bf16 v[64:67], v[182:185], v[216:219], v[64:67]
	v_mfma_f32_16x16x32_bf16 v[116:119], v[178:181], v[196:199], v[116:119]
	v_mfma_f32_16x16x32_bf16 v[112:115], v[186:189], v[196:199], v[112:115]
	v_mfma_f32_16x16x32_bf16 v[100:103], v[178:181], v[204:207], v[100:103]
	v_mfma_f32_16x16x32_bf16 v[96:99], v[186:189], v[204:207], v[96:99]
	v_mfma_f32_16x16x32_bf16 v[84:87], v[178:181], v[212:215], v[84:87]
	v_mfma_f32_16x16x32_bf16 v[80:83], v[186:189], v[212:215], v[80:83]
	v_mfma_f32_16x16x32_bf16 v[68:71], v[178:181], v[220:223], v[68:71]
	v_mfma_f32_16x16x32_bf16 v[64:67], v[186:189], v[220:223], v[64:67]
	s_setprio 0
	s_barrier
	s_add_i32 s81, s65, s54
	v_lshl_add_u64 v[154:155], s[48:49], 0, v[132:133]
	s_mov_b32 m0, s81
	ds_read_b128 v[190:193], v160 offset:16384
	ds_read_b128 v[196:199], v160 offset:17408
	ds_read_b128 v[200:203], v160 offset:18432
	ds_read_b128 v[204:207], v160 offset:19456
	ds_read_b128 v[208:211], v160 offset:20480
	ds_read_b128 v[212:215], v160 offset:21504
	ds_read_b128 v[216:219], v160 offset:22528
	ds_read_b128 v[220:223], v160 offset:23552
	global_load_lds_dwordx4 v[154:155], off
	s_add_i32 m0, s81, 0x2000
	s_add_u32 s82, s48, 0x2b0000
	v_lshl_add_u64 v[224:225], s[48:49], 0, v[136:137]
	s_addc_u32 s83, s49, 0
	s_add_i32 s81, s66, s54
	global_load_lds_dwordx4 v[224:225], off
	v_lshl_add_u64 v[226:227], s[82:83], 0, v[132:133]
	s_mov_b32 m0, s81
	v_lshl_add_u64 v[228:229], s[52:53], 0, v[134:135]
	global_load_lds_dwordx4 v[226:227], off
	v_lshl_add_u64 v[226:227], s[82:83], 0, v[136:137]
	s_add_i32 m0, s81, 0x2000
	s_nop 0
	global_load_lds_dwordx4 v[226:227], off
	v_lshl_add_u64 v[226:227], s[52:53], 0, v[128:129]
	s_mov_b32 m0, s55
	s_nop 0
	global_load_lds_dwordx4 v[226:227], off
	s_mov_b32 m0, s56
	s_nop 0
	global_load_lds_dwordx4 v[228:229], off
	s_waitcnt vmcnt(8)
	s_waitcnt lgkmcnt(0)
	s_setprio 1
	s_barrier
	v_mfma_f32_16x16x32_bf16 v[60:63], v[150:153], v[190:193], v[60:63]
	v_mfma_f32_16x16x32_bf16 v[56:59], v[166:169], v[190:193], v[56:59]
	v_mfma_f32_16x16x32_bf16 v[44:47], v[150:153], v[200:203], v[44:47]
	v_mfma_f32_16x16x32_bf16 v[40:43], v[166:169], v[200:203], v[40:43]
	v_mfma_f32_16x16x32_bf16 v[28:31], v[150:153], v[208:211], v[28:31]
	v_mfma_f32_16x16x32_bf16 v[24:27], v[166:169], v[208:211], v[24:27]
	v_mfma_f32_16x16x32_bf16 v[12:15], v[150:153], v[216:219], v[12:15]
	v_mfma_f32_16x16x32_bf16 v[8:11], v[166:169], v[216:219], v[8:11]
	v_mfma_f32_16x16x32_bf16 v[60:63], v[162:165], v[196:199], v[60:63]
	v_mfma_f32_16x16x32_bf16 v[56:59], v[170:173], v[196:199], v[56:59]
	v_mfma_f32_16x16x32_bf16 v[44:47], v[162:165], v[204:207], v[44:47]
	v_mfma_f32_16x16x32_bf16 v[40:43], v[170:173], v[204:207], v[40:43]
	v_mfma_f32_16x16x32_bf16 v[28:31], v[162:165], v[212:215], v[28:31]
	v_mfma_f32_16x16x32_bf16 v[24:27], v[170:173], v[212:215], v[24:27]
	v_mfma_f32_16x16x32_bf16 v[12:15], v[162:165], v[220:223], v[12:15]
	v_mfma_f32_16x16x32_bf16 v[8:11], v[170:173], v[220:223], v[8:11]
	v_mfma_f32_16x16x32_bf16 v[52:55], v[174:177], v[190:193], v[52:55]
	v_mfma_f32_16x16x32_bf16 v[48:51], v[182:185], v[190:193], v[48:51]
	v_mfma_f32_16x16x32_bf16 v[36:39], v[174:177], v[200:203], v[36:39]
	v_mfma_f32_16x16x32_bf16 v[32:35], v[182:185], v[200:203], v[32:35]
	v_mfma_f32_16x16x32_bf16 v[20:23], v[174:177], v[208:211], v[20:23]
	v_mfma_f32_16x16x32_bf16 v[16:19], v[182:185], v[208:211], v[16:19]
	v_mfma_f32_16x16x32_bf16 v[4:7], v[174:177], v[216:219], v[4:7]
	v_mfma_f32_16x16x32_bf16 v[0:3], v[182:185], v[216:219], v[0:3]
	v_mfma_f32_16x16x32_bf16 v[52:55], v[178:181], v[196:199], v[52:55]
	v_mfma_f32_16x16x32_bf16 v[48:51], v[186:189], v[196:199], v[48:51]
	v_mfma_f32_16x16x32_bf16 v[36:39], v[178:181], v[204:207], v[36:39]
	v_mfma_f32_16x16x32_bf16 v[32:35], v[186:189], v[204:207], v[32:35]
	v_mfma_f32_16x16x32_bf16 v[20:23], v[178:181], v[212:215], v[20:23]
	v_mfma_f32_16x16x32_bf16 v[16:19], v[186:189], v[212:215], v[16:19]
	v_mfma_f32_16x16x32_bf16 v[4:7], v[178:181], v[220:223], v[4:7]
	v_mfma_f32_16x16x32_bf16 v[0:3], v[186:189], v[220:223], v[0:3]
	s_setprio 0
	s_barrier
	s_add_i32 s81, 0, 0x18000
	v_add_u32_e32 v161, s81, v156
	s_add_i32 s82, 0, 0x1c000
	ds_read_b128 v[150:153], v161
	ds_read_b128 v[162:165], v161 offset:1024
	ds_read_b128 v[166:169], v161 offset:2048
	ds_read_b128 v[170:173], v161 offset:3072
	v_add_u32_e32 v161, s82, v156
	ds_read_b128 v[174:177], v161
	ds_read_b128 v[178:181], v161 offset:1024
	ds_read_b128 v[182:185], v161 offset:2048
	ds_read_b128 v[186:189], v161 offset:3072
	s_add_u32 s52, s52, 0x2b0000
	s_addc_u32 s53, s53, 0
	s_mov_b32 m0, s57
	v_lshl_add_u64 v[230:231], s[52:53], 0, v[128:129]
	ds_read_b128 v[190:193], v160 offset:32768
	ds_read_b128 v[196:199], v160 offset:33792
	ds_read_b128 v[200:203], v160 offset:34816
	ds_read_b128 v[204:207], v160 offset:35840
	ds_read_b128 v[208:211], v160 offset:36864
	ds_read_b128 v[212:215], v160 offset:37888
	ds_read_b128 v[216:219], v160 offset:38912
	ds_read_b128 v[220:223], v160 offset:39936
	global_load_lds_dwordx4 v[230:231], off
	v_lshl_add_u64 v[230:231], s[52:53], 0, v[134:135]
	s_mov_b32 m0, s58
	s_nop 0
	global_load_lds_dwordx4 v[230:231], off
	s_waitcnt vmcnt(8)
	s_waitcnt lgkmcnt(0)
	s_setprio 1
	s_barrier
	v_mfma_f32_16x16x32_bf16 v[124:127], v[150:153], v[190:193], v[124:127]
	v_mfma_f32_16x16x32_bf16 v[120:123], v[166:169], v[190:193], v[120:123]
	v_mfma_f32_16x16x32_bf16 v[108:111], v[150:153], v[200:203], v[108:111]
	v_mfma_f32_16x16x32_bf16 v[104:107], v[166:169], v[200:203], v[104:107]
	v_mfma_f32_16x16x32_bf16 v[92:95], v[150:153], v[208:211], v[92:95]
	v_mfma_f32_16x16x32_bf16 v[88:91], v[166:169], v[208:211], v[88:91]
	v_mfma_f32_16x16x32_bf16 v[76:79], v[150:153], v[216:219], v[76:79]
	v_mfma_f32_16x16x32_bf16 v[72:75], v[166:169], v[216:219], v[72:75]
	v_mfma_f32_16x16x32_bf16 v[124:127], v[162:165], v[196:199], v[124:127]
	v_mfma_f32_16x16x32_bf16 v[120:123], v[170:173], v[196:199], v[120:123]
	v_mfma_f32_16x16x32_bf16 v[108:111], v[162:165], v[204:207], v[108:111]
	v_mfma_f32_16x16x32_bf16 v[104:107], v[170:173], v[204:207], v[104:107]
	v_mfma_f32_16x16x32_bf16 v[92:95], v[162:165], v[212:215], v[92:95]
	v_mfma_f32_16x16x32_bf16 v[88:91], v[170:173], v[212:215], v[88:91]
	v_mfma_f32_16x16x32_bf16 v[76:79], v[162:165], v[220:223], v[76:79]
	v_mfma_f32_16x16x32_bf16 v[72:75], v[170:173], v[220:223], v[72:75]
	v_mfma_f32_16x16x32_bf16 v[116:119], v[174:177], v[190:193], v[116:119]
	v_mfma_f32_16x16x32_bf16 v[112:115], v[182:185], v[190:193], v[112:115]
	v_mfma_f32_16x16x32_bf16 v[100:103], v[174:177], v[200:203], v[100:103]
	v_mfma_f32_16x16x32_bf16 v[96:99], v[182:185], v[200:203], v[96:99]
	v_mfma_f32_16x16x32_bf16 v[84:87], v[174:177], v[208:211], v[84:87]
	v_mfma_f32_16x16x32_bf16 v[80:83], v[182:185], v[208:211], v[80:83]
	v_mfma_f32_16x16x32_bf16 v[68:71], v[174:177], v[216:219], v[68:71]
	v_mfma_f32_16x16x32_bf16 v[64:67], v[182:185], v[216:219], v[64:67]
	v_mfma_f32_16x16x32_bf16 v[116:119], v[178:181], v[196:199], v[116:119]
	v_mfma_f32_16x16x32_bf16 v[112:115], v[186:189], v[196:199], v[112:115]
	v_mfma_f32_16x16x32_bf16 v[100:103], v[178:181], v[204:207], v[100:103]
	v_mfma_f32_16x16x32_bf16 v[96:99], v[186:189], v[204:207], v[96:99]
	v_mfma_f32_16x16x32_bf16 v[84:87], v[178:181], v[212:215], v[84:87]
	v_mfma_f32_16x16x32_bf16 v[80:83], v[186:189], v[212:215], v[80:83]
	v_mfma_f32_16x16x32_bf16 v[68:71], v[178:181], v[220:223], v[68:71]
	v_mfma_f32_16x16x32_bf16 v[64:67], v[186:189], v[220:223], v[64:67]
	s_setprio 0
	s_barrier
	s_add_i32 s52, s81, s54
	v_lshl_add_u64 v[154:155], v[154:155], 0, s[14:15]
	s_mov_b32 m0, s52
	ds_read_b128 v[190:193], v160 offset:49152
	ds_read_b128 v[196:199], v160 offset:50176
	ds_read_b128 v[200:203], v160 offset:51200
	ds_read_b128 v[204:207], v160 offset:52224
	ds_read_b128 v[208:211], v160 offset:53248
	ds_read_b128 v[212:215], v160 offset:54272
	ds_read_b128 v[216:219], v160 offset:55296
	ds_read_b128 v[220:223], v160 offset:56320
	global_load_lds_dwordx4 v[154:155], off
	s_add_i32 m0, s52, 0x2000
	s_add_u32 s48, s48, 0x2b0080
	v_lshl_add_u64 v[154:155], v[224:225], 0, s[14:15]
	s_addc_u32 s49, s49, 0
	s_add_i32 s52, s82, s54
	global_load_lds_dwordx4 v[154:155], off
	v_lshl_add_u64 v[154:155], s[48:49], 0, v[132:133]
	s_mov_b32 m0, s52
	s_nop 0
	global_load_lds_dwordx4 v[154:155], off
	v_lshl_add_u64 v[154:155], s[48:49], 0, v[136:137]
	s_add_i32 m0, s52, 0x2000
	s_nop 0
	global_load_lds_dwordx4 v[154:155], off
	v_lshl_add_u64 v[154:155], v[226:227], 0, s[14:15]
	s_mov_b32 m0, s62
	s_nop 0
	global_load_lds_dwordx4 v[154:155], off
	v_lshl_add_u64 v[154:155], v[228:229], 0, s[14:15]
	s_mov_b32 m0, s63
	s_nop 0
	global_load_lds_dwordx4 v[154:155], off
	s_nop 0
	s_waitcnt vmcnt(8)
	s_waitcnt lgkmcnt(0)
	s_setprio 1
	s_barrier
	v_mfma_f32_16x16x32_bf16 v[60:63], v[150:153], v[190:193], v[60:63]
	v_mfma_f32_16x16x32_bf16 v[56:59], v[166:169], v[190:193], v[56:59]
	v_mfma_f32_16x16x32_bf16 v[44:47], v[150:153], v[200:203], v[44:47]
	v_mfma_f32_16x16x32_bf16 v[40:43], v[166:169], v[200:203], v[40:43]
	v_mfma_f32_16x16x32_bf16 v[28:31], v[150:153], v[208:211], v[28:31]
	v_mfma_f32_16x16x32_bf16 v[24:27], v[166:169], v[208:211], v[24:27]
	v_mfma_f32_16x16x32_bf16 v[12:15], v[150:153], v[216:219], v[12:15]
	v_mfma_f32_16x16x32_bf16 v[8:11], v[166:169], v[216:219], v[8:11]
	v_mfma_f32_16x16x32_bf16 v[60:63], v[162:165], v[196:199], v[60:63]
	v_mfma_f32_16x16x32_bf16 v[56:59], v[170:173], v[196:199], v[56:59]
	v_mfma_f32_16x16x32_bf16 v[44:47], v[162:165], v[204:207], v[44:47]
	v_mfma_f32_16x16x32_bf16 v[40:43], v[170:173], v[204:207], v[40:43]
	v_mfma_f32_16x16x32_bf16 v[28:31], v[162:165], v[212:215], v[28:31]
	v_mfma_f32_16x16x32_bf16 v[24:27], v[170:173], v[212:215], v[24:27]
	v_mfma_f32_16x16x32_bf16 v[12:15], v[162:165], v[220:223], v[12:15]
	v_mfma_f32_16x16x32_bf16 v[8:11], v[170:173], v[220:223], v[8:11]
	v_mfma_f32_16x16x32_bf16 v[52:55], v[174:177], v[190:193], v[52:55]
	v_mfma_f32_16x16x32_bf16 v[48:51], v[182:185], v[190:193], v[48:51]
	v_mfma_f32_16x16x32_bf16 v[36:39], v[174:177], v[200:203], v[36:39]
	v_mfma_f32_16x16x32_bf16 v[32:35], v[182:185], v[200:203], v[32:35]
	v_mfma_f32_16x16x32_bf16 v[20:23], v[174:177], v[208:211], v[20:23]
	v_mfma_f32_16x16x32_bf16 v[16:19], v[182:185], v[208:211], v[16:19]
	v_mfma_f32_16x16x32_bf16 v[4:7], v[174:177], v[216:219], v[4:7]
	v_mfma_f32_16x16x32_bf16 v[0:3], v[182:185], v[216:219], v[0:3]
	v_mfma_f32_16x16x32_bf16 v[52:55], v[178:181], v[196:199], v[52:55]
	v_mfma_f32_16x16x32_bf16 v[48:51], v[186:189], v[196:199], v[48:51]
	v_mfma_f32_16x16x32_bf16 v[36:39], v[178:181], v[204:207], v[36:39]
	v_mfma_f32_16x16x32_bf16 v[32:35], v[186:189], v[204:207], v[32:35]
	v_mfma_f32_16x16x32_bf16 v[20:23], v[178:181], v[212:215], v[20:23]
	v_mfma_f32_16x16x32_bf16 v[16:19], v[186:189], v[212:215], v[16:19]
	v_mfma_f32_16x16x32_bf16 v[4:7], v[178:181], v[220:223], v[4:7]
	v_mfma_f32_16x16x32_bf16 v[0:3], v[186:189], v[220:223], v[0:3]
	s_setprio 0
	s_barrier
	s_add_u32 s50, s50, 0x100
	s_addc_u32 s51, s51, 0
	s_add_u32 s78, s78, 0x100
	s_addc_u32 s79, s79, 0
	s_cmp_ge_i32 s80, s76
	s_mov_b32 s48, s80
	s_cbranch_scc0 .LBB0_4304
	s_and_b64 vcc, exec, s[16:17]
	s_cbranch_vccz .LBB0_4307
	s_barrier
